# full stack, K-loop compute segments without s_setprio toggles
# speedup vs baseline: 1.0035x; 1.0035x over previous
; #define PG8_STAGEX(b, gbase) do { if constexpr (XR) { if (lane < 16) __builtin_amdgcn_global_load_lds((const unsigned*)((const char*)(gbase) + voffX), (PG8_LAS unsigned*)(lds + XR_OFF + (b) * 2048 + wid * 256), 16, 0, 0); } } while (0)
; #define PG8_LDX(b) do { if constexpr (XR) { _Pragma("unroll") for (int k = 0; k < 2; ++k) Ax_[k] = *(const PG8_LAS bf16x8*)(lds + XR_OFF + (b) * 2048 + aoffx + k * 1024); } } while (0)
; #define PG8_MMAX() do { if constexpr (XR) { if (hasx) { __builtin_amdgcn_s_setprio(1); if (wr == 0) PG8_MMAX_(B0); else PG8_MMAX_(B1); __builtin_amdgcn_s_setprio(0); } } } while (0)
; #define PG8_WAIT_LOOP() do { if constexpr (XR) PG8_WAIT_V(9); else PG8_WAIT_V(8); } while (0)
; #define PG8_STAGE(bufoff, gbase, voff) do { _Pragma("unroll") for (int _i = 0; _i < 2; ++_i) \
;         __builtin_amdgcn_global_load_lds((const unsigned*)((const char*)(gbase) + (voff)[_i]), (PG8_LAS unsigned*)(lds + (bufoff) + ldsw + _i * 8192), 16, 0, 0); } while (0)
; #define PG8_LDA(dst, b, h) do { _Pragma("unroll") for (int m = 0; m < 4; ++m) _Pragma("unroll") for (int k = 0; k < 2; ++k) dst[m][k] = *(const PG8_LAS bf16x8*)(lds + PG8_SA(b, h) + aoff + m * 2048 + k * 1024); } while (0)
; #define PG8_LDB(dst, b, h) do { _Pragma("unroll") for (int n = 0; n < 2; ++n) _Pragma("unroll") for (int k = 0; k < 2; ++k) dst[n][k] = *(const PG8_LAS bf16x8*)(lds + PG8_SB(b, h) + boff + n * 2048 + k * 1024); } while (0)
; #define PG8_WAIT_L(n) asm volatile("s_waitcnt lgkmcnt(" #n ")" ::: "memory")
; #define PG8_BAR __builtin_amdgcn_s_barrier()
; #define PG8_SCHED __builtin_amdgcn_sched_barrier(0)
; template <class Epi, class Sched, bool ALIGN_EPI = false, bool SP2 = false, bool DRAIN = true, bool XR = false>
; __device__ __forceinline__ void gemm_phase(PG8_LAS unsigned char* lds, const Gemm g, const Sched& S, const Epi& E) {
;     ...
;             PG8_LDB(B0, 0, 0); PG8_LDB(B1, 0, 1); PG8_SCHED; PG8_LDA(At, 0, 0); PG8_LDX(0); PG8_STAGE(PG8_SA(1, 1), a1 + hstepA, voffA);
;             PG8_WAIT_LOOP(); PG8_WAIT_L(0); PG8_BAR; PG8_MMA(0, 0, At, B0); PG8_MMA(0, 1, At, B1); PG8_MMAX(); PG8_BAR; PG8_SCHED;
;             PG8_LDA(At, 0, 1); PG8_STAGE(PG8_SB(0, 0), b2, voffB); PG8_STAGE(PG8_SB(0, 1), b2 + hstep, voffB); PG8_STAGE(PG8_SA(0, 0), a2, voffA); PG8_STAGEX(0, x2);
.LBB0_325:
	s_add_i32 s26, s61, s25
	s_and_b32 s27, s26, s43
	s_lshr_b32 s84, s27, 2
	s_lshl_b32 s27, s27, 7
	s_lshl_b64 s[0:1], s[84:85], 9
	s_and_b32 s27, s27, 0x100
	s_add_u32 s0, s80, s0
	s_addc_u32 s1, s81, s1
	s_add_u32 s40, s0, s27
	s_addc_u32 s41, s1, 0
	s_add_i32 s26, s26, 2
	s_and_b32 s0, s26, s43
	s_lshr_b32 s84, s0, 2
	s_lshl_b32 s1, s0, 7
	s_lshl_b64 s[26:27], s[84:85], 9
	s_and_b32 s1, s1, 0x100
	s_add_u32 s26, s80, s26
	s_addc_u32 s27, s81, s27
	s_add_u32 s26, s26, s1
	s_mov_b32 s1, s85
	s_addc_u32 s27, s27, 0
	s_lshl_b64 s[0:1], s[0:1], 7
	s_add_u32 s36, s76, s0
	s_addc_u32 vcc_lo, s77, s1
	s_add_i32 vcc_hi, 0, 0x10000
	s_cmp_eq_u32 s42, s25
	s_cselect_b32 s1, s22, s27
	s_cselect_b32 s0, s5, s26
	v_add_u32_e32 v2, vcc_hi, v183
	s_cselect_b32 s27, s24, vcc_lo
	s_cselect_b32 s26, s23, s36
	s_add_i32 s36, 0, 0x14000
	ds_read_b128 v[134:137], v2
	ds_read_b128 v[148:151], v2 offset:1024
	ds_read_b128 v[152:155], v2 offset:2048
	ds_read_b128 v[156:159], v2 offset:3072
	v_add_u32_e32 v2, s36, v183
	ds_read_b128 v[160:163], v2
	ds_read_b128 v[164:167], v2 offset:1024
	ds_read_b128 v[168:171], v2 offset:2048
	ds_read_b128 v[172:175], v2 offset:3072
	s_add_u32 s40, s40, s30
	s_addc_u32 s41, s41, s31
	v_lshl_add_u64 v[4:5], s[40:41], 0, v[144:145]
	v_lshl_add_u64 v[4:5], v[4:5], 0, s[86:87]
	s_add_i32 m0, s46, 0xc000
	ds_read_b128 v[176:179], v186
	ds_read_b128 v[188:191], v186 offset:1024
	ds_read_b128 v[192:195], v186 offset:2048
	ds_read_b128 v[196:199], v186 offset:3072
	ds_read_b128 v[200:203], v186 offset:4096
	ds_read_b128 v[214:217], v186 offset:5120
	ds_read_b128 v[218:221], v186 offset:6144
	ds_read_b128 v[222:225], v186 offset:7168
	global_load_lds_dwordx4 v[4:5], off
	v_lshl_add_u64 v[4:5], s[40:41], 0, v[140:141]
	v_lshl_add_u64 v[4:5], v[4:5], 0, s[86:87]
	s_add_i32 m0, s46, 0xe000
	s_nop 0
	global_load_lds_dwordx4 v[4:5], off
	s_waitcnt vmcnt(8)
	s_waitcnt lgkmcnt(0)
	s_barrier
	v_mfma_f32_16x16x32_bf16 v[130:133], v[134:137], v[176:179], v[130:133]
	v_mfma_f32_16x16x32_bf16 v[126:129], v[152:155], v[176:179], v[126:129]
	v_mfma_f32_16x16x32_bf16 v[122:125], v[134:137], v[192:195], v[122:125]
	v_mfma_f32_16x16x32_bf16 v[118:121], v[152:155], v[192:195], v[118:121]
	v_mfma_f32_16x16x32_bf16 v[114:117], v[134:137], v[200:203], v[114:117]
	v_mfma_f32_16x16x32_bf16 v[110:113], v[152:155], v[200:203], v[110:113]
	v_mfma_f32_16x16x32_bf16 v[106:109], v[134:137], v[218:221], v[106:109]
	v_mfma_f32_16x16x32_bf16 v[102:105], v[152:155], v[218:221], v[102:105]
	v_mfma_f32_16x16x32_bf16 v[130:133], v[148:151], v[188:191], v[130:133]
	v_mfma_f32_16x16x32_bf16 v[126:129], v[156:159], v[188:191], v[126:129]
	v_mfma_f32_16x16x32_bf16 v[122:125], v[148:151], v[196:199], v[122:125]
	v_mfma_f32_16x16x32_bf16 v[118:121], v[156:159], v[196:199], v[118:121]
	v_mfma_f32_16x16x32_bf16 v[114:117], v[148:151], v[214:217], v[114:117]
	v_mfma_f32_16x16x32_bf16 v[110:113], v[156:159], v[214:217], v[110:113]
	v_mfma_f32_16x16x32_bf16 v[106:109], v[148:151], v[222:225], v[106:109]
	v_mfma_f32_16x16x32_bf16 v[102:105], v[156:159], v[222:225], v[102:105]
	v_mfma_f32_16x16x32_bf16 v[98:101], v[160:163], v[176:179], v[98:101]
	v_mfma_f32_16x16x32_bf16 v[94:97], v[168:171], v[176:179], v[94:97]
	v_mfma_f32_16x16x32_bf16 v[90:93], v[160:163], v[192:195], v[90:93]
	v_mfma_f32_16x16x32_bf16 v[86:89], v[168:171], v[192:195], v[86:89]
	v_mfma_f32_16x16x32_bf16 v[82:85], v[160:163], v[200:203], v[82:85]
	v_mfma_f32_16x16x32_bf16 v[78:81], v[168:171], v[200:203], v[78:81]
	v_mfma_f32_16x16x32_bf16 v[74:77], v[160:163], v[218:221], v[74:77]
	v_mfma_f32_16x16x32_bf16 v[70:73], v[168:171], v[218:221], v[70:73]
	v_mfma_f32_16x16x32_bf16 v[98:101], v[164:167], v[188:191], v[98:101]
	v_mfma_f32_16x16x32_bf16 v[94:97], v[172:175], v[188:191], v[94:97]
	v_mfma_f32_16x16x32_bf16 v[90:93], v[164:167], v[196:199], v[90:93]
	v_mfma_f32_16x16x32_bf16 v[86:89], v[172:175], v[196:199], v[86:89]
	v_mfma_f32_16x16x32_bf16 v[82:85], v[164:167], v[214:217], v[82:85]
	v_mfma_f32_16x16x32_bf16 v[78:81], v[172:175], v[214:217], v[78:81]
	v_mfma_f32_16x16x32_bf16 v[74:77], v[164:167], v[222:225], v[74:77]
	v_mfma_f32_16x16x32_bf16 v[70:73], v[172:175], v[222:225], v[70:73]
	s_barrier
	s_add_i32 s40, vcc_hi, s44
	v_lshl_add_u64 v[180:181], s[26:27], 0, v[142:143]
	s_mov_b32 m0, s40
	ds_read_b128 v[176:179], v186 offset:16384
	ds_read_b128 v[188:191], v186 offset:17408
	ds_read_b128 v[192:195], v186 offset:18432
	ds_read_b128 v[196:199], v186 offset:19456
	ds_read_b128 v[200:203], v186 offset:20480
	ds_read_b128 v[214:217], v186 offset:21504
	ds_read_b128 v[218:221], v186 offset:22528
	ds_read_b128 v[222:225], v186 offset:23552
	global_load_lds_dwordx4 v142, s[26:27]
	s_add_i32 m0, s40, 0x2000
	v_lshl_add_u64 v[204:205], s[26:27], 0, v[138:139]
	s_add_u32 s26, s26, s30
	s_addc_u32 s27, s27, s31
	s_add_i32 s36, s36, s44
	global_load_lds_dwordx4 v[204:205], off
	v_lshl_add_u64 v[206:207], s[26:27], 0, v[142:143]
	s_mov_b32 m0, s36
	v_lshl_add_u64 v[208:209], s[26:27], 0, v[138:139]
	global_load_lds_dwordx4 v142, s[26:27]
	s_add_i32 m0, s36, 0x2000
	v_lshl_add_u64 v[226:227], s[0:1], 0, v[144:145]
	global_load_lds_dwordx4 v138, s[26:27]
	s_mov_b32 m0, s46
	v_lshl_add_u64 v[228:229], s[0:1], 0, v[140:141]
	global_load_lds_dwordx4 v144, s[0:1]
	s_mov_b32 m0, s47
	s_nop 0
	global_load_lds_dwordx4 v140, s[0:1]
	s_waitcnt vmcnt(8)
	s_waitcnt lgkmcnt(0)
	s_barrier
; #define PG8_LDX(b) do { if constexpr (XR) { _Pragma("unroll") for (int k = 0; k < 2; ++k) Ax_[k] = *(const PG8_LAS bf16x8*)(lds + XR_OFF + (b) * 2048 + aoffx + k * 1024); } } while (0)
; #define PG8_MMAX() do { if constexpr (XR) { if (hasx) { __builtin_amdgcn_s_setprio(1); if (wr == 0) PG8_MMAX_(B0); else PG8_MMAX_(B1); __builtin_amdgcn_s_setprio(0); } } } while (0)
; #define PG8_WAIT_LOOP() do { if constexpr (XR) PG8_WAIT_V(9); else PG8_WAIT_V(8); } while (0)
; #define PG8_STAGE(bufoff, gbase, voff) do { _Pragma("unroll") for (int _i = 0; _i < 2; ++_i) \
;         __builtin_amdgcn_global_load_lds((const unsigned*)((const char*)(gbase) + (voff)[_i]), (PG8_LAS unsigned*)(lds + (bufoff) + ldsw + _i * 8192), 16, 0, 0); } while (0)
; #define PG8_LDA(dst, b, h) do { _Pragma("unroll") for (int m = 0; m < 4; ++m) _Pragma("unroll") for (int k = 0; k < 2; ++k) dst[m][k] = *(const PG8_LAS bf16x8*)(lds + PG8_SA(b, h) + aoff + m * 2048 + k * 1024); } while (0)
; #define PG8_LDB(dst, b, h) do { _Pragma("unroll") for (int n = 0; n < 2; ++n) _Pragma("unroll") for (int k = 0; k < 2; ++k) dst[n][k] = *(const PG8_LAS bf16x8*)(lds + PG8_SB(b, h) + boff + n * 2048 + k * 1024); } while (0)
; #define PG8_MMA(ai, bj, At, Bt) do { __builtin_amdgcn_s_setprio(1); _Pragma("unroll") for (int m = 0; m < 4; ++m) _Pragma("unroll") for (int n = 0; n < 2; ++n) _Pragma("unroll") for (int k = 0; k < 2; ++k) \
;         acc[ai][bj][m][n] = __builtin_amdgcn_mfma_f32_16x16x32_bf16(Bt[n][k], At[m][k], acc[ai][bj][m][n], 0, 0, 0); __builtin_amdgcn_s_setprio(0); } while (0)
; #define PG8_WAIT_L(n) asm volatile("s_waitcnt lgkmcnt(" #n ")" ::: "memory")
; #define PG8_BAR __builtin_amdgcn_s_barrier()
; #define PG8_SCHED __builtin_amdgcn_sched_barrier(0)
; template <class Epi, class Sched, bool ALIGN_EPI = false, bool SP2 = false, bool DRAIN = true, bool XR = false>
; __device__ __forceinline__ void gemm_phase(PG8_LAS unsigned char* lds, const Gemm g, const Sched& S, const Epi& E) {
;     ...
;             PG8_WAIT_LOOP(); PG8_WAIT_L(0); PG8_BAR; PG8_MMA(1, 0, At, B0); PG8_MMA(1, 1, At, B1); PG8_BAR; PG8_SCHED;
;             PG8_LDB(B0, 1, 0); PG8_LDB(B1, 1, 1); PG8_SCHED; PG8_LDA(At, 1, 0); PG8_LDX(1); PG8_STAGE(PG8_SA(0, 1), a2 + hstepA, voffA);
;             PG8_WAIT_LOOP(); PG8_WAIT_L(0); PG8_BAR; PG8_MMA(0, 0, At, B0); PG8_MMA(0, 1, At, B1); PG8_MMAX(); PG8_BAR; PG8_SCHED;
	v_mfma_f32_16x16x32_bf16 v[66:69], v[134:137], v[176:179], v[66:69]
	v_mfma_f32_16x16x32_bf16 v[62:65], v[152:155], v[176:179], v[62:65]
	v_mfma_f32_16x16x32_bf16 v[58:61], v[134:137], v[192:195], v[58:61]
	v_mfma_f32_16x16x32_bf16 v[54:57], v[152:155], v[192:195], v[54:57]
	v_mfma_f32_16x16x32_bf16 v[50:53], v[134:137], v[200:203], v[50:53]
	v_mfma_f32_16x16x32_bf16 v[46:49], v[152:155], v[200:203], v[46:49]
	v_mfma_f32_16x16x32_bf16 v[42:45], v[134:137], v[218:221], v[42:45]
	v_mfma_f32_16x16x32_bf16 v[38:41], v[152:155], v[218:221], v[38:41]
	v_mfma_f32_16x16x32_bf16 v[66:69], v[148:151], v[188:191], v[66:69]
	v_mfma_f32_16x16x32_bf16 v[62:65], v[156:159], v[188:191], v[62:65]
	v_mfma_f32_16x16x32_bf16 v[58:61], v[148:151], v[196:199], v[58:61]
	v_mfma_f32_16x16x32_bf16 v[54:57], v[156:159], v[196:199], v[54:57]
	v_mfma_f32_16x16x32_bf16 v[50:53], v[148:151], v[214:217], v[50:53]
	v_mfma_f32_16x16x32_bf16 v[46:49], v[156:159], v[214:217], v[46:49]
	v_mfma_f32_16x16x32_bf16 v[42:45], v[148:151], v[222:225], v[42:45]
	v_mfma_f32_16x16x32_bf16 v[38:41], v[156:159], v[222:225], v[38:41]
	v_mfma_f32_16x16x32_bf16 v[34:37], v[160:163], v[176:179], v[34:37]
	v_mfma_f32_16x16x32_bf16 v[30:33], v[168:171], v[176:179], v[30:33]
	v_mfma_f32_16x16x32_bf16 v[26:29], v[160:163], v[192:195], v[26:29]
	v_mfma_f32_16x16x32_bf16 v[22:25], v[168:171], v[192:195], v[22:25]
	v_mfma_f32_16x16x32_bf16 v[18:21], v[160:163], v[200:203], v[18:21]
	v_mfma_f32_16x16x32_bf16 v[14:17], v[168:171], v[200:203], v[14:17]
	v_mfma_f32_16x16x32_bf16 v[10:13], v[160:163], v[218:221], v[10:13]
	v_mfma_f32_16x16x32_bf16 v[4:7], v[168:171], v[218:221], v[6:9]
	v_mfma_f32_16x16x32_bf16 v[34:37], v[164:167], v[188:191], v[34:37]
	v_mfma_f32_16x16x32_bf16 v[30:33], v[172:175], v[188:191], v[30:33]
	v_mfma_f32_16x16x32_bf16 v[26:29], v[164:167], v[196:199], v[26:29]
	v_mfma_f32_16x16x32_bf16 v[22:25], v[172:175], v[196:199], v[22:25]
	v_mfma_f32_16x16x32_bf16 v[18:21], v[164:167], v[214:217], v[18:21]
	v_mfma_f32_16x16x32_bf16 v[14:17], v[172:175], v[214:217], v[14:17]
	v_mfma_f32_16x16x32_bf16 v[10:13], v[164:167], v[222:225], v[10:13]
	v_mfma_f32_16x16x32_bf16 v[4:7], v[172:175], v[222:225], v[4:7]
	s_barrier
	s_add_i32 s26, 0, 0x18000
	v_add_u32_e32 v2, s26, v183
	s_add_i32 s27, 0, 0x1c000
	ds_read_b128 v[134:137], v2
	ds_read_b128 v[148:151], v2 offset:1024
	ds_read_b128 v[152:155], v2 offset:2048
	ds_read_b128 v[156:159], v2 offset:3072
	v_add_u32_e32 v2, s27, v183
	ds_read_b128 v[160:163], v2
	ds_read_b128 v[164:167], v2 offset:1024
	ds_read_b128 v[168:171], v2 offset:2048
	ds_read_b128 v[172:175], v2 offset:3072
	s_add_u32 s0, s0, s30
	s_addc_u32 s1, s1, s31
	s_mov_b32 m0, s48
	ds_read_b128 v[176:179], v186 offset:32768
	ds_read_b128 v[188:191], v186 offset:33792
	ds_read_b128 v[192:195], v186 offset:34816
	ds_read_b128 v[196:199], v186 offset:35840
	ds_read_b128 v[200:203], v186 offset:36864
	ds_read_b128 v[214:217], v186 offset:37888
	ds_read_b128 v[218:221], v186 offset:38912
	ds_read_b128 v[222:225], v186 offset:39936
	global_load_lds_dwordx4 v144, s[0:1]
	s_mov_b32 m0, s49
	s_nop 0
	global_load_lds_dwordx4 v140, s[0:1]
	s_waitcnt vmcnt(8)
	s_waitcnt lgkmcnt(0)
	s_barrier
	v_mfma_f32_16x16x32_bf16 v[130:133], v[134:137], v[176:179], v[130:133]
	v_mfma_f32_16x16x32_bf16 v[126:129], v[152:155], v[176:179], v[126:129]
	v_mfma_f32_16x16x32_bf16 v[122:125], v[134:137], v[192:195], v[122:125]
	v_mfma_f32_16x16x32_bf16 v[118:121], v[152:155], v[192:195], v[118:121]
	v_mfma_f32_16x16x32_bf16 v[114:117], v[134:137], v[200:203], v[114:117]
	v_mfma_f32_16x16x32_bf16 v[110:113], v[152:155], v[200:203], v[110:113]
	v_mfma_f32_16x16x32_bf16 v[106:109], v[134:137], v[218:221], v[106:109]
	v_mfma_f32_16x16x32_bf16 v[102:105], v[152:155], v[218:221], v[102:105]
	v_mfma_f32_16x16x32_bf16 v[130:133], v[148:151], v[188:191], v[130:133]
	v_mfma_f32_16x16x32_bf16 v[126:129], v[156:159], v[188:191], v[126:129]
	v_mfma_f32_16x16x32_bf16 v[122:125], v[148:151], v[196:199], v[122:125]
	v_mfma_f32_16x16x32_bf16 v[118:121], v[156:159], v[196:199], v[118:121]
	v_mfma_f32_16x16x32_bf16 v[114:117], v[148:151], v[214:217], v[114:117]
	v_mfma_f32_16x16x32_bf16 v[110:113], v[156:159], v[214:217], v[110:113]
	v_mfma_f32_16x16x32_bf16 v[106:109], v[148:151], v[222:225], v[106:109]
	v_mfma_f32_16x16x32_bf16 v[102:105], v[156:159], v[222:225], v[102:105]
	v_mfma_f32_16x16x32_bf16 v[98:101], v[160:163], v[176:179], v[98:101]
	v_mfma_f32_16x16x32_bf16 v[94:97], v[168:171], v[176:179], v[94:97]
	v_mfma_f32_16x16x32_bf16 v[90:93], v[160:163], v[192:195], v[90:93]
	v_mfma_f32_16x16x32_bf16 v[86:89], v[168:171], v[192:195], v[86:89]
	v_mfma_f32_16x16x32_bf16 v[82:85], v[160:163], v[200:203], v[82:85]
	v_mfma_f32_16x16x32_bf16 v[78:81], v[168:171], v[200:203], v[78:81]
	v_mfma_f32_16x16x32_bf16 v[74:77], v[160:163], v[218:221], v[74:77]
	v_mfma_f32_16x16x32_bf16 v[70:73], v[168:171], v[218:221], v[70:73]
	v_mfma_f32_16x16x32_bf16 v[98:101], v[164:167], v[188:191], v[98:101]
	v_mfma_f32_16x16x32_bf16 v[94:97], v[172:175], v[188:191], v[94:97]
	v_mfma_f32_16x16x32_bf16 v[90:93], v[164:167], v[196:199], v[90:93]
	v_mfma_f32_16x16x32_bf16 v[86:89], v[172:175], v[196:199], v[86:89]
	v_mfma_f32_16x16x32_bf16 v[82:85], v[164:167], v[214:217], v[82:85]
	v_mfma_f32_16x16x32_bf16 v[78:81], v[172:175], v[214:217], v[78:81]
	v_mfma_f32_16x16x32_bf16 v[74:77], v[164:167], v[222:225], v[74:77]
	v_mfma_f32_16x16x32_bf16 v[70:73], v[172:175], v[222:225], v[70:73]
	s_barrier
; #define PG8_STAGEX(b, gbase) do { if constexpr (XR) { if (lane < 16) __builtin_amdgcn_global_load_lds((const unsigned*)((const char*)(gbase) + voffX), (PG8_LAS unsigned*)(lds + XR_OFF + (b) * 2048 + wid * 256), 16, 0, 0); } } while (0)
; #define PG8_WAIT_LOOP() do { if constexpr (XR) PG8_WAIT_V(9); else PG8_WAIT_V(8); } while (0)
; #define PG8_STAGE(bufoff, gbase, voff) do { _Pragma("unroll") for (int _i = 0; _i < 2; ++_i) \
;         __builtin_amdgcn_global_load_lds((const unsigned*)((const char*)(gbase) + (voff)[_i]), (PG8_LAS unsigned*)(lds + (bufoff) + ldsw + _i * 8192), 16, 0, 0); } while (0)
; #define PG8_LDA(dst, b, h) do { _Pragma("unroll") for (int m = 0; m < 4; ++m) _Pragma("unroll") for (int k = 0; k < 2; ++k) dst[m][k] = *(const PG8_LAS bf16x8*)(lds + PG8_SA(b, h) + aoff + m * 2048 + k * 1024); } while (0)
; #define PG8_MMA(ai, bj, At, Bt) do { __builtin_amdgcn_s_setprio(1); _Pragma("unroll") for (int m = 0; m < 4; ++m) _Pragma("unroll") for (int n = 0; n < 2; ++n) _Pragma("unroll") for (int k = 0; k < 2; ++k) \
;         acc[ai][bj][m][n] = __builtin_amdgcn_mfma_f32_16x16x32_bf16(Bt[n][k], At[m][k], acc[ai][bj][m][n], 0, 0, 0); __builtin_amdgcn_s_setprio(0); } while (0)
; #define PG8_WAIT_L(n) asm volatile("s_waitcnt lgkmcnt(" #n ")" ::: "memory")
; #define PG8_BAR __builtin_amdgcn_s_barrier()
; #define PG8_SCHED __builtin_amdgcn_sched_barrier(0)
; template <class Epi, class Sched, bool ALIGN_EPI = false, bool SP2 = false, bool DRAIN = true, bool XR = false>
; __device__ __forceinline__ void gemm_phase(PG8_LAS unsigned char* lds, const Gemm g, const Sched& S, const Epi& E) {
;     ...
;             PG8_LDA(At, 1, 1); PG8_STAGE(PG8_SB(1, 0), b3, voffB); PG8_STAGE(PG8_SB(1, 1), b3 + hstep, voffB); PG8_STAGE(PG8_SA(1, 0), a3, voffA); PG8_STAGEX(1, x3);
;             PG8_WAIT_LOOP(); PG8_WAIT_L(0); PG8_BAR; PG8_MMA(1, 0, At, B0); PG8_MMA(1, 1, At, B1); PG8_BAR; PG8_SCHED;
	s_add_i32 s0, s26, s44
	v_lshl_add_u64 v[8:9], v[180:181], 0, s[86:87]
	s_mov_b32 m0, s0
	ds_read_b128 v[176:179], v186 offset:49152
	ds_read_b128 v[188:191], v186 offset:50176
	ds_read_b128 v[192:195], v186 offset:51200
	ds_read_b128 v[196:199], v186 offset:52224
	ds_read_b128 v[200:203], v186 offset:53248
	ds_read_b128 v[214:217], v186 offset:54272
	ds_read_b128 v[218:221], v186 offset:55296
	ds_read_b128 v[222:225], v186 offset:56320
	global_load_lds_dwordx4 v[8:9], off
	v_lshl_add_u64 v[8:9], v[204:205], 0, s[86:87]
	s_add_i32 m0, s0, 0x2000
	s_add_i32 s0, s27, s44
	global_load_lds_dwordx4 v[8:9], off
	v_lshl_add_u64 v[8:9], v[206:207], 0, s[86:87]
	s_mov_b32 m0, s0
	s_nop 0
	global_load_lds_dwordx4 v[8:9], off
	v_lshl_add_u64 v[8:9], v[208:209], 0, s[86:87]
	s_add_i32 m0, s0, 0x2000
	s_nop 0
	global_load_lds_dwordx4 v[8:9], off
	v_lshl_add_u64 v[8:9], v[226:227], 0, s[86:87]
	s_mov_b32 m0, s67
	s_nop 0
	global_load_lds_dwordx4 v[8:9], off
	v_lshl_add_u64 v[8:9], v[228:229], 0, s[86:87]
	s_mov_b32 m0, s71
	s_nop 0
	global_load_lds_dwordx4 v[8:9], off
	s_waitcnt vmcnt(8)
	s_waitcnt lgkmcnt(0)
	s_barrier
	v_mfma_f32_16x16x32_bf16 v[66:69], v[134:137], v[176:179], v[66:69]
	v_mfma_f32_16x16x32_bf16 v[62:65], v[152:155], v[176:179], v[62:65]
	v_mfma_f32_16x16x32_bf16 v[58:61], v[134:137], v[192:195], v[58:61]
	v_mfma_f32_16x16x32_bf16 v[54:57], v[152:155], v[192:195], v[54:57]
	v_mfma_f32_16x16x32_bf16 v[50:53], v[134:137], v[200:203], v[50:53]
	v_mfma_f32_16x16x32_bf16 v[46:49], v[152:155], v[200:203], v[46:49]
	v_mfma_f32_16x16x32_bf16 v[42:45], v[134:137], v[218:221], v[42:45]
	v_mfma_f32_16x16x32_bf16 v[38:41], v[152:155], v[218:221], v[38:41]
	v_mfma_f32_16x16x32_bf16 v[66:69], v[148:151], v[188:191], v[66:69]
	v_mfma_f32_16x16x32_bf16 v[62:65], v[156:159], v[188:191], v[62:65]
	v_mfma_f32_16x16x32_bf16 v[58:61], v[148:151], v[196:199], v[58:61]
	v_mfma_f32_16x16x32_bf16 v[54:57], v[156:159], v[196:199], v[54:57]
	v_mfma_f32_16x16x32_bf16 v[50:53], v[148:151], v[214:217], v[50:53]
	v_mfma_f32_16x16x32_bf16 v[46:49], v[156:159], v[214:217], v[46:49]
	v_mfma_f32_16x16x32_bf16 v[42:45], v[148:151], v[222:225], v[42:45]
	v_mfma_f32_16x16x32_bf16 v[38:41], v[156:159], v[222:225], v[38:41]
	v_mfma_f32_16x16x32_bf16 v[34:37], v[160:163], v[176:179], v[34:37]
	v_mfma_f32_16x16x32_bf16 v[30:33], v[168:171], v[176:179], v[30:33]
	v_mfma_f32_16x16x32_bf16 v[26:29], v[160:163], v[192:195], v[26:29]
	v_mfma_f32_16x16x32_bf16 v[22:25], v[168:171], v[192:195], v[22:25]
	v_mfma_f32_16x16x32_bf16 v[18:21], v[160:163], v[200:203], v[18:21]
	v_mfma_f32_16x16x32_bf16 v[14:17], v[168:171], v[200:203], v[14:17]
	v_mfma_f32_16x16x32_bf16 v[8:11], v[160:163], v[218:221], v[10:13]
	v_mfma_f32_16x16x32_bf16 v[4:7], v[168:171], v[218:221], v[4:7]
	v_mfma_f32_16x16x32_bf16 v[34:37], v[164:167], v[188:191], v[34:37]
	v_mfma_f32_16x16x32_bf16 v[30:33], v[172:175], v[188:191], v[30:33]
	v_mfma_f32_16x16x32_bf16 v[26:29], v[164:167], v[196:199], v[26:29]
	v_mfma_f32_16x16x32_bf16 v[22:25], v[172:175], v[196:199], v[22:25]
	v_mfma_f32_16x16x32_bf16 v[18:21], v[164:167], v[214:217], v[18:21]
	v_mfma_f32_16x16x32_bf16 v[14:17], v[172:175], v[214:217], v[14:17]
	v_mfma_f32_16x16x32_bf16 v[10:13], v[164:167], v[222:225], v[8:11]
	v_mfma_f32_16x16x32_bf16 v[6:9], v[172:175], v[222:225], v[4:7]
	s_barrier
	s_add_i32 s25, s25, 2
	s_cmp_ge_i32 s25, s89
	s_cbranch_scc0 .LBB0_325

; #define PG8_STAGEX(b, gbase) do { if constexpr (XR) { if (lane < 16) __builtin_amdgcn_global_load_lds((const unsigned*)((const char*)(gbase) + voffX), (PG8_LAS unsigned*)(lds + XR_OFF + (b) * 2048 + wid * 256), 16, 0, 0); } } while (0)
; #define PG8_LDX(b) do { if constexpr (XR) { _Pragma("unroll") for (int k = 0; k < 2; ++k) Ax_[k] = *(const PG8_LAS bf16x8*)(lds + XR_OFF + (b) * 2048 + aoffx + k * 1024); } } while (0)
; #define PG8_MMAX() do { if constexpr (XR) { if (hasx) { __builtin_amdgcn_s_setprio(1); if (wr == 0) PG8_MMAX_(B0); else PG8_MMAX_(B1); __builtin_amdgcn_s_setprio(0); } } } while (0)
; #define PG8_WAIT_LOOP() do { if constexpr (XR) PG8_WAIT_V(9); else PG8_WAIT_V(8); } while (0)
; #define PG8_STAGE(bufoff, gbase, voff) do { _Pragma("unroll") for (int _i = 0; _i < 2; ++_i) \
;         __builtin_amdgcn_global_load_lds((const unsigned*)((const char*)(gbase) + (voff)[_i]), (PG8_LAS unsigned*)(lds + (bufoff) + ldsw + _i * 8192), 16, 0, 0); } while (0)
; #define PG8_LDA(dst, b, h) do { _Pragma("unroll") for (int m = 0; m < 4; ++m) _Pragma("unroll") for (int k = 0; k < 2; ++k) dst[m][k] = *(const PG8_LAS bf16x8*)(lds + PG8_SA(b, h) + aoff + m * 2048 + k * 1024); } while (0)
; #define PG8_LDB(dst, b, h) do { _Pragma("unroll") for (int n = 0; n < 2; ++n) _Pragma("unroll") for (int k = 0; k < 2; ++k) dst[n][k] = *(const PG8_LAS bf16x8*)(lds + PG8_SB(b, h) + boff + n * 2048 + k * 1024); } while (0)
; #define PG8_WAIT_L(n) asm volatile("s_waitcnt lgkmcnt(" #n ")" ::: "memory")
; #define PG8_BAR __builtin_amdgcn_s_barrier()
; #define PG8_SCHED __builtin_amdgcn_sched_barrier(0)
; template <class Epi, class Sched, bool ALIGN_EPI = false, bool SP2 = false, bool DRAIN = true, bool XR = false>
; __device__ __forceinline__ void gemm_phase(PG8_LAS unsigned char* lds, const Gemm g, const Sched& S, const Epi& E) {
;     ...
;             PG8_LDB(B0, 0, 0); PG8_LDB(B1, 0, 1); PG8_SCHED; PG8_LDA(At, 0, 0); PG8_LDX(0); PG8_STAGE(PG8_SA(1, 1), a1 + hstepA, voffA);
;             PG8_WAIT_LOOP(); PG8_WAIT_L(0); PG8_BAR; PG8_MMA(0, 0, At, B0); PG8_MMA(0, 1, At, B1); PG8_MMAX(); PG8_BAR; PG8_SCHED;
;             PG8_LDA(At, 0, 1); PG8_STAGE(PG8_SB(0, 0), b2, voffB); PG8_STAGE(PG8_SB(0, 1), b2 + hstep, voffB); PG8_STAGE(PG8_SA(0, 0), a2, voffA); PG8_STAGEX(0, x2);
.LBB0_1020:
	s_add_i32 s4, s72, -2
	s_and_b32 s73, s4, s61
	s_lshr_b32 s84, s73, 2
	s_lshl_b32 s36, s73, 7
	s_lshl_b64 s[4:5], s[84:85], 9
	s_and_b32 s36, s36, 0x100
	s_add_u32 s4, s44, s4
	s_addc_u32 s5, s45, s5
	s_add_u32 s73, s4, s36
	s_addc_u32 s77, s5, 0
	s_and_b32 s4, s72, s61
	s_lshr_b32 s84, s4, 2
	s_lshl_b32 s5, s4, 7
	s_lshl_b64 s[74:75], s[84:85], 9
	s_and_b32 s5, s5, 0x100
	s_add_u32 s36, s44, s74
	s_addc_u32 s74, s45, s75
	s_add_u32 s36, s36, s5
	s_mov_b32 s5, s85
	s_addc_u32 s74, s74, 0
	s_lshl_b64 s[4:5], s[4:5], 7
	s_add_u32 s76, s42, s4
	s_addc_u32 s75, s43, s5
	s_add_i32 s78, 0, 0x10000
	s_cmp_eq_u32 s60, s72
	s_cselect_b32 s5, s35, s74
	s_cselect_b32 s4, s34, s36
	s_cselect_b32 s75, s41, s75
	s_cselect_b32 s74, s40, s76
	s_add_i32 s36, 0, 0x14000
	v_add_u32_e32 v104, s78, v176
	v_add_u32_e32 v168, s36, v176
	ds_read_b128 v[84:87], v104
	ds_read_b128 v[88:91], v104 offset:1024
	ds_read_b128 v[96:99], v104 offset:2048
	ds_read_b128 v[104:107], v104 offset:3072
	ds_read_b128 v[148:151], v168
	ds_read_b128 v[152:155], v168 offset:1024
	ds_read_b128 v[156:159], v168 offset:2048
	ds_read_b128 v[168:171], v168 offset:3072
	s_add_u32 s76, s73, s18
	s_addc_u32 s77, s77, s19
	v_lshl_add_u64 v[204:205], s[76:77], 0, v[162:163]
	v_lshl_add_u64 v[204:205], v[204:205], 0, s[86:87]
	s_add_i32 m0, s54, 0xc000
	ds_read_b128 v[172:175], v178
	ds_read_b128 v[180:183], v178 offset:1024
	ds_read_b128 v[184:187], v178 offset:2048
	ds_read_b128 v[188:191], v178 offset:3072
	ds_read_b128 v[192:195], v178 offset:4096
	ds_read_b128 v[196:199], v178 offset:5120
	ds_read_b128 v[200:203], v178 offset:6144
	ds_read_b128 v[214:217], v178 offset:7168
	global_load_lds_dwordx4 v[204:205], off
	v_lshl_add_u64 v[204:205], s[76:77], 0, v[164:165]
	v_lshl_add_u64 v[204:205], v[204:205], 0, s[86:87]
	s_add_i32 m0, s54, 0xe000
	s_nop 0
	global_load_lds_dwordx4 v[204:205], off
	s_waitcnt vmcnt(8)
	s_waitcnt lgkmcnt(0)
	s_barrier
	v_mfma_f32_16x16x32_bf16 v[144:147], v[84:87], v[172:175], v[144:147]
	v_mfma_f32_16x16x32_bf16 v[140:143], v[96:99], v[172:175], v[140:143]
	v_mfma_f32_16x16x32_bf16 v[128:131], v[84:87], v[184:187], v[128:131]
	v_mfma_f32_16x16x32_bf16 v[124:127], v[96:99], v[184:187], v[124:127]
	v_mfma_f32_16x16x32_bf16 v[112:115], v[84:87], v[192:195], v[112:115]
	v_mfma_f32_16x16x32_bf16 v[108:111], v[96:99], v[192:195], v[108:111]
	v_mfma_f32_16x16x32_bf16 v[80:83], v[84:87], v[200:203], v[80:83]
	v_mfma_f32_16x16x32_bf16 v[76:79], v[96:99], v[200:203], v[76:79]
	v_mfma_f32_16x16x32_bf16 v[144:147], v[88:91], v[180:183], v[144:147]
	v_mfma_f32_16x16x32_bf16 v[140:143], v[104:107], v[180:183], v[140:143]
	v_mfma_f32_16x16x32_bf16 v[128:131], v[88:91], v[188:191], v[128:131]
	v_mfma_f32_16x16x32_bf16 v[124:127], v[104:107], v[188:191], v[124:127]
	v_mfma_f32_16x16x32_bf16 v[112:115], v[88:91], v[196:199], v[112:115]
	v_mfma_f32_16x16x32_bf16 v[108:111], v[104:107], v[196:199], v[108:111]
	v_mfma_f32_16x16x32_bf16 v[80:83], v[88:91], v[214:217], v[80:83]
	v_mfma_f32_16x16x32_bf16 v[76:79], v[104:107], v[214:217], v[76:79]
	v_mfma_f32_16x16x32_bf16 v[136:139], v[148:151], v[172:175], v[136:139]
	v_mfma_f32_16x16x32_bf16 v[132:135], v[156:159], v[172:175], v[132:135]
	v_mfma_f32_16x16x32_bf16 v[120:123], v[148:151], v[184:187], v[120:123]
	v_mfma_f32_16x16x32_bf16 v[116:119], v[156:159], v[184:187], v[116:119]
	v_mfma_f32_16x16x32_bf16 v[100:103], v[148:151], v[192:195], v[100:103]
	v_mfma_f32_16x16x32_bf16 v[92:95], v[156:159], v[192:195], v[92:95]
	v_mfma_f32_16x16x32_bf16 v[72:75], v[148:151], v[200:203], v[72:75]
	v_mfma_f32_16x16x32_bf16 v[68:71], v[156:159], v[200:203], v[68:71]
	v_mfma_f32_16x16x32_bf16 v[136:139], v[152:155], v[180:183], v[136:139]
	v_mfma_f32_16x16x32_bf16 v[132:135], v[168:171], v[180:183], v[132:135]
	v_mfma_f32_16x16x32_bf16 v[120:123], v[152:155], v[188:191], v[120:123]
	v_mfma_f32_16x16x32_bf16 v[116:119], v[168:171], v[188:191], v[116:119]
	v_mfma_f32_16x16x32_bf16 v[100:103], v[152:155], v[196:199], v[100:103]
	v_mfma_f32_16x16x32_bf16 v[92:95], v[168:171], v[196:199], v[92:95]
	v_mfma_f32_16x16x32_bf16 v[72:75], v[152:155], v[214:217], v[72:75]
	v_mfma_f32_16x16x32_bf16 v[68:71], v[168:171], v[214:217], v[68:71]
	s_barrier
	s_add_i32 s73, s78, s51
	v_lshl_add_u64 v[204:205], s[74:75], 0, v[2:3]
	s_mov_b32 m0, s73
	ds_read_b128 v[172:175], v178 offset:16384
	ds_read_b128 v[180:183], v178 offset:17408
	ds_read_b128 v[184:187], v178 offset:18432
	ds_read_b128 v[188:191], v178 offset:19456
	ds_read_b128 v[192:195], v178 offset:20480
	ds_read_b128 v[196:199], v178 offset:21504
	ds_read_b128 v[200:203], v178 offset:22528
	ds_read_b128 v[214:217], v178 offset:23552
	global_load_lds_dwordx4 v2, s[74:75]
	s_add_i32 m0, s73, 0x2000
	v_lshl_add_u64 v[206:207], s[74:75], 0, v[166:167]
	s_add_u32 s74, s74, s18
	s_addc_u32 s75, s75, s19
	s_add_i32 s36, s36, s51
	global_load_lds_dwordx4 v[206:207], off
	v_lshl_add_u64 v[208:209], s[74:75], 0, v[2:3]
	s_mov_b32 m0, s36
	v_lshl_add_u64 v[212:213], s[74:75], 0, v[166:167]
	global_load_lds_dwordx4 v2, s[74:75]
	s_add_i32 m0, s36, 0x2000
	v_lshl_add_u64 v[218:219], s[4:5], 0, v[162:163]
	global_load_lds_dwordx4 v166, s[74:75]
	s_mov_b32 m0, s54
	v_lshl_add_u64 v[220:221], s[4:5], 0, v[164:165]
	global_load_lds_dwordx4 v162, s[4:5]
	s_mov_b32 m0, s55
	s_nop 0
	global_load_lds_dwordx4 v164, s[4:5]
	s_waitcnt vmcnt(8)
	s_waitcnt lgkmcnt(0)
	s_barrier
; #define PG8_LDX(b) do { if constexpr (XR) { _Pragma("unroll") for (int k = 0; k < 2; ++k) Ax_[k] = *(const PG8_LAS bf16x8*)(lds + XR_OFF + (b) * 2048 + aoffx + k * 1024); } } while (0)
; #define PG8_MMAX() do { if constexpr (XR) { if (hasx) { __builtin_amdgcn_s_setprio(1); if (wr == 0) PG8_MMAX_(B0); else PG8_MMAX_(B1); __builtin_amdgcn_s_setprio(0); } } } while (0)
; #define PG8_WAIT_LOOP() do { if constexpr (XR) PG8_WAIT_V(9); else PG8_WAIT_V(8); } while (0)
; #define PG8_STAGE(bufoff, gbase, voff) do { _Pragma("unroll") for (int _i = 0; _i < 2; ++_i) \
;         __builtin_amdgcn_global_load_lds((const unsigned*)((const char*)(gbase) + (voff)[_i]), (PG8_LAS unsigned*)(lds + (bufoff) + ldsw + _i * 8192), 16, 0, 0); } while (0)
; #define PG8_LDA(dst, b, h) do { _Pragma("unroll") for (int m = 0; m < 4; ++m) _Pragma("unroll") for (int k = 0; k < 2; ++k) dst[m][k] = *(const PG8_LAS bf16x8*)(lds + PG8_SA(b, h) + aoff + m * 2048 + k * 1024); } while (0)
; #define PG8_LDB(dst, b, h) do { _Pragma("unroll") for (int n = 0; n < 2; ++n) _Pragma("unroll") for (int k = 0; k < 2; ++k) dst[n][k] = *(const PG8_LAS bf16x8*)(lds + PG8_SB(b, h) + boff + n * 2048 + k * 1024); } while (0)
; #define PG8_MMA(ai, bj, At, Bt) do { __builtin_amdgcn_s_setprio(1); _Pragma("unroll") for (int m = 0; m < 4; ++m) _Pragma("unroll") for (int n = 0; n < 2; ++n) _Pragma("unroll") for (int k = 0; k < 2; ++k) \
;         acc[ai][bj][m][n] = __builtin_amdgcn_mfma_f32_16x16x32_bf16(Bt[n][k], At[m][k], acc[ai][bj][m][n], 0, 0, 0); __builtin_amdgcn_s_setprio(0); } while (0)
; #define PG8_WAIT_L(n) asm volatile("s_waitcnt lgkmcnt(" #n ")" ::: "memory")
; #define PG8_BAR __builtin_amdgcn_s_barrier()
; #define PG8_SCHED __builtin_amdgcn_sched_barrier(0)
; template <class Epi, class Sched, bool ALIGN_EPI = false, bool SP2 = false, bool DRAIN = true, bool XR = false>
; __device__ __forceinline__ void gemm_phase(PG8_LAS unsigned char* lds, const Gemm g, const Sched& S, const Epi& E) {
;     ...
;             PG8_WAIT_LOOP(); PG8_WAIT_L(0); PG8_BAR; PG8_MMA(1, 0, At, B0); PG8_MMA(1, 1, At, B1); PG8_BAR; PG8_SCHED;
;             PG8_LDB(B0, 1, 0); PG8_LDB(B1, 1, 1); PG8_SCHED; PG8_LDA(At, 1, 0); PG8_LDX(1); PG8_STAGE(PG8_SA(0, 1), a2 + hstepA, voffA);
;             PG8_WAIT_LOOP(); PG8_WAIT_L(0); PG8_BAR; PG8_MMA(0, 0, At, B0); PG8_MMA(0, 1, At, B1); PG8_MMAX(); PG8_BAR; PG8_SCHED;
	v_mfma_f32_16x16x32_bf16 v[64:67], v[84:87], v[172:175], v[64:67]
	v_mfma_f32_16x16x32_bf16 v[60:63], v[96:99], v[172:175], v[60:63]
	v_mfma_f32_16x16x32_bf16 v[48:51], v[84:87], v[184:187], v[48:51]
	v_mfma_f32_16x16x32_bf16 v[44:47], v[96:99], v[184:187], v[44:47]
	v_mfma_f32_16x16x32_bf16 v[32:35], v[84:87], v[192:195], v[32:35]
	v_mfma_f32_16x16x32_bf16 v[28:31], v[96:99], v[192:195], v[28:31]
	v_mfma_f32_16x16x32_bf16 v[16:19], v[84:87], v[200:203], v[16:19]
	v_mfma_f32_16x16x32_bf16 v[12:15], v[96:99], v[200:203], v[12:15]
	v_mfma_f32_16x16x32_bf16 v[64:67], v[88:91], v[180:183], v[64:67]
	v_mfma_f32_16x16x32_bf16 v[60:63], v[104:107], v[180:183], v[60:63]
	v_mfma_f32_16x16x32_bf16 v[48:51], v[88:91], v[188:191], v[48:51]
	v_mfma_f32_16x16x32_bf16 v[44:47], v[104:107], v[188:191], v[44:47]
	v_mfma_f32_16x16x32_bf16 v[32:35], v[88:91], v[196:199], v[32:35]
	v_mfma_f32_16x16x32_bf16 v[28:31], v[104:107], v[196:199], v[28:31]
	v_mfma_f32_16x16x32_bf16 v[16:19], v[88:91], v[214:217], v[16:19]
	v_mfma_f32_16x16x32_bf16 v[12:15], v[104:107], v[214:217], v[12:15]
	v_mfma_f32_16x16x32_bf16 v[56:59], v[148:151], v[172:175], v[56:59]
	v_mfma_f32_16x16x32_bf16 v[52:55], v[156:159], v[172:175], v[52:55]
	v_mfma_f32_16x16x32_bf16 v[40:43], v[148:151], v[184:187], v[40:43]
	v_mfma_f32_16x16x32_bf16 v[36:39], v[156:159], v[184:187], v[36:39]
	v_mfma_f32_16x16x32_bf16 v[24:27], v[148:151], v[192:195], v[24:27]
	v_mfma_f32_16x16x32_bf16 v[20:23], v[156:159], v[192:195], v[20:23]
	v_mfma_f32_16x16x32_bf16 v[8:11], v[148:151], v[200:203], v[8:11]
	v_mfma_f32_16x16x32_bf16 v[4:7], v[156:159], v[200:203], v[4:7]
	v_mfma_f32_16x16x32_bf16 v[56:59], v[152:155], v[180:183], v[56:59]
	v_mfma_f32_16x16x32_bf16 v[52:55], v[168:171], v[180:183], v[52:55]
	v_mfma_f32_16x16x32_bf16 v[40:43], v[152:155], v[188:191], v[40:43]
	v_mfma_f32_16x16x32_bf16 v[36:39], v[168:171], v[188:191], v[36:39]
	v_mfma_f32_16x16x32_bf16 v[24:27], v[152:155], v[196:199], v[24:27]
	v_mfma_f32_16x16x32_bf16 v[20:23], v[168:171], v[196:199], v[20:23]
	v_mfma_f32_16x16x32_bf16 v[8:11], v[152:155], v[214:217], v[8:11]
	v_mfma_f32_16x16x32_bf16 v[4:7], v[168:171], v[214:217], v[4:7]
	s_barrier
	s_add_i32 s36, 0, 0x18000
	s_add_i32 s73, 0, 0x1c000
	v_add_u32_e32 v104, s36, v176
	v_add_u32_e32 v168, s73, v176
	ds_read_b128 v[84:87], v104
	ds_read_b128 v[88:91], v104 offset:1024
	ds_read_b128 v[96:99], v104 offset:2048
	ds_read_b128 v[104:107], v104 offset:3072
	ds_read_b128 v[148:151], v168
	ds_read_b128 v[152:155], v168 offset:1024
	ds_read_b128 v[156:159], v168 offset:2048
	ds_read_b128 v[168:171], v168 offset:3072
	s_add_u32 s4, s4, s18
	s_addc_u32 s5, s5, s19
	s_mov_b32 m0, s56
	ds_read_b128 v[172:175], v178 offset:32768
	ds_read_b128 v[180:183], v178 offset:33792
	ds_read_b128 v[184:187], v178 offset:34816
	ds_read_b128 v[188:191], v178 offset:35840
	ds_read_b128 v[192:195], v178 offset:36864
	ds_read_b128 v[196:199], v178 offset:37888
	ds_read_b128 v[200:203], v178 offset:38912
	ds_read_b128 v[214:217], v178 offset:39936
	global_load_lds_dwordx4 v162, s[4:5]
	s_mov_b32 m0, s57
	s_nop 0
	global_load_lds_dwordx4 v164, s[4:5]
	s_waitcnt vmcnt(8)
	s_waitcnt lgkmcnt(0)
	s_barrier
	v_mfma_f32_16x16x32_bf16 v[144:147], v[84:87], v[172:175], v[144:147]
	v_mfma_f32_16x16x32_bf16 v[140:143], v[96:99], v[172:175], v[140:143]
	v_mfma_f32_16x16x32_bf16 v[128:131], v[84:87], v[184:187], v[128:131]
	v_mfma_f32_16x16x32_bf16 v[124:127], v[96:99], v[184:187], v[124:127]
	v_mfma_f32_16x16x32_bf16 v[112:115], v[84:87], v[192:195], v[112:115]
	v_mfma_f32_16x16x32_bf16 v[108:111], v[96:99], v[192:195], v[108:111]
	v_mfma_f32_16x16x32_bf16 v[80:83], v[84:87], v[200:203], v[80:83]
	v_mfma_f32_16x16x32_bf16 v[76:79], v[96:99], v[200:203], v[76:79]
	v_mfma_f32_16x16x32_bf16 v[144:147], v[88:91], v[180:183], v[144:147]
	v_mfma_f32_16x16x32_bf16 v[140:143], v[104:107], v[180:183], v[140:143]
	v_mfma_f32_16x16x32_bf16 v[128:131], v[88:91], v[188:191], v[128:131]
	v_mfma_f32_16x16x32_bf16 v[124:127], v[104:107], v[188:191], v[124:127]
	v_mfma_f32_16x16x32_bf16 v[112:115], v[88:91], v[196:199], v[112:115]
	v_mfma_f32_16x16x32_bf16 v[108:111], v[104:107], v[196:199], v[108:111]
	v_mfma_f32_16x16x32_bf16 v[80:83], v[88:91], v[214:217], v[80:83]
	v_mfma_f32_16x16x32_bf16 v[76:79], v[104:107], v[214:217], v[76:79]
	v_mfma_f32_16x16x32_bf16 v[136:139], v[148:151], v[172:175], v[136:139]
	v_mfma_f32_16x16x32_bf16 v[132:135], v[156:159], v[172:175], v[132:135]
	v_mfma_f32_16x16x32_bf16 v[120:123], v[148:151], v[184:187], v[120:123]
	v_mfma_f32_16x16x32_bf16 v[116:119], v[156:159], v[184:187], v[116:119]
	v_mfma_f32_16x16x32_bf16 v[100:103], v[148:151], v[192:195], v[100:103]
	v_mfma_f32_16x16x32_bf16 v[92:95], v[156:159], v[192:195], v[92:95]
	v_mfma_f32_16x16x32_bf16 v[72:75], v[148:151], v[200:203], v[72:75]
	v_mfma_f32_16x16x32_bf16 v[68:71], v[156:159], v[200:203], v[68:71]
	v_mfma_f32_16x16x32_bf16 v[136:139], v[152:155], v[180:183], v[136:139]
	v_mfma_f32_16x16x32_bf16 v[132:135], v[168:171], v[180:183], v[132:135]
	v_mfma_f32_16x16x32_bf16 v[120:123], v[152:155], v[188:191], v[120:123]
	v_mfma_f32_16x16x32_bf16 v[116:119], v[168:171], v[188:191], v[116:119]
	v_mfma_f32_16x16x32_bf16 v[100:103], v[152:155], v[196:199], v[100:103]
	v_mfma_f32_16x16x32_bf16 v[92:95], v[168:171], v[196:199], v[92:95]
	v_mfma_f32_16x16x32_bf16 v[72:75], v[152:155], v[214:217], v[72:75]
	v_mfma_f32_16x16x32_bf16 v[68:71], v[168:171], v[214:217], v[68:71]
	s_barrier
; #define PG8_STAGEX(b, gbase) do { if constexpr (XR) { if (lane < 16) __builtin_amdgcn_global_load_lds((const unsigned*)((const char*)(gbase) + voffX), (PG8_LAS unsigned*)(lds + XR_OFF + (b) * 2048 + wid * 256), 16, 0, 0); } } while (0)
; #define PG8_WAIT_LOOP() do { if constexpr (XR) PG8_WAIT_V(9); else PG8_WAIT_V(8); } while (0)
; #define PG8_STAGE(bufoff, gbase, voff) do { _Pragma("unroll") for (int _i = 0; _i < 2; ++_i) \
;         __builtin_amdgcn_global_load_lds((const unsigned*)((const char*)(gbase) + (voff)[_i]), (PG8_LAS unsigned*)(lds + (bufoff) + ldsw + _i * 8192), 16, 0, 0); } while (0)
; #define PG8_LDA(dst, b, h) do { _Pragma("unroll") for (int m = 0; m < 4; ++m) _Pragma("unroll") for (int k = 0; k < 2; ++k) dst[m][k] = *(const PG8_LAS bf16x8*)(lds + PG8_SA(b, h) + aoff + m * 2048 + k * 1024); } while (0)
; #define PG8_MMA(ai, bj, At, Bt) do { __builtin_amdgcn_s_setprio(1); _Pragma("unroll") for (int m = 0; m < 4; ++m) _Pragma("unroll") for (int n = 0; n < 2; ++n) _Pragma("unroll") for (int k = 0; k < 2; ++k) \
;         acc[ai][bj][m][n] = __builtin_amdgcn_mfma_f32_16x16x32_bf16(Bt[n][k], At[m][k], acc[ai][bj][m][n], 0, 0, 0); __builtin_amdgcn_s_setprio(0); } while (0)
; #define PG8_WAIT_L(n) asm volatile("s_waitcnt lgkmcnt(" #n ")" ::: "memory")
; #define PG8_BAR __builtin_amdgcn_s_barrier()
; #define PG8_SCHED __builtin_amdgcn_sched_barrier(0)
; template <class Epi, class Sched, bool ALIGN_EPI = false, bool SP2 = false, bool DRAIN = true, bool XR = false>
; __device__ __forceinline__ void gemm_phase(PG8_LAS unsigned char* lds, const Gemm g, const Sched& S, const Epi& E) {
;     ...
;             PG8_LDA(At, 1, 1); PG8_STAGE(PG8_SB(1, 0), b3, voffB); PG8_STAGE(PG8_SB(1, 1), b3 + hstep, voffB); PG8_STAGE(PG8_SA(1, 0), a3, voffA); PG8_STAGEX(1, x3);
;             PG8_WAIT_LOOP(); PG8_WAIT_L(0); PG8_BAR; PG8_MMA(1, 0, At, B0); PG8_MMA(1, 1, At, B1); PG8_BAR; PG8_SCHED;
	s_add_i32 s4, s36, s51
	v_lshl_add_u64 v[204:205], v[204:205], 0, s[86:87]
	s_mov_b32 m0, s4
	ds_read_b128 v[172:175], v178 offset:49152
	ds_read_b128 v[180:183], v178 offset:50176
	ds_read_b128 v[184:187], v178 offset:51200
	ds_read_b128 v[188:191], v178 offset:52224
	ds_read_b128 v[192:195], v178 offset:53248
	ds_read_b128 v[196:199], v178 offset:54272
	ds_read_b128 v[200:203], v178 offset:55296
	ds_read_b128 v[214:217], v178 offset:56320
	global_load_lds_dwordx4 v[204:205], off
	v_lshl_add_u64 v[204:205], v[206:207], 0, s[86:87]
	s_add_i32 m0, s4, 0x2000
	s_add_i32 s4, s73, s51
	global_load_lds_dwordx4 v[204:205], off
	v_lshl_add_u64 v[204:205], v[208:209], 0, s[86:87]
	s_mov_b32 m0, s4
	s_nop 0
	global_load_lds_dwordx4 v[204:205], off
	v_lshl_add_u64 v[204:205], v[212:213], 0, s[86:87]
	s_add_i32 m0, s4, 0x2000
	s_nop 0
	global_load_lds_dwordx4 v[204:205], off
	v_lshl_add_u64 v[204:205], v[218:219], 0, s[86:87]
	s_mov_b32 m0, s62
	s_nop 0
	global_load_lds_dwordx4 v[204:205], off
	v_lshl_add_u64 v[204:205], v[220:221], 0, s[86:87]
	s_mov_b32 m0, s63
	s_nop 0
	global_load_lds_dwordx4 v[204:205], off
	s_waitcnt vmcnt(8)
	s_waitcnt lgkmcnt(0)
	s_barrier
	v_mfma_f32_16x16x32_bf16 v[64:67], v[84:87], v[172:175], v[64:67]
	v_mfma_f32_16x16x32_bf16 v[60:63], v[96:99], v[172:175], v[60:63]
	v_mfma_f32_16x16x32_bf16 v[48:51], v[84:87], v[184:187], v[48:51]
	v_mfma_f32_16x16x32_bf16 v[44:47], v[96:99], v[184:187], v[44:47]
	v_mfma_f32_16x16x32_bf16 v[32:35], v[84:87], v[192:195], v[32:35]
	v_mfma_f32_16x16x32_bf16 v[28:31], v[96:99], v[192:195], v[28:31]
	v_mfma_f32_16x16x32_bf16 v[16:19], v[84:87], v[200:203], v[16:19]
	v_mfma_f32_16x16x32_bf16 v[12:15], v[96:99], v[200:203], v[12:15]
	v_mfma_f32_16x16x32_bf16 v[64:67], v[88:91], v[180:183], v[64:67]
	v_mfma_f32_16x16x32_bf16 v[60:63], v[104:107], v[180:183], v[60:63]
	v_mfma_f32_16x16x32_bf16 v[48:51], v[88:91], v[188:191], v[48:51]
	v_mfma_f32_16x16x32_bf16 v[44:47], v[104:107], v[188:191], v[44:47]
	v_mfma_f32_16x16x32_bf16 v[32:35], v[88:91], v[196:199], v[32:35]
	v_mfma_f32_16x16x32_bf16 v[28:31], v[104:107], v[196:199], v[28:31]
	v_mfma_f32_16x16x32_bf16 v[16:19], v[88:91], v[214:217], v[16:19]
	v_mfma_f32_16x16x32_bf16 v[12:15], v[104:107], v[214:217], v[12:15]
	v_mfma_f32_16x16x32_bf16 v[56:59], v[148:151], v[172:175], v[56:59]
	v_mfma_f32_16x16x32_bf16 v[52:55], v[156:159], v[172:175], v[52:55]
	v_mfma_f32_16x16x32_bf16 v[40:43], v[148:151], v[184:187], v[40:43]
	v_mfma_f32_16x16x32_bf16 v[36:39], v[156:159], v[184:187], v[36:39]
	v_mfma_f32_16x16x32_bf16 v[24:27], v[148:151], v[192:195], v[24:27]
	v_mfma_f32_16x16x32_bf16 v[20:23], v[156:159], v[192:195], v[20:23]
	v_mfma_f32_16x16x32_bf16 v[8:11], v[148:151], v[200:203], v[8:11]
	v_mfma_f32_16x16x32_bf16 v[4:7], v[156:159], v[200:203], v[4:7]
	v_mfma_f32_16x16x32_bf16 v[56:59], v[152:155], v[180:183], v[56:59]
	v_mfma_f32_16x16x32_bf16 v[52:55], v[168:171], v[180:183], v[52:55]
	v_mfma_f32_16x16x32_bf16 v[40:43], v[152:155], v[188:191], v[40:43]
	v_mfma_f32_16x16x32_bf16 v[36:39], v[168:171], v[188:191], v[36:39]
	v_mfma_f32_16x16x32_bf16 v[24:27], v[152:155], v[196:199], v[24:27]
	v_mfma_f32_16x16x32_bf16 v[20:23], v[168:171], v[196:199], v[20:23]
	v_mfma_f32_16x16x32_bf16 v[8:11], v[152:155], v[214:217], v[8:11]
	v_mfma_f32_16x16x32_bf16 v[4:7], v[168:171], v[214:217], v[4:7]
	s_barrier
	s_add_i32 s4, s72, 2
	s_cmp_ge_i32 s72, s60
	s_mov_b32 s72, s4
	s_cbranch_scc0 .LBB0_1020

; #define PG8_LDX(b) do { if constexpr (XR) { _Pragma("unroll") for (int k = 0; k < 2; ++k) Ax_[k] = *(const PG8_LAS bf16x8*)(lds + XR_OFF + (b) * 2048 + aoffx + k * 1024); } } while (0)
; #define PG8_MMAX() do { if constexpr (XR) { if (hasx) { __builtin_amdgcn_s_setprio(1); if (wr == 0) PG8_MMAX_(B0); else PG8_MMAX_(B1); __builtin_amdgcn_s_setprio(0); } } } while (0)
; #define PG8_WAIT_LOOP() do { if constexpr (XR) PG8_WAIT_V(9); else PG8_WAIT_V(8); } while (0)
; #define PG8_STAGE(bufoff, gbase, voff) do { _Pragma("unroll") for (int _i = 0; _i < 2; ++_i) \
;         __builtin_amdgcn_global_load_lds((const unsigned*)((const char*)(gbase) + (voff)[_i]), (PG8_LAS unsigned*)(lds + (bufoff) + ldsw + _i * 8192), 16, 0, 0); } while (0)
; #define PG8_LDA(dst, b, h) do { _Pragma("unroll") for (int m = 0; m < 4; ++m) _Pragma("unroll") for (int k = 0; k < 2; ++k) dst[m][k] = *(const PG8_LAS bf16x8*)(lds + PG8_SA(b, h) + aoff + m * 2048 + k * 1024); } while (0)
; #define PG8_LDB(dst, b, h) do { _Pragma("unroll") for (int n = 0; n < 2; ++n) _Pragma("unroll") for (int k = 0; k < 2; ++k) dst[n][k] = *(const PG8_LAS bf16x8*)(lds + PG8_SB(b, h) + boff + n * 2048 + k * 1024); } while (0)
; #define PG8_MMA(ai, bj, At, Bt) do { __builtin_amdgcn_s_setprio(1); _Pragma("unroll") for (int m = 0; m < 4; ++m) _Pragma("unroll") for (int n = 0; n < 2; ++n) _Pragma("unroll") for (int k = 0; k < 2; ++k) \
;         acc[ai][bj][m][n] = __builtin_amdgcn_mfma_f32_16x16x32_bf16(Bt[n][k], At[m][k], acc[ai][bj][m][n], 0, 0, 0); __builtin_amdgcn_s_setprio(0); } while (0)
; #define PG8_WAIT_L(n) asm volatile("s_waitcnt lgkmcnt(" #n ")" ::: "memory")
; #define PG8_BAR __builtin_amdgcn_s_barrier()
; #define PG8_SCHED __builtin_amdgcn_sched_barrier(0)
; template <class Epi, class Sched, bool ALIGN_EPI = false, bool SP2 = false, bool DRAIN = true, bool XR = false>
; __device__ __forceinline__ void gemm_phase(PG8_LAS unsigned char* lds, const Gemm g, const Sched& S, const Epi& E) {
;     ...
;             PG8_LDB(B0, 0, 0); PG8_LDB(B1, 0, 1); PG8_SCHED; PG8_LDA(At, 0, 0); PG8_LDX(0); PG8_STAGE(PG8_SA(1, 1), a1 + hstepA, voffA);
;             PG8_WAIT_LOOP(); PG8_WAIT_L(0); PG8_BAR; PG8_MMA(0, 0, At, B0); PG8_MMA(0, 1, At, B1); PG8_MMAX(); PG8_BAR; PG8_SCHED;
.LBB0_1220:
	v_add_u32_e32 v4, 0x10000, v250
	ds_read_b128 v[158:161], v4
	ds_read_b128 v[162:165], v4 offset:1024
	ds_read_b128 v[166:169], v4 offset:2048
	ds_read_b128 v[170:173], v4 offset:3072
	v_add_u32_e32 v4, 0x14000, v250
	s_and_b32 s8, s50, s82
	ds_read_b128 v[142:145], v4
	ds_read_b128 v[146:149], v4 offset:1024
	ds_read_b128 v[150:153], v4 offset:2048
	ds_read_b128 v[154:157], v4 offset:3072
	s_lshr_b32 s84, s8, 2
	s_lshl_b32 s8, s8, 7
	s_lshl_b64 s[6:7], s[84:85], 9
	s_and_b32 s8, s8, 0x100
	s_add_u32 s6, s18, s6
	s_addc_u32 s7, s19, s7
	s_add_u32 s6, s6, s8
	s_addc_u32 s7, s7, 0
	s_add_u32 s6, s6, s10
	v_add_u32_e32 v4, 0x22400, v240
	s_addc_u32 s7, s7, s11
	ds_read_b128 v[182:185], v251
	ds_read_b128 v[186:189], v251 offset:1024
	ds_read_b128 v[190:193], v251 offset:2048
	ds_read_b128 v[194:197], v251 offset:3072
	ds_read_b128 v[198:201], v251 offset:4096
	ds_read_b128 v[202:205], v251 offset:5120
	ds_read_b128 v[224:227], v251 offset:6144
	ds_read_b128 v[228:231], v251 offset:7168
	ds_read_b128 v[174:177], v4
	ds_read_b128 v[178:181], v4 offset:1024
	v_lshl_add_u64 v[4:5], s[6:7], 0, v[214:215]
	v_lshl_add_u64 v[4:5], v[4:5], 0, s[86:87]
	s_add_i32 m0, s64, 0xc000
	s_nop 0
	global_load_lds_dwordx4 v[4:5], off
	v_lshl_add_u64 v[4:5], s[6:7], 0, v[218:219]
	v_lshl_add_u64 v[4:5], v[4:5], 0, s[86:87]
	s_add_i32 m0, s64, 0xe000
	s_nop 0
	global_load_lds_dwordx4 v[4:5], off
	s_waitcnt vmcnt(9)
	s_waitcnt lgkmcnt(0)
	s_barrier
	v_mfma_f32_16x16x32_bf16 v[138:141], v[158:161], v[182:185], v[138:141]
	v_mfma_f32_16x16x32_bf16 v[134:137], v[166:169], v[182:185], v[134:137]
	v_mfma_f32_16x16x32_bf16 v[130:133], v[158:161], v[190:193], v[130:133]
	v_mfma_f32_16x16x32_bf16 v[126:129], v[166:169], v[190:193], v[126:129]
	v_mfma_f32_16x16x32_bf16 v[122:125], v[158:161], v[198:201], v[122:125]
	v_mfma_f32_16x16x32_bf16 v[118:121], v[166:169], v[198:201], v[118:121]
	v_mfma_f32_16x16x32_bf16 v[114:117], v[158:161], v[224:227], v[114:117]
	v_mfma_f32_16x16x32_bf16 v[110:113], v[166:169], v[224:227], v[110:113]
	v_mfma_f32_16x16x32_bf16 v[138:141], v[162:165], v[186:189], v[138:141]
	v_mfma_f32_16x16x32_bf16 v[134:137], v[170:173], v[186:189], v[134:137]
	v_mfma_f32_16x16x32_bf16 v[130:133], v[162:165], v[194:197], v[130:133]
	v_mfma_f32_16x16x32_bf16 v[126:129], v[170:173], v[194:197], v[126:129]
	v_mfma_f32_16x16x32_bf16 v[122:125], v[162:165], v[202:205], v[122:125]
	v_mfma_f32_16x16x32_bf16 v[118:121], v[170:173], v[202:205], v[118:121]
	v_mfma_f32_16x16x32_bf16 v[114:117], v[162:165], v[228:231], v[114:117]
	v_mfma_f32_16x16x32_bf16 v[110:113], v[170:173], v[228:231], v[110:113]
	v_mfma_f32_16x16x32_bf16 v[106:109], v[142:145], v[182:185], v[106:109]
	v_mfma_f32_16x16x32_bf16 v[102:105], v[150:153], v[182:185], v[102:105]
	v_mfma_f32_16x16x32_bf16 v[98:101], v[142:145], v[190:193], v[98:101]
	v_mfma_f32_16x16x32_bf16 v[94:97], v[150:153], v[190:193], v[94:97]
	v_mfma_f32_16x16x32_bf16 v[90:93], v[142:145], v[198:201], v[90:93]
	v_mfma_f32_16x16x32_bf16 v[86:89], v[150:153], v[198:201], v[86:89]
	v_mfma_f32_16x16x32_bf16 v[82:85], v[142:145], v[224:227], v[82:85]
	v_mfma_f32_16x16x32_bf16 v[78:81], v[150:153], v[224:227], v[78:81]
	v_mfma_f32_16x16x32_bf16 v[106:109], v[146:149], v[186:189], v[106:109]
	v_mfma_f32_16x16x32_bf16 v[102:105], v[154:157], v[186:189], v[102:105]
	v_mfma_f32_16x16x32_bf16 v[98:101], v[146:149], v[194:197], v[98:101]
	v_mfma_f32_16x16x32_bf16 v[94:97], v[154:157], v[194:197], v[94:97]
	v_mfma_f32_16x16x32_bf16 v[90:93], v[146:149], v[202:205], v[90:93]
	v_mfma_f32_16x16x32_bf16 v[86:89], v[154:157], v[202:205], v[86:89]
	v_mfma_f32_16x16x32_bf16 v[82:85], v[146:149], v[228:231], v[82:85]
	v_mfma_f32_16x16x32_bf16 v[78:81], v[154:157], v[228:231], v[78:81]
	v_cndmask_b32_e64 v4, 0, 1, s[22:23]
	v_cmp_ne_u32_e64 s[8:9], 1, v4
	v_cndmask_b32_e64 v4, 0, 1, s[40:41]
	s_andn2_b64 vcc, exec, s[22:23]
	v_cmp_ne_u32_e64 s[6:7], 1, v4
	s_cbranch_vccnz .LBB0_1226
	s_setprio 1
	s_and_b64 vcc, exec, s[6:7]
	s_mov_b64 s[48:49], -1
	s_cbranch_vccnz .LBB0_1223
	v_mfma_f32_16x16x32_bf16 v[10:13], v[142:145], v[174:177], v[10:13]
	s_mov_b64 s[48:49], 0
	v_mfma_f32_16x16x32_bf16 v[6:9], v[150:153], v[174:177], v[6:9]
	v_mfma_f32_16x16x32_bf16 v[10:13], v[146:149], v[178:181], v[10:13]
	v_mfma_f32_16x16x32_bf16 v[6:9], v[154:157], v[178:181], v[6:9]

; #define PG8_STAGEX(b, gbase) do { if constexpr (XR) { if (lane < 16) __builtin_amdgcn_global_load_lds((const unsigned*)((const char*)(gbase) + voffX), (PG8_LAS unsigned*)(lds + XR_OFF + (b) * 2048 + wid * 256), 16, 0, 0); } } while (0)
; #define PG8_LDX(b) do { if constexpr (XR) { _Pragma("unroll") for (int k = 0; k < 2; ++k) Ax_[k] = *(const PG8_LAS bf16x8*)(lds + XR_OFF + (b) * 2048 + aoffx + k * 1024); } } while (0)
; #define PG8_MMAX() do { if constexpr (XR) { if (hasx) { __builtin_amdgcn_s_setprio(1); if (wr == 0) PG8_MMAX_(B0); else PG8_MMAX_(B1); __builtin_amdgcn_s_setprio(0); } } } while (0)
; #define PG8_WAIT_LOOP() do { if constexpr (XR) PG8_WAIT_V(9); else PG8_WAIT_V(8); } while (0)
; #define PG8_STAGE(bufoff, gbase, voff) do { _Pragma("unroll") for (int _i = 0; _i < 2; ++_i) \
;         __builtin_amdgcn_global_load_lds((const unsigned*)((const char*)(gbase) + (voff)[_i]), (PG8_LAS unsigned*)(lds + (bufoff) + ldsw + _i * 8192), 16, 0, 0); } while (0)
; #define PG8_LDA(dst, b, h) do { _Pragma("unroll") for (int m = 0; m < 4; ++m) _Pragma("unroll") for (int k = 0; k < 2; ++k) dst[m][k] = *(const PG8_LAS bf16x8*)(lds + PG8_SA(b, h) + aoff + m * 2048 + k * 1024); } while (0)
; #define PG8_LDB(dst, b, h) do { _Pragma("unroll") for (int n = 0; n < 2; ++n) _Pragma("unroll") for (int k = 0; k < 2; ++k) dst[n][k] = *(const PG8_LAS bf16x8*)(lds + PG8_SB(b, h) + boff + n * 2048 + k * 1024); } while (0)
; #define PG8_WAIT_L(n) asm volatile("s_waitcnt lgkmcnt(" #n ")" ::: "memory")
; #define PG8_BAR __builtin_amdgcn_s_barrier()
; template <class Epi, class Sched, bool ALIGN_EPI = false, bool SP2 = false, bool DRAIN = true, bool XR = false>
; __device__ __forceinline__ void gemm_phase(PG8_LAS unsigned char* lds, const Gemm g, const Sched& S, const Epi& E) {
;     ...
;             PG8_LDA(At, 0, 1); PG8_STAGE(PG8_SB(0, 0), b2, voffB); PG8_STAGE(PG8_SB(0, 1), b2 + hstep, voffB); PG8_STAGE(PG8_SA(0, 0), a2, voffA); PG8_STAGEX(0, x2);
;             PG8_WAIT_LOOP(); PG8_WAIT_L(0); PG8_BAR; PG8_MMA(1, 0, At, B0); PG8_MMA(1, 1, At, B1); PG8_BAR; PG8_SCHED;
;             PG8_LDB(B0, 1, 0); PG8_LDB(B1, 1, 1); PG8_SCHED; PG8_LDA(At, 1, 0); PG8_LDX(1); PG8_STAGE(PG8_SA(0, 1), a2 + hstepA, voffA);
;             PG8_WAIT_LOOP(); PG8_WAIT_L(0); PG8_BAR; PG8_MMA(0, 0, At, B0); PG8_MMA(0, 1, At, B1); PG8_MMAX(); PG8_BAR; PG8_SCHED;
.LBB0_1228:
	s_or_b64 exec, exec, s[50:51]
	s_waitcnt vmcnt(9)
	s_waitcnt lgkmcnt(0)
	s_barrier
	v_mfma_f32_16x16x32_bf16 v[74:77], v[158:161], v[198:201], v[74:77]
	v_mfma_f32_16x16x32_bf16 v[70:73], v[166:169], v[198:201], v[70:73]
	v_mfma_f32_16x16x32_bf16 v[66:69], v[158:161], v[190:193], v[66:69]
	v_mfma_f32_16x16x32_bf16 v[62:65], v[166:169], v[190:193], v[62:65]
	v_mfma_f32_16x16x32_bf16 v[58:61], v[158:161], v[182:185], v[58:61]
	v_mfma_f32_16x16x32_bf16 v[54:57], v[166:169], v[182:185], v[54:57]
	v_mfma_f32_16x16x32_bf16 v[50:53], v[158:161], v[174:177], v[50:53]
	v_mfma_f32_16x16x32_bf16 v[46:49], v[166:169], v[174:177], v[46:49]
	v_mfma_f32_16x16x32_bf16 v[74:77], v[162:165], v[202:205], v[74:77]
	v_mfma_f32_16x16x32_bf16 v[70:73], v[170:173], v[202:205], v[70:73]
	v_mfma_f32_16x16x32_bf16 v[66:69], v[162:165], v[194:197], v[66:69]
	v_mfma_f32_16x16x32_bf16 v[62:65], v[170:173], v[194:197], v[62:65]
	v_mfma_f32_16x16x32_bf16 v[58:61], v[162:165], v[186:189], v[58:61]
	v_mfma_f32_16x16x32_bf16 v[54:57], v[170:173], v[186:189], v[54:57]
	v_mfma_f32_16x16x32_bf16 v[50:53], v[162:165], v[178:181], v[50:53]
	v_mfma_f32_16x16x32_bf16 v[46:49], v[170:173], v[178:181], v[46:49]
	v_mfma_f32_16x16x32_bf16 v[42:45], v[142:145], v[198:201], v[42:45]
	v_mfma_f32_16x16x32_bf16 v[38:41], v[150:153], v[198:201], v[38:41]
	v_mfma_f32_16x16x32_bf16 v[34:37], v[142:145], v[190:193], v[34:37]
	v_mfma_f32_16x16x32_bf16 v[30:33], v[150:153], v[190:193], v[30:33]
	v_mfma_f32_16x16x32_bf16 v[26:29], v[142:145], v[182:185], v[26:29]
	v_mfma_f32_16x16x32_bf16 v[22:25], v[150:153], v[182:185], v[22:25]
	v_mfma_f32_16x16x32_bf16 v[18:21], v[142:145], v[174:177], v[18:21]
	v_mfma_f32_16x16x32_bf16 v[14:17], v[150:153], v[174:177], v[14:17]
	v_mfma_f32_16x16x32_bf16 v[42:45], v[146:149], v[202:205], v[42:45]
	v_mfma_f32_16x16x32_bf16 v[38:41], v[154:157], v[202:205], v[38:41]
	v_mfma_f32_16x16x32_bf16 v[34:37], v[146:149], v[194:197], v[34:37]
	v_mfma_f32_16x16x32_bf16 v[30:33], v[154:157], v[194:197], v[30:33]
	v_mfma_f32_16x16x32_bf16 v[26:29], v[146:149], v[186:189], v[26:29]
	v_mfma_f32_16x16x32_bf16 v[22:25], v[154:157], v[186:189], v[22:25]
	v_mfma_f32_16x16x32_bf16 v[18:21], v[146:149], v[178:181], v[18:21]
	v_mfma_f32_16x16x32_bf16 v[14:17], v[154:157], v[178:181], v[14:17]
	s_barrier
	v_add_u32_e32 v142, 0x18000, v250
	v_add_u32_e32 v154, 0x1c000, v250
	ds_read_b128 v[158:161], v142
	ds_read_b128 v[162:165], v142 offset:1024
	ds_read_b128 v[166:169], v142 offset:2048
	ds_read_b128 v[170:173], v142 offset:3072
	ds_read_b128 v[142:145], v154
	ds_read_b128 v[146:149], v154 offset:1024
	ds_read_b128 v[150:153], v154 offset:2048
	ds_read_b128 v[154:157], v154 offset:3072
	s_add_u32 s48, s48, s10
	s_addc_u32 s49, s49, s11
	s_mov_b32 m0, s71
	v_add_u32_e32 v178, 0x22c00, v240
	ds_read_b128 v[182:185], v251 offset:32768
	ds_read_b128 v[186:189], v251 offset:33792
	ds_read_b128 v[190:193], v251 offset:34816
	ds_read_b128 v[194:197], v251 offset:35840
	ds_read_b128 v[198:201], v251 offset:36864
	ds_read_b128 v[202:205], v251 offset:37888
	ds_read_b128 v[242:245], v251 offset:38912
	ds_read_b128 v[206:209], v251 offset:39936
	ds_read_b128 v[174:177], v178
	ds_read_b128 v[178:181], v178 offset:1024
	global_load_lds_dwordx4 v214, s[48:49]
	s_mov_b32 m0, s72
	s_nop 0
	global_load_lds_dwordx4 v218, s[48:49]
	s_waitcnt vmcnt(9)
	s_waitcnt lgkmcnt(0)
	s_barrier
	v_mfma_f32_16x16x32_bf16 v[138:141], v[158:161], v[182:185], v[138:141]
	v_mfma_f32_16x16x32_bf16 v[134:137], v[166:169], v[182:185], v[134:137]
	v_mfma_f32_16x16x32_bf16 v[130:133], v[158:161], v[190:193], v[130:133]
	v_mfma_f32_16x16x32_bf16 v[126:129], v[166:169], v[190:193], v[126:129]
	v_mfma_f32_16x16x32_bf16 v[122:125], v[158:161], v[198:201], v[122:125]
	v_mfma_f32_16x16x32_bf16 v[118:121], v[166:169], v[198:201], v[118:121]
	v_mfma_f32_16x16x32_bf16 v[114:117], v[158:161], v[242:245], v[114:117]
	v_mfma_f32_16x16x32_bf16 v[110:113], v[166:169], v[242:245], v[110:113]
	v_mfma_f32_16x16x32_bf16 v[138:141], v[162:165], v[186:189], v[138:141]
	v_mfma_f32_16x16x32_bf16 v[134:137], v[170:173], v[186:189], v[134:137]
	v_mfma_f32_16x16x32_bf16 v[130:133], v[162:165], v[194:197], v[130:133]
	v_mfma_f32_16x16x32_bf16 v[126:129], v[170:173], v[194:197], v[126:129]
	v_mfma_f32_16x16x32_bf16 v[122:125], v[162:165], v[202:205], v[122:125]
	v_mfma_f32_16x16x32_bf16 v[118:121], v[170:173], v[202:205], v[118:121]
	v_mfma_f32_16x16x32_bf16 v[114:117], v[162:165], v[206:209], v[114:117]
	v_mfma_f32_16x16x32_bf16 v[110:113], v[170:173], v[206:209], v[110:113]
	v_mfma_f32_16x16x32_bf16 v[106:109], v[142:145], v[182:185], v[106:109]
	v_mfma_f32_16x16x32_bf16 v[102:105], v[150:153], v[182:185], v[102:105]
	v_mfma_f32_16x16x32_bf16 v[98:101], v[142:145], v[190:193], v[98:101]
	v_mfma_f32_16x16x32_bf16 v[94:97], v[150:153], v[190:193], v[94:97]
	v_mfma_f32_16x16x32_bf16 v[90:93], v[142:145], v[198:201], v[90:93]
	v_mfma_f32_16x16x32_bf16 v[86:89], v[150:153], v[198:201], v[86:89]
	v_mfma_f32_16x16x32_bf16 v[82:85], v[142:145], v[242:245], v[82:85]
	v_mfma_f32_16x16x32_bf16 v[78:81], v[150:153], v[242:245], v[78:81]
	v_mfma_f32_16x16x32_bf16 v[106:109], v[146:149], v[186:189], v[106:109]
	v_mfma_f32_16x16x32_bf16 v[102:105], v[154:157], v[186:189], v[102:105]
	v_mfma_f32_16x16x32_bf16 v[98:101], v[146:149], v[194:197], v[98:101]
	v_mfma_f32_16x16x32_bf16 v[94:97], v[154:157], v[194:197], v[94:97]
	v_mfma_f32_16x16x32_bf16 v[90:93], v[146:149], v[202:205], v[90:93]
	v_mfma_f32_16x16x32_bf16 v[86:89], v[154:157], v[202:205], v[86:89]
	v_mfma_f32_16x16x32_bf16 v[82:85], v[146:149], v[206:209], v[82:85]
	v_mfma_f32_16x16x32_bf16 v[78:81], v[154:157], v[206:209], v[78:81]
	s_and_b64 vcc, exec, s[8:9]
	s_cbranch_vccnz .LBB0_1234
	s_setprio 1
	s_and_b64 vcc, exec, s[6:7]
	s_mov_b64 s[6:7], -1
	s_cbranch_vccnz .LBB0_1231
	v_mfma_f32_16x16x32_bf16 v[10:13], v[142:145], v[174:177], v[10:13]
	s_mov_b64 s[6:7], 0
	v_mfma_f32_16x16x32_bf16 v[6:9], v[150:153], v[174:177], v[6:9]
	v_mfma_f32_16x16x32_bf16 v[10:13], v[146:149], v[178:181], v[10:13]
	v_mfma_f32_16x16x32_bf16 v[6:9], v[154:157], v[178:181], v[6:9]

; #define PG8_STAGEX(b, gbase) do { if constexpr (XR) { if (lane < 16) __builtin_amdgcn_global_load_lds((const unsigned*)((const char*)(gbase) + voffX), (PG8_LAS unsigned*)(lds + XR_OFF + (b) * 2048 + wid * 256), 16, 0, 0); } } while (0)
; #define PG8_WAIT_LOOP() do { if constexpr (XR) PG8_WAIT_V(9); else PG8_WAIT_V(8); } while (0)
; #define PG8_STAGE(bufoff, gbase, voff) do { _Pragma("unroll") for (int _i = 0; _i < 2; ++_i) \
;         __builtin_amdgcn_global_load_lds((const unsigned*)((const char*)(gbase) + (voff)[_i]), (PG8_LAS unsigned*)(lds + (bufoff) + ldsw + _i * 8192), 16, 0, 0); } while (0)
; #define PG8_LDA(dst, b, h) do { _Pragma("unroll") for (int m = 0; m < 4; ++m) _Pragma("unroll") for (int k = 0; k < 2; ++k) dst[m][k] = *(const PG8_LAS bf16x8*)(lds + PG8_SA(b, h) + aoff + m * 2048 + k * 1024); } while (0)
; #define PG8_MMA(ai, bj, At, Bt) do { __builtin_amdgcn_s_setprio(1); _Pragma("unroll") for (int m = 0; m < 4; ++m) _Pragma("unroll") for (int n = 0; n < 2; ++n) _Pragma("unroll") for (int k = 0; k < 2; ++k) \
;         acc[ai][bj][m][n] = __builtin_amdgcn_mfma_f32_16x16x32_bf16(Bt[n][k], At[m][k], acc[ai][bj][m][n], 0, 0, 0); __builtin_amdgcn_s_setprio(0); } while (0)
; #define PG8_WAIT_L(n) asm volatile("s_waitcnt lgkmcnt(" #n ")" ::: "memory")
; #define PG8_BAR __builtin_amdgcn_s_barrier()
; #define PG8_SCHED __builtin_amdgcn_sched_barrier(0)
; template <class Epi, class Sched, bool ALIGN_EPI = false, bool SP2 = false, bool DRAIN = true, bool XR = false>
; __device__ __forceinline__ void gemm_phase(PG8_LAS unsigned char* lds, const Gemm g, const Sched& S, const Epi& E) {
;     ...
;         for (int t = 0; t < nt; t += 2) {
;             if constexpr (Epi::MIDSCALE) { if (t == (nt >> 1)) E.midscale(acc, cur, wr, fr); }
;     ...
;             PG8_LDA(At, 1, 1); PG8_STAGE(PG8_SB(1, 0), b3, voffB); PG8_STAGE(PG8_SB(1, 1), b3 + hstep, voffB); PG8_STAGE(PG8_SA(1, 0), a3, voffA); PG8_STAGEX(1, x3);
;             PG8_WAIT_LOOP(); PG8_WAIT_L(0); PG8_BAR; PG8_MMA(1, 0, At, B0); PG8_MMA(1, 1, At, B1); PG8_BAR; PG8_SCHED;
.LBB0_1236:
	s_or_b64 exec, exec, s[6:7]
	s_waitcnt vmcnt(9)
	s_waitcnt lgkmcnt(0)
	s_barrier
	v_mfma_f32_16x16x32_bf16 v[74:77], v[158:161], v[198:201], v[74:77]
	v_mfma_f32_16x16x32_bf16 v[70:73], v[166:169], v[198:201], v[70:73]
	v_mfma_f32_16x16x32_bf16 v[66:69], v[158:161], v[190:193], v[66:69]
	v_mfma_f32_16x16x32_bf16 v[62:65], v[166:169], v[190:193], v[62:65]
	v_mfma_f32_16x16x32_bf16 v[58:61], v[158:161], v[182:185], v[58:61]
	v_mfma_f32_16x16x32_bf16 v[54:57], v[166:169], v[182:185], v[54:57]
	v_mfma_f32_16x16x32_bf16 v[50:53], v[158:161], v[174:177], v[50:53]
	v_mfma_f32_16x16x32_bf16 v[46:49], v[166:169], v[174:177], v[46:49]
	v_mfma_f32_16x16x32_bf16 v[74:77], v[162:165], v[202:205], v[74:77]
	v_mfma_f32_16x16x32_bf16 v[70:73], v[170:173], v[202:205], v[70:73]
	v_mfma_f32_16x16x32_bf16 v[66:69], v[162:165], v[194:197], v[66:69]
	v_mfma_f32_16x16x32_bf16 v[62:65], v[170:173], v[194:197], v[62:65]
	v_mfma_f32_16x16x32_bf16 v[58:61], v[162:165], v[186:189], v[58:61]
	v_mfma_f32_16x16x32_bf16 v[54:57], v[170:173], v[186:189], v[54:57]
	v_mfma_f32_16x16x32_bf16 v[50:53], v[162:165], v[178:181], v[50:53]
	v_mfma_f32_16x16x32_bf16 v[46:49], v[170:173], v[178:181], v[46:49]
	v_mfma_f32_16x16x32_bf16 v[42:45], v[142:145], v[198:201], v[42:45]
	v_mfma_f32_16x16x32_bf16 v[38:41], v[150:153], v[198:201], v[38:41]
	v_mfma_f32_16x16x32_bf16 v[34:37], v[142:145], v[190:193], v[34:37]
	v_mfma_f32_16x16x32_bf16 v[30:33], v[150:153], v[190:193], v[30:33]
	v_mfma_f32_16x16x32_bf16 v[26:29], v[142:145], v[182:185], v[26:29]
	v_mfma_f32_16x16x32_bf16 v[22:25], v[150:153], v[182:185], v[22:25]
	v_mfma_f32_16x16x32_bf16 v[18:21], v[142:145], v[174:177], v[18:21]
	v_mfma_f32_16x16x32_bf16 v[14:17], v[150:153], v[174:177], v[14:17]
	v_mfma_f32_16x16x32_bf16 v[42:45], v[146:149], v[202:205], v[42:45]
	v_mfma_f32_16x16x32_bf16 v[38:41], v[154:157], v[202:205], v[38:41]
	v_mfma_f32_16x16x32_bf16 v[34:37], v[146:149], v[194:197], v[34:37]
	v_mfma_f32_16x16x32_bf16 v[30:33], v[154:157], v[194:197], v[30:33]
	v_mfma_f32_16x16x32_bf16 v[26:29], v[146:149], v[186:189], v[26:29]
	v_mfma_f32_16x16x32_bf16 v[22:25], v[154:157], v[186:189], v[22:25]
	v_mfma_f32_16x16x32_bf16 v[18:21], v[146:149], v[178:181], v[18:21]
	v_mfma_f32_16x16x32_bf16 v[14:17], v[154:157], v[178:181], v[14:17]
	s_barrier
	s_cmp_ge_i32 s89, s81
	s_cbranch_scc1 .LBB0_1238
	s_mov_b32 s50, s89
	s_cmp_lg_u32 s83, s50
	s_cbranch_scc0 .LBB0_1219
	s_branch .LBB0_1220

; #define PG8_LDX(b) do { if constexpr (XR) { _Pragma("unroll") for (int k = 0; k < 2; ++k) Ax_[k] = *(const PG8_LAS bf16x8*)(lds + XR_OFF + (b) * 2048 + aoffx + k * 1024); } } while (0)
; #define PG8_MMAX() do { if constexpr (XR) { if (hasx) { __builtin_amdgcn_s_setprio(1); if (wr == 0) PG8_MMAX_(B0); else PG8_MMAX_(B1); __builtin_amdgcn_s_setprio(0); } } } while (0)
; #define PG8_WAIT_LOOP() do { if constexpr (XR) PG8_WAIT_V(9); else PG8_WAIT_V(8); } while (0)
; #define PG8_STAGE(bufoff, gbase, voff) do { _Pragma("unroll") for (int _i = 0; _i < 2; ++_i) \
;         __builtin_amdgcn_global_load_lds((const unsigned*)((const char*)(gbase) + (voff)[_i]), (PG8_LAS unsigned*)(lds + (bufoff) + ldsw + _i * 8192), 16, 0, 0); } while (0)
; #define PG8_LDA(dst, b, h) do { _Pragma("unroll") for (int m = 0; m < 4; ++m) _Pragma("unroll") for (int k = 0; k < 2; ++k) dst[m][k] = *(const PG8_LAS bf16x8*)(lds + PG8_SA(b, h) + aoff + m * 2048 + k * 1024); } while (0)
; #define PG8_LDB(dst, b, h) do { _Pragma("unroll") for (int n = 0; n < 2; ++n) _Pragma("unroll") for (int k = 0; k < 2; ++k) dst[n][k] = *(const PG8_LAS bf16x8*)(lds + PG8_SB(b, h) + boff + n * 2048 + k * 1024); } while (0)
; #define PG8_MMA(ai, bj, At, Bt) do { __builtin_amdgcn_s_setprio(1); _Pragma("unroll") for (int m = 0; m < 4; ++m) _Pragma("unroll") for (int n = 0; n < 2; ++n) _Pragma("unroll") for (int k = 0; k < 2; ++k) \
;         acc[ai][bj][m][n] = __builtin_amdgcn_mfma_f32_16x16x32_bf16(Bt[n][k], At[m][k], acc[ai][bj][m][n], 0, 0, 0); __builtin_amdgcn_s_setprio(0); } while (0)
; #define PG8_WAIT_L(n) asm volatile("s_waitcnt lgkmcnt(" #n ")" ::: "memory")
; #define PG8_BAR __builtin_amdgcn_s_barrier()
; #define PG8_SCHED __builtin_amdgcn_sched_barrier(0)
; template <class Epi, class Sched, bool ALIGN_EPI = false, bool SP2 = false, bool DRAIN = true, bool XR = false>
; __device__ __forceinline__ void gemm_phase(PG8_LAS unsigned char* lds, const Gemm g, const Sched& S, const Epi& E) {
;     ...
;             PG8_LDB(B0, 0, 0); PG8_LDB(B1, 0, 1); PG8_SCHED; PG8_LDA(At, 0, 0); PG8_LDX(0); PG8_STAGE(PG8_SA(1, 1), a1 + hstepA, voffA);
;             PG8_WAIT_LOOP(); PG8_WAIT_L(0); PG8_BAR; PG8_MMA(0, 0, At, B0); PG8_MMA(0, 1, At, B1); PG8_MMAX(); PG8_BAR; PG8_SCHED;
.LBB0_1359:
	v_add_u32_e32 v2, 0x10000, v248
	s_add_i32 s4, s90, -2
	ds_read_b128 v[158:161], v2
	ds_read_b128 v[162:165], v2 offset:1024
	ds_read_b128 v[166:169], v2 offset:2048
	ds_read_b128 v[170:173], v2 offset:3072
	v_add_u32_e32 v2, 0x14000, v248
	s_and_b32 s6, s4, s73
	ds_read_b128 v[142:145], v2
	ds_read_b128 v[146:149], v2 offset:1024
	ds_read_b128 v[150:153], v2 offset:2048
	ds_read_b128 v[154:157], v2 offset:3072
	s_lshr_b32 s84, s6, 2
	s_lshl_b32 s6, s6, 7
	s_lshl_b64 s[4:5], s[84:85], 9
	s_and_b32 s6, s6, 0x100
	s_add_u32 s4, s56, s4
	s_addc_u32 s5, s57, s5
	s_add_u32 s4, s4, s6
	s_addc_u32 s5, s5, 0
	s_add_u32 s4, s4, s28
	s_addc_u32 s5, s5, s29
	v_lshl_add_u64 v[4:5], s[4:5], 0, v[220:221]
	v_add_u32_e32 v2, 0x22400, v250
	v_lshl_add_u64 v[4:5], v[4:5], 0, s[86:87]
	s_add_i32 m0, s13, 0xc000
	ds_read_b128 v[182:185], v249
	ds_read_b128 v[186:189], v249 offset:1024
	ds_read_b128 v[190:193], v249 offset:2048
	ds_read_b128 v[194:197], v249 offset:3072
	ds_read_b128 v[198:201], v249 offset:4096
	ds_read_b128 v[202:205], v249 offset:5120
	ds_read_b128 v[206:209], v249 offset:6144
	ds_read_b128 v[224:227], v249 offset:7168
	ds_read_b128 v[174:177], v2
	ds_read_b128 v[178:181], v2 offset:1024
	global_load_lds_dwordx4 v[4:5], off
	v_lshl_add_u64 v[4:5], s[4:5], 0, v[216:217]
	v_lshl_add_u64 v[4:5], v[4:5], 0, s[86:87]
	s_add_i32 m0, s13, 0xe000
	s_nop 0
	global_load_lds_dwordx4 v[4:5], off
	s_waitcnt vmcnt(9)
	s_waitcnt lgkmcnt(0)
	s_barrier
	v_mfma_f32_16x16x32_bf16 v[138:141], v[158:161], v[182:185], v[138:141]
	v_mfma_f32_16x16x32_bf16 v[134:137], v[166:169], v[182:185], v[134:137]
	v_mfma_f32_16x16x32_bf16 v[122:125], v[158:161], v[190:193], v[122:125]
	v_mfma_f32_16x16x32_bf16 v[118:121], v[166:169], v[190:193], v[118:121]
	v_mfma_f32_16x16x32_bf16 v[106:109], v[158:161], v[198:201], v[106:109]
	v_mfma_f32_16x16x32_bf16 v[102:105], v[166:169], v[198:201], v[102:105]
	v_mfma_f32_16x16x32_bf16 v[90:93], v[158:161], v[206:209], v[90:93]
	v_mfma_f32_16x16x32_bf16 v[86:89], v[166:169], v[206:209], v[86:89]
	v_mfma_f32_16x16x32_bf16 v[138:141], v[162:165], v[186:189], v[138:141]
	v_mfma_f32_16x16x32_bf16 v[134:137], v[170:173], v[186:189], v[134:137]
	v_mfma_f32_16x16x32_bf16 v[122:125], v[162:165], v[194:197], v[122:125]
	v_mfma_f32_16x16x32_bf16 v[118:121], v[170:173], v[194:197], v[118:121]
	v_mfma_f32_16x16x32_bf16 v[106:109], v[162:165], v[202:205], v[106:109]
	v_mfma_f32_16x16x32_bf16 v[102:105], v[170:173], v[202:205], v[102:105]
	v_mfma_f32_16x16x32_bf16 v[90:93], v[162:165], v[224:227], v[90:93]
	v_mfma_f32_16x16x32_bf16 v[86:89], v[170:173], v[224:227], v[86:89]
	v_mfma_f32_16x16x32_bf16 v[130:133], v[142:145], v[182:185], v[130:133]
	v_mfma_f32_16x16x32_bf16 v[126:129], v[150:153], v[182:185], v[126:129]
	v_mfma_f32_16x16x32_bf16 v[114:117], v[142:145], v[190:193], v[114:117]
	v_mfma_f32_16x16x32_bf16 v[110:113], v[150:153], v[190:193], v[110:113]
	v_mfma_f32_16x16x32_bf16 v[98:101], v[142:145], v[198:201], v[98:101]
	v_mfma_f32_16x16x32_bf16 v[94:97], v[150:153], v[198:201], v[94:97]
	v_mfma_f32_16x16x32_bf16 v[82:85], v[142:145], v[206:209], v[82:85]
	v_mfma_f32_16x16x32_bf16 v[78:81], v[150:153], v[206:209], v[78:81]
	v_mfma_f32_16x16x32_bf16 v[130:133], v[146:149], v[186:189], v[130:133]
	v_mfma_f32_16x16x32_bf16 v[126:129], v[154:157], v[186:189], v[126:129]
	v_mfma_f32_16x16x32_bf16 v[114:117], v[146:149], v[194:197], v[114:117]
	v_mfma_f32_16x16x32_bf16 v[110:113], v[154:157], v[194:197], v[110:113]
	v_mfma_f32_16x16x32_bf16 v[98:101], v[146:149], v[202:205], v[98:101]
	v_mfma_f32_16x16x32_bf16 v[94:97], v[154:157], v[202:205], v[94:97]
	v_mfma_f32_16x16x32_bf16 v[82:85], v[146:149], v[224:227], v[82:85]
	v_mfma_f32_16x16x32_bf16 v[78:81], v[154:157], v[224:227], v[78:81]
	v_cndmask_b32_e64 v2, 0, 1, s[46:47]
	v_cmp_ne_u32_e64 s[6:7], 1, v2
	v_cndmask_b32_e64 v2, 0, 1, s[44:45]
	s_andn2_b64 vcc, exec, s[46:47]
	v_cmp_ne_u32_e64 s[4:5], 1, v2
	s_cbranch_vccnz .LBB0_1365
	s_setprio 1
	s_and_b64 vcc, exec, s[4:5]
	s_mov_b64 s[60:61], -1
	s_cbranch_vccnz .LBB0_1362
	v_mfma_f32_16x16x32_bf16 v[10:13], v[142:145], v[174:177], v[10:13]
	s_mov_b64 s[60:61], 0
	v_mfma_f32_16x16x32_bf16 v[6:9], v[150:153], v[174:177], v[6:9]
	v_mfma_f32_16x16x32_bf16 v[10:13], v[146:149], v[178:181], v[10:13]
	v_mfma_f32_16x16x32_bf16 v[6:9], v[154:157], v[178:181], v[6:9]

; #define PG8_LDX(b) do { if constexpr (XR) { _Pragma("unroll") for (int k = 0; k < 2; ++k) Ax_[k] = *(const PG8_LAS bf16x8*)(lds + XR_OFF + (b) * 2048 + aoffx + k * 1024); } } while (0)
; #define PG8_MMAX() do { if constexpr (XR) { if (hasx) { __builtin_amdgcn_s_setprio(1); if (wr == 0) PG8_MMAX_(B0); else PG8_MMAX_(B1); __builtin_amdgcn_s_setprio(0); } } } while (0)
; #define PG8_WAIT_LOOP() do { if constexpr (XR) PG8_WAIT_V(9); else PG8_WAIT_V(8); } while (0)
; #define PG8_STAGE(bufoff, gbase, voff) do { _Pragma("unroll") for (int _i = 0; _i < 2; ++_i) \
;         __builtin_amdgcn_global_load_lds((const unsigned*)((const char*)(gbase) + (voff)[_i]), (PG8_LAS unsigned*)(lds + (bufoff) + ldsw + _i * 8192), 16, 0, 0); } while (0)
; #define PG8_LDA(dst, b, h) do { _Pragma("unroll") for (int m = 0; m < 4; ++m) _Pragma("unroll") for (int k = 0; k < 2; ++k) dst[m][k] = *(const PG8_LAS bf16x8*)(lds + PG8_SA(b, h) + aoff + m * 2048 + k * 1024); } while (0)
; #define PG8_LDB(dst, b, h) do { _Pragma("unroll") for (int n = 0; n < 2; ++n) _Pragma("unroll") for (int k = 0; k < 2; ++k) dst[n][k] = *(const PG8_LAS bf16x8*)(lds + PG8_SB(b, h) + boff + n * 2048 + k * 1024); } while (0)
; #define PG8_MMA(ai, bj, At, Bt) do { __builtin_amdgcn_s_setprio(1); _Pragma("unroll") for (int m = 0; m < 4; ++m) _Pragma("unroll") for (int n = 0; n < 2; ++n) _Pragma("unroll") for (int k = 0; k < 2; ++k) \
;         acc[ai][bj][m][n] = __builtin_amdgcn_mfma_f32_16x16x32_bf16(Bt[n][k], At[m][k], acc[ai][bj][m][n], 0, 0, 0); __builtin_amdgcn_s_setprio(0); } while (0)
; #define PG8_WAIT_L(n) asm volatile("s_waitcnt lgkmcnt(" #n ")" ::: "memory")
; #define PG8_BAR __builtin_amdgcn_s_barrier()
; #define PG8_SCHED __builtin_amdgcn_sched_barrier(0)
; template <class Epi, class Sched, bool ALIGN_EPI = false, bool SP2 = false, bool DRAIN = true, bool XR = false>
; __device__ __forceinline__ void gemm_phase(PG8_LAS unsigned char* lds, const Gemm g, const Sched& S, const Epi& E) {
;     ...
;             PG8_WAIT_LOOP(); PG8_WAIT_L(0); PG8_BAR; PG8_MMA(1, 0, At, B0); PG8_MMA(1, 1, At, B1); PG8_BAR; PG8_SCHED;
;             PG8_LDB(B0, 1, 0); PG8_LDB(B1, 1, 1); PG8_SCHED; PG8_LDA(At, 1, 0); PG8_LDX(1); PG8_STAGE(PG8_SA(0, 1), a2 + hstepA, voffA);
;             PG8_WAIT_LOOP(); PG8_WAIT_L(0); PG8_BAR; PG8_MMA(0, 0, At, B0); PG8_MMA(0, 1, At, B1); PG8_MMAX(); PG8_BAR; PG8_SCHED;
.LBB0_1367:
	s_or_b64 exec, exec, s[62:63]
	s_waitcnt vmcnt(9)
	s_waitcnt lgkmcnt(0)
	s_barrier
	v_mfma_f32_16x16x32_bf16 v[74:77], v[158:161], v[198:201], v[74:77]
	v_mfma_f32_16x16x32_bf16 v[70:73], v[166:169], v[198:201], v[70:73]
	v_mfma_f32_16x16x32_bf16 v[58:61], v[158:161], v[190:193], v[58:61]
	v_mfma_f32_16x16x32_bf16 v[54:57], v[166:169], v[190:193], v[54:57]
	v_mfma_f32_16x16x32_bf16 v[42:45], v[158:161], v[182:185], v[42:45]
	v_mfma_f32_16x16x32_bf16 v[38:41], v[166:169], v[182:185], v[38:41]
	v_mfma_f32_16x16x32_bf16 v[26:29], v[158:161], v[174:177], v[26:29]
	v_mfma_f32_16x16x32_bf16 v[22:25], v[166:169], v[174:177], v[22:25]
	v_mfma_f32_16x16x32_bf16 v[74:77], v[162:165], v[202:205], v[74:77]
	v_mfma_f32_16x16x32_bf16 v[70:73], v[170:173], v[202:205], v[70:73]
	v_mfma_f32_16x16x32_bf16 v[58:61], v[162:165], v[194:197], v[58:61]
	v_mfma_f32_16x16x32_bf16 v[54:57], v[170:173], v[194:197], v[54:57]
	v_mfma_f32_16x16x32_bf16 v[42:45], v[162:165], v[186:189], v[42:45]
	v_mfma_f32_16x16x32_bf16 v[38:41], v[170:173], v[186:189], v[38:41]
	v_mfma_f32_16x16x32_bf16 v[26:29], v[162:165], v[178:181], v[26:29]
	v_mfma_f32_16x16x32_bf16 v[22:25], v[170:173], v[178:181], v[22:25]
	v_mfma_f32_16x16x32_bf16 v[66:69], v[142:145], v[198:201], v[66:69]
	v_mfma_f32_16x16x32_bf16 v[62:65], v[150:153], v[198:201], v[62:65]
	v_mfma_f32_16x16x32_bf16 v[50:53], v[142:145], v[190:193], v[50:53]
	v_mfma_f32_16x16x32_bf16 v[46:49], v[150:153], v[190:193], v[46:49]
	v_mfma_f32_16x16x32_bf16 v[34:37], v[142:145], v[182:185], v[34:37]
	v_mfma_f32_16x16x32_bf16 v[30:33], v[150:153], v[182:185], v[30:33]
	v_mfma_f32_16x16x32_bf16 v[18:21], v[142:145], v[174:177], v[18:21]
	v_mfma_f32_16x16x32_bf16 v[14:17], v[150:153], v[174:177], v[14:17]
	v_mfma_f32_16x16x32_bf16 v[66:69], v[146:149], v[202:205], v[66:69]
	v_mfma_f32_16x16x32_bf16 v[62:65], v[154:157], v[202:205], v[62:65]
	v_mfma_f32_16x16x32_bf16 v[50:53], v[146:149], v[194:197], v[50:53]
	v_mfma_f32_16x16x32_bf16 v[46:49], v[154:157], v[194:197], v[46:49]
	v_mfma_f32_16x16x32_bf16 v[34:37], v[146:149], v[186:189], v[34:37]
	v_mfma_f32_16x16x32_bf16 v[30:33], v[154:157], v[186:189], v[30:33]
	v_mfma_f32_16x16x32_bf16 v[18:21], v[146:149], v[178:181], v[18:21]
	v_mfma_f32_16x16x32_bf16 v[14:17], v[154:157], v[178:181], v[14:17]
	s_barrier
	v_add_u32_e32 v2, 0x18000, v248
	ds_read_b128 v[158:161], v2
	ds_read_b128 v[162:165], v2 offset:1024
	ds_read_b128 v[166:169], v2 offset:2048
	ds_read_b128 v[170:173], v2 offset:3072
	v_add_u32_e32 v2, 0x1c000, v248
	ds_read_b128 v[142:145], v2
	ds_read_b128 v[146:149], v2 offset:1024
	ds_read_b128 v[150:153], v2 offset:2048
	ds_read_b128 v[154:157], v2 offset:3072
	s_add_u32 s8, s60, s28
	s_addc_u32 s9, s61, s29
	s_mov_b32 m0, s19
	v_add_u32_e32 v2, 0x22c00, v250
	ds_read_b128 v[182:185], v249 offset:32768
	ds_read_b128 v[186:189], v249 offset:33792
	ds_read_b128 v[190:193], v249 offset:34816
	ds_read_b128 v[194:197], v249 offset:35840
	ds_read_b128 v[198:201], v249 offset:36864
	ds_read_b128 v[202:205], v249 offset:37888
	ds_read_b128 v[206:209], v249 offset:38912
	ds_read_b128 v[242:245], v249 offset:39936
	ds_read_b128 v[174:177], v2
	ds_read_b128 v[178:181], v2 offset:1024
	global_load_lds_dwordx4 v220, s[8:9]
	s_mov_b32 m0, s22
	s_nop 0
	global_load_lds_dwordx4 v216, s[8:9]
	s_waitcnt vmcnt(9)
	s_waitcnt lgkmcnt(0)
	s_barrier
	v_mfma_f32_16x16x32_bf16 v[138:141], v[158:161], v[182:185], v[138:141]
	v_mfma_f32_16x16x32_bf16 v[134:137], v[166:169], v[182:185], v[134:137]
	v_mfma_f32_16x16x32_bf16 v[122:125], v[158:161], v[190:193], v[122:125]
	v_mfma_f32_16x16x32_bf16 v[118:121], v[166:169], v[190:193], v[118:121]
	v_mfma_f32_16x16x32_bf16 v[106:109], v[158:161], v[198:201], v[106:109]
	v_mfma_f32_16x16x32_bf16 v[102:105], v[166:169], v[198:201], v[102:105]
	v_mfma_f32_16x16x32_bf16 v[90:93], v[158:161], v[206:209], v[90:93]
	v_mfma_f32_16x16x32_bf16 v[86:89], v[166:169], v[206:209], v[86:89]
	v_mfma_f32_16x16x32_bf16 v[138:141], v[162:165], v[186:189], v[138:141]
	v_mfma_f32_16x16x32_bf16 v[134:137], v[170:173], v[186:189], v[134:137]
	v_mfma_f32_16x16x32_bf16 v[122:125], v[162:165], v[194:197], v[122:125]
	v_mfma_f32_16x16x32_bf16 v[118:121], v[170:173], v[194:197], v[118:121]
	v_mfma_f32_16x16x32_bf16 v[106:109], v[162:165], v[202:205], v[106:109]
	v_mfma_f32_16x16x32_bf16 v[102:105], v[170:173], v[202:205], v[102:105]
	v_mfma_f32_16x16x32_bf16 v[90:93], v[162:165], v[242:245], v[90:93]
	v_mfma_f32_16x16x32_bf16 v[86:89], v[170:173], v[242:245], v[86:89]
	v_mfma_f32_16x16x32_bf16 v[130:133], v[142:145], v[182:185], v[130:133]
	v_mfma_f32_16x16x32_bf16 v[126:129], v[150:153], v[182:185], v[126:129]
	v_mfma_f32_16x16x32_bf16 v[114:117], v[142:145], v[190:193], v[114:117]
	v_mfma_f32_16x16x32_bf16 v[110:113], v[150:153], v[190:193], v[110:113]
	v_mfma_f32_16x16x32_bf16 v[98:101], v[142:145], v[198:201], v[98:101]
	v_mfma_f32_16x16x32_bf16 v[94:97], v[150:153], v[198:201], v[94:97]
	v_mfma_f32_16x16x32_bf16 v[82:85], v[142:145], v[206:209], v[82:85]
	v_mfma_f32_16x16x32_bf16 v[78:81], v[150:153], v[206:209], v[78:81]
	v_mfma_f32_16x16x32_bf16 v[130:133], v[146:149], v[186:189], v[130:133]
	v_mfma_f32_16x16x32_bf16 v[126:129], v[154:157], v[186:189], v[126:129]
	v_mfma_f32_16x16x32_bf16 v[114:117], v[146:149], v[194:197], v[114:117]
	v_mfma_f32_16x16x32_bf16 v[110:113], v[154:157], v[194:197], v[110:113]
	v_mfma_f32_16x16x32_bf16 v[98:101], v[146:149], v[202:205], v[98:101]
	v_mfma_f32_16x16x32_bf16 v[94:97], v[154:157], v[202:205], v[94:97]
	v_mfma_f32_16x16x32_bf16 v[82:85], v[146:149], v[242:245], v[82:85]
	v_mfma_f32_16x16x32_bf16 v[78:81], v[154:157], v[242:245], v[78:81]
	s_and_b64 vcc, exec, s[6:7]
	s_cbranch_vccnz .LBB0_1373
	s_setprio 1
	s_and_b64 vcc, exec, s[4:5]
	s_mov_b64 s[4:5], -1
	s_cbranch_vccnz .LBB0_1370
	v_mfma_f32_16x16x32_bf16 v[10:13], v[142:145], v[174:177], v[10:13]
	s_mov_b64 s[4:5], 0
	v_mfma_f32_16x16x32_bf16 v[6:9], v[150:153], v[174:177], v[6:9]
	v_mfma_f32_16x16x32_bf16 v[10:13], v[146:149], v[178:181], v[10:13]
	v_mfma_f32_16x16x32_bf16 v[6:9], v[154:157], v[178:181], v[6:9]

; #define PG8_STAGEX(b, gbase) do { if constexpr (XR) { if (lane < 16) __builtin_amdgcn_global_load_lds((const unsigned*)((const char*)(gbase) + voffX), (PG8_LAS unsigned*)(lds + XR_OFF + (b) * 2048 + wid * 256), 16, 0, 0); } } while (0)
; #define PG8_WAIT_LOOP() do { if constexpr (XR) PG8_WAIT_V(9); else PG8_WAIT_V(8); } while (0)
; #define PG8_STAGE(bufoff, gbase, voff) do { _Pragma("unroll") for (int _i = 0; _i < 2; ++_i) \
;         __builtin_amdgcn_global_load_lds((const unsigned*)((const char*)(gbase) + (voff)[_i]), (PG8_LAS unsigned*)(lds + (bufoff) + ldsw + _i * 8192), 16, 0, 0); } while (0)
; #define PG8_LDA(dst, b, h) do { _Pragma("unroll") for (int m = 0; m < 4; ++m) _Pragma("unroll") for (int k = 0; k < 2; ++k) dst[m][k] = *(const PG8_LAS bf16x8*)(lds + PG8_SA(b, h) + aoff + m * 2048 + k * 1024); } while (0)
; #define PG8_MMA(ai, bj, At, Bt) do { __builtin_amdgcn_s_setprio(1); _Pragma("unroll") for (int m = 0; m < 4; ++m) _Pragma("unroll") for (int n = 0; n < 2; ++n) _Pragma("unroll") for (int k = 0; k < 2; ++k) \
;         acc[ai][bj][m][n] = __builtin_amdgcn_mfma_f32_16x16x32_bf16(Bt[n][k], At[m][k], acc[ai][bj][m][n], 0, 0, 0); __builtin_amdgcn_s_setprio(0); } while (0)
; #define PG8_WAIT_L(n) asm volatile("s_waitcnt lgkmcnt(" #n ")" ::: "memory")
; #define PG8_BAR __builtin_amdgcn_s_barrier()
; #define PG8_SCHED __builtin_amdgcn_sched_barrier(0)
; template <class Epi, class Sched, bool ALIGN_EPI = false, bool SP2 = false, bool DRAIN = true, bool XR = false>
; __device__ __forceinline__ void gemm_phase(PG8_LAS unsigned char* lds, const Gemm g, const Sched& S, const Epi& E) {
;     ...
;         for (int t = 0; t < nt; t += 2) {
;     ...
;             PG8_LDA(At, 1, 1); PG8_STAGE(PG8_SB(1, 0), b3, voffB); PG8_STAGE(PG8_SB(1, 1), b3 + hstep, voffB); PG8_STAGE(PG8_SA(1, 0), a3, voffA); PG8_STAGEX(1, x3);
;             PG8_WAIT_LOOP(); PG8_WAIT_L(0); PG8_BAR; PG8_MMA(1, 0, At, B0); PG8_MMA(1, 1, At, B1); PG8_BAR; PG8_SCHED;
.LBB0_1375:
	s_or_b64 exec, exec, s[4:5]
	s_waitcnt vmcnt(9)
	s_waitcnt lgkmcnt(0)
	s_barrier
	v_mfma_f32_16x16x32_bf16 v[74:77], v[158:161], v[198:201], v[74:77]
	v_mfma_f32_16x16x32_bf16 v[70:73], v[166:169], v[198:201], v[70:73]
	v_mfma_f32_16x16x32_bf16 v[58:61], v[158:161], v[190:193], v[58:61]
	v_mfma_f32_16x16x32_bf16 v[54:57], v[166:169], v[190:193], v[54:57]
	v_mfma_f32_16x16x32_bf16 v[42:45], v[158:161], v[182:185], v[42:45]
	v_mfma_f32_16x16x32_bf16 v[38:41], v[166:169], v[182:185], v[38:41]
	v_mfma_f32_16x16x32_bf16 v[26:29], v[158:161], v[174:177], v[26:29]
	v_mfma_f32_16x16x32_bf16 v[22:25], v[166:169], v[174:177], v[22:25]
	v_mfma_f32_16x16x32_bf16 v[74:77], v[162:165], v[202:205], v[74:77]
	v_mfma_f32_16x16x32_bf16 v[70:73], v[170:173], v[202:205], v[70:73]
	v_mfma_f32_16x16x32_bf16 v[58:61], v[162:165], v[194:197], v[58:61]
	v_mfma_f32_16x16x32_bf16 v[54:57], v[170:173], v[194:197], v[54:57]
	v_mfma_f32_16x16x32_bf16 v[42:45], v[162:165], v[186:189], v[42:45]
	v_mfma_f32_16x16x32_bf16 v[38:41], v[170:173], v[186:189], v[38:41]
	v_mfma_f32_16x16x32_bf16 v[26:29], v[162:165], v[178:181], v[26:29]
	v_mfma_f32_16x16x32_bf16 v[22:25], v[170:173], v[178:181], v[22:25]
	v_mfma_f32_16x16x32_bf16 v[66:69], v[142:145], v[198:201], v[66:69]
	v_mfma_f32_16x16x32_bf16 v[62:65], v[150:153], v[198:201], v[62:65]
	v_mfma_f32_16x16x32_bf16 v[50:53], v[142:145], v[190:193], v[50:53]
	v_mfma_f32_16x16x32_bf16 v[46:49], v[150:153], v[190:193], v[46:49]
	v_mfma_f32_16x16x32_bf16 v[34:37], v[142:145], v[182:185], v[34:37]
	v_mfma_f32_16x16x32_bf16 v[30:33], v[150:153], v[182:185], v[30:33]
	v_mfma_f32_16x16x32_bf16 v[18:21], v[142:145], v[174:177], v[18:21]
	v_mfma_f32_16x16x32_bf16 v[14:17], v[150:153], v[174:177], v[14:17]
	v_mfma_f32_16x16x32_bf16 v[66:69], v[146:149], v[202:205], v[66:69]
	v_mfma_f32_16x16x32_bf16 v[62:65], v[154:157], v[202:205], v[62:65]
	v_mfma_f32_16x16x32_bf16 v[50:53], v[146:149], v[194:197], v[50:53]
	v_mfma_f32_16x16x32_bf16 v[46:49], v[154:157], v[194:197], v[46:49]
	v_mfma_f32_16x16x32_bf16 v[34:37], v[146:149], v[186:189], v[34:37]
	v_mfma_f32_16x16x32_bf16 v[30:33], v[154:157], v[186:189], v[30:33]
	v_mfma_f32_16x16x32_bf16 v[18:21], v[146:149], v[178:181], v[18:21]
	v_mfma_f32_16x16x32_bf16 v[14:17], v[154:157], v[178:181], v[14:17]
	s_barrier
	s_add_i32 s4, s90, 2
	s_cmp_ge_i32 s90, s65
	s_cbranch_scc1 .LBB0_1378
	s_mov_b32 s90, s4
	s_branch .LBB0_1359

; #define PG8_STAGEX(b, gbase) do { if constexpr (XR) { if (lane < 16) __builtin_amdgcn_global_load_lds((const unsigned*)((const char*)(gbase) + voffX), (PG8_LAS unsigned*)(lds + XR_OFF + (b) * 2048 + wid * 256), 16, 0, 0); } } while (0)
; #define PG8_LDX(b) do { if constexpr (XR) { _Pragma("unroll") for (int k = 0; k < 2; ++k) Ax_[k] = *(const PG8_LAS bf16x8*)(lds + XR_OFF + (b) * 2048 + aoffx + k * 1024); } } while (0)
; #define PG8_MMAX() do { if constexpr (XR) { if (hasx) { __builtin_amdgcn_s_setprio(1); if (wr == 0) PG8_MMAX_(B0); else PG8_MMAX_(B1); __builtin_amdgcn_s_setprio(0); } } } while (0)
; #define PG8_WAIT_LOOP() do { if constexpr (XR) PG8_WAIT_V(9); else PG8_WAIT_V(8); } while (0)
; #define PG8_STAGE(bufoff, gbase, voff) do { _Pragma("unroll") for (int _i = 0; _i < 2; ++_i) \
;         __builtin_amdgcn_global_load_lds((const unsigned*)((const char*)(gbase) + (voff)[_i]), (PG8_LAS unsigned*)(lds + (bufoff) + ldsw + _i * 8192), 16, 0, 0); } while (0)
; #define PG8_BAR __builtin_amdgcn_s_barrier()
; template <class Epi, class Sched, bool ALIGN_EPI = false, bool SP2 = false, bool DRAIN = true, bool XR = false>
; __device__ __forceinline__ void gemm_phase(PG8_LAS unsigned char* lds, const Gemm g, const Sched& S, const Epi& E) {
;     ...
;             PG8_LDB(B0, 0, 0); PG8_LDB(B1, 0, 1); PG8_SCHED; PG8_LDA(At, 0, 0); PG8_LDX(0); PG8_STAGE(PG8_SA(1, 1), a1 + hstepA, voffA);
;             PG8_WAIT_LOOP(); PG8_WAIT_L(0); PG8_BAR; PG8_MMA(0, 0, At, B0); PG8_MMA(0, 1, At, B1); PG8_MMAX(); PG8_BAR; PG8_SCHED;
;             PG8_LDA(At, 0, 1); PG8_STAGE(PG8_SB(0, 0), b2, voffB); PG8_STAGE(PG8_SB(0, 1), b2 + hstep, voffB); PG8_STAGE(PG8_SA(0, 0), a2, voffA); PG8_STAGEX(0, x2);
;             PG8_WAIT_LOOP(); PG8_WAIT_L(0); PG8_BAR; PG8_MMA(1, 0, At, B0); PG8_MMA(1, 1, At, B1); PG8_BAR; PG8_SCHED;
;             PG8_LDB(B0, 1, 0); PG8_LDB(B1, 1, 1); PG8_SCHED; PG8_LDA(At, 1, 0); PG8_LDX(1); PG8_STAGE(PG8_SA(0, 1), a2 + hstepA, voffA);
;             PG8_WAIT_LOOP(); PG8_WAIT_L(0); PG8_BAR; PG8_MMA(0, 0, At, B0); PG8_MMA(0, 1, At, B1); PG8_MMAX(); PG8_BAR; PG8_SCHED;
;             PG8_LDA(At, 1, 1); PG8_STAGE(PG8_SB(1, 0), b3, voffB); PG8_STAGE(PG8_SB(1, 1), b3 + hstep, voffB); PG8_STAGE(PG8_SA(1, 0), a3, voffA); PG8_STAGEX(1, x3);
;             PG8_WAIT_LOOP(); PG8_WAIT_L(0); PG8_BAR; PG8_MMA(1, 0, At, B0); PG8_MMA(1, 1, At, B1); PG8_BAR; PG8_SCHED;
.LBB0_1500:
	s_or_b64 exec, exec, s[4:5]
	s_waitcnt vmcnt(9)
	s_waitcnt lgkmcnt(0)
	s_barrier
	v_mfma_f32_16x16x32_bf16 v[72:75], v[156:159], v[196:199], v[72:75]
	v_mfma_f32_16x16x32_bf16 v[68:71], v[164:167], v[196:199], v[68:71]
	v_mfma_f32_16x16x32_bf16 v[64:67], v[156:159], v[188:191], v[64:67]
	v_mfma_f32_16x16x32_bf16 v[60:63], v[164:167], v[188:191], v[60:63]
	v_mfma_f32_16x16x32_bf16 v[56:59], v[156:159], v[180:183], v[56:59]
	v_mfma_f32_16x16x32_bf16 v[52:55], v[164:167], v[180:183], v[52:55]
	v_mfma_f32_16x16x32_bf16 v[48:51], v[156:159], v[172:175], v[48:51]
	v_mfma_f32_16x16x32_bf16 v[44:47], v[164:167], v[172:175], v[44:47]
	v_mfma_f32_16x16x32_bf16 v[72:75], v[160:163], v[200:203], v[72:75]
	v_mfma_f32_16x16x32_bf16 v[68:71], v[168:171], v[200:203], v[68:71]
	v_mfma_f32_16x16x32_bf16 v[64:67], v[160:163], v[192:195], v[64:67]
	v_mfma_f32_16x16x32_bf16 v[60:63], v[168:171], v[192:195], v[60:63]
	v_mfma_f32_16x16x32_bf16 v[56:59], v[160:163], v[184:187], v[56:59]
	v_mfma_f32_16x16x32_bf16 v[52:55], v[168:171], v[184:187], v[52:55]
	v_mfma_f32_16x16x32_bf16 v[48:51], v[160:163], v[176:179], v[48:51]
	v_mfma_f32_16x16x32_bf16 v[44:47], v[168:171], v[176:179], v[44:47]
	v_mfma_f32_16x16x32_bf16 v[40:43], v[140:143], v[196:199], v[40:43]
	v_mfma_f32_16x16x32_bf16 v[36:39], v[148:151], v[196:199], v[36:39]
	v_mfma_f32_16x16x32_bf16 v[32:35], v[140:143], v[188:191], v[32:35]
	v_mfma_f32_16x16x32_bf16 v[28:31], v[148:151], v[188:191], v[28:31]
	v_mfma_f32_16x16x32_bf16 v[24:27], v[140:143], v[180:183], v[24:27]
	v_mfma_f32_16x16x32_bf16 v[20:23], v[148:151], v[180:183], v[20:23]
	v_mfma_f32_16x16x32_bf16 v[16:19], v[140:143], v[172:175], v[16:19]
	v_mfma_f32_16x16x32_bf16 v[12:15], v[148:151], v[172:175], v[12:15]
	v_mfma_f32_16x16x32_bf16 v[40:43], v[144:147], v[200:203], v[40:43]
	v_mfma_f32_16x16x32_bf16 v[36:39], v[152:155], v[200:203], v[36:39]
	v_mfma_f32_16x16x32_bf16 v[32:35], v[144:147], v[192:195], v[32:35]
	v_mfma_f32_16x16x32_bf16 v[28:31], v[152:155], v[192:195], v[28:31]
	v_mfma_f32_16x16x32_bf16 v[24:27], v[144:147], v[184:187], v[24:27]
	v_mfma_f32_16x16x32_bf16 v[20:23], v[152:155], v[184:187], v[20:23]
	v_mfma_f32_16x16x32_bf16 v[16:19], v[144:147], v[176:179], v[16:19]
	v_mfma_f32_16x16x32_bf16 v[12:15], v[152:155], v[176:179], v[12:15]
	s_barrier
	s_add_i32 s70, s70, 2
	s_cmp_ge_i32 s70, s14
	s_cbranch_scc1 .LBB0_1517
.LBB0_1501:
	s_add_i32 s64, s83, s70
	v_add_u32_e32 v140, 0x10000, v248
	v_add_u32_e32 v152, 0x14000, v248
	s_and_b32 s6, s64, s97
	ds_read_b128 v[156:159], v140
	ds_read_b128 v[160:163], v140 offset:1024
	ds_read_b128 v[164:167], v140 offset:2048
	ds_read_b128 v[168:171], v140 offset:3072
	ds_read_b128 v[140:143], v152
	ds_read_b128 v[144:147], v152 offset:1024
	ds_read_b128 v[148:151], v152 offset:2048
	ds_read_b128 v[152:155], v152 offset:3072
	s_lshr_b32 s84, s6, 2
	s_lshl_b32 s6, s6, 7
	s_lshl_b64 s[4:5], s[84:85], 9
	s_and_b32 s6, s6, 0x100
	s_add_u32 s4, s40, s4
	s_addc_u32 s5, s41, s5
	s_add_u32 s4, s4, s6
	s_addc_u32 s5, s5, 0
	s_add_u32 s4, s4, s28
	s_addc_u32 s5, s5, s29
	v_lshl_add_u64 v[212:213], s[4:5], 0, v[204:205]
	v_add_u32_e32 v176, 0x22400, v250
	v_lshl_add_u64 v[212:213], v[212:213], 0, s[86:87]
	s_add_i32 m0, s90, 0xc000
	ds_read_b128 v[180:183], v249
	ds_read_b128 v[184:187], v249 offset:1024
	ds_read_b128 v[188:191], v249 offset:2048
	ds_read_b128 v[192:195], v249 offset:3072
	ds_read_b128 v[196:199], v249 offset:4096
	ds_read_b128 v[200:203], v249 offset:5120
	ds_read_b128 v[206:209], v249 offset:6144
	ds_read_b128 v[222:225], v249 offset:7168
	ds_read_b128 v[172:175], v176
	ds_read_b128 v[176:179], v176 offset:1024
	global_load_lds_dwordx4 v[212:213], off
	v_lshl_add_u64 v[212:213], s[4:5], 0, v[216:217]
	v_lshl_add_u64 v[212:213], v[212:213], 0, s[86:87]
	s_add_i32 m0, s90, 0xe000
	s_nop 0
	global_load_lds_dwordx4 v[212:213], off
	s_waitcnt vmcnt(9)
	s_waitcnt lgkmcnt(0)
	s_barrier
	v_mfma_f32_16x16x32_bf16 v[136:139], v[156:159], v[180:183], v[136:139]
	v_mfma_f32_16x16x32_bf16 v[132:135], v[164:167], v[180:183], v[132:135]
	v_mfma_f32_16x16x32_bf16 v[128:131], v[156:159], v[188:191], v[128:131]
	v_mfma_f32_16x16x32_bf16 v[124:127], v[164:167], v[188:191], v[124:127]
	v_mfma_f32_16x16x32_bf16 v[120:123], v[156:159], v[196:199], v[120:123]
	v_mfma_f32_16x16x32_bf16 v[116:119], v[164:167], v[196:199], v[116:119]
	v_mfma_f32_16x16x32_bf16 v[112:115], v[156:159], v[206:209], v[112:115]
	v_mfma_f32_16x16x32_bf16 v[108:111], v[164:167], v[206:209], v[108:111]
	v_mfma_f32_16x16x32_bf16 v[136:139], v[160:163], v[184:187], v[136:139]
	v_mfma_f32_16x16x32_bf16 v[132:135], v[168:171], v[184:187], v[132:135]
	v_mfma_f32_16x16x32_bf16 v[128:131], v[160:163], v[192:195], v[128:131]
	v_mfma_f32_16x16x32_bf16 v[124:127], v[168:171], v[192:195], v[124:127]
	v_mfma_f32_16x16x32_bf16 v[120:123], v[160:163], v[200:203], v[120:123]
	v_mfma_f32_16x16x32_bf16 v[116:119], v[168:171], v[200:203], v[116:119]
	v_mfma_f32_16x16x32_bf16 v[112:115], v[160:163], v[222:225], v[112:115]
	v_mfma_f32_16x16x32_bf16 v[108:111], v[168:171], v[222:225], v[108:111]
	v_mfma_f32_16x16x32_bf16 v[104:107], v[140:143], v[180:183], v[104:107]
	v_mfma_f32_16x16x32_bf16 v[100:103], v[148:151], v[180:183], v[100:103]
	v_mfma_f32_16x16x32_bf16 v[96:99], v[140:143], v[188:191], v[96:99]
	v_mfma_f32_16x16x32_bf16 v[92:95], v[148:151], v[188:191], v[92:95]
	v_mfma_f32_16x16x32_bf16 v[88:91], v[140:143], v[196:199], v[88:91]
	v_mfma_f32_16x16x32_bf16 v[84:87], v[148:151], v[196:199], v[84:87]
	v_mfma_f32_16x16x32_bf16 v[80:83], v[140:143], v[206:209], v[80:83]
	v_mfma_f32_16x16x32_bf16 v[76:79], v[148:151], v[206:209], v[76:79]
	v_mfma_f32_16x16x32_bf16 v[104:107], v[144:147], v[184:187], v[104:107]
	v_mfma_f32_16x16x32_bf16 v[100:103], v[152:155], v[184:187], v[100:103]
	v_mfma_f32_16x16x32_bf16 v[96:99], v[144:147], v[192:195], v[96:99]
	v_mfma_f32_16x16x32_bf16 v[92:95], v[152:155], v[192:195], v[92:95]
	v_mfma_f32_16x16x32_bf16 v[88:91], v[144:147], v[200:203], v[88:91]
	v_mfma_f32_16x16x32_bf16 v[84:87], v[152:155], v[200:203], v[84:87]
	v_mfma_f32_16x16x32_bf16 v[80:83], v[144:147], v[222:225], v[80:83]
	v_mfma_f32_16x16x32_bf16 v[76:79], v[152:155], v[222:225], v[76:79]
	v_cndmask_b32_e64 v180, 0, 1, s[46:47]
	v_cmp_ne_u32_e64 s[6:7], 1, v180
	v_cndmask_b32_e64 v180, 0, 1, s[52:53]
	s_andn2_b64 vcc, exec, s[46:47]
	v_cmp_ne_u32_e64 s[4:5], 1, v180
	s_cbranch_vccnz .LBB0_1507
	s_setprio 1
	s_and_b64 vcc, exec, s[4:5]
	s_mov_b64 s[62:63], -1
	s_cbranch_vccnz .LBB0_1504
	v_mfma_f32_16x16x32_bf16 v[8:11], v[140:143], v[172:175], v[8:11]
	s_mov_b64 s[62:63], 0
	v_mfma_f32_16x16x32_bf16 v[4:7], v[148:151], v[172:175], v[4:7]
	v_mfma_f32_16x16x32_bf16 v[8:11], v[144:147], v[176:179], v[8:11]
	v_mfma_f32_16x16x32_bf16 v[4:7], v[152:155], v[176:179], v[4:7]

; #define PG8_STAGEX(b, gbase) do { if constexpr (XR) { if (lane < 16) __builtin_amdgcn_global_load_lds((const unsigned*)((const char*)(gbase) + voffX), (PG8_LAS unsigned*)(lds + XR_OFF + (b) * 2048 + wid * 256), 16, 0, 0); } } while (0)
; #define PG8_LDX(b) do { if constexpr (XR) { _Pragma("unroll") for (int k = 0; k < 2; ++k) Ax_[k] = *(const PG8_LAS bf16x8*)(lds + XR_OFF + (b) * 2048 + aoffx + k * 1024); } } while (0)
; #define PG8_MMAX() do { if constexpr (XR) { if (hasx) { __builtin_amdgcn_s_setprio(1); if (wr == 0) PG8_MMAX_(B0); else PG8_MMAX_(B1); __builtin_amdgcn_s_setprio(0); } } } while (0)
; #define PG8_WAIT_LOOP() do { if constexpr (XR) PG8_WAIT_V(9); else PG8_WAIT_V(8); } while (0)
; #define PG8_STAGE(bufoff, gbase, voff) do { _Pragma("unroll") for (int _i = 0; _i < 2; ++_i) \
;         __builtin_amdgcn_global_load_lds((const unsigned*)((const char*)(gbase) + (voff)[_i]), (PG8_LAS unsigned*)(lds + (bufoff) + ldsw + _i * 8192), 16, 0, 0); } while (0)
; #define PG8_BAR __builtin_amdgcn_s_barrier()
; template <class Epi, class Sched, bool ALIGN_EPI = false, bool SP2 = false, bool DRAIN = true, bool XR = false>
; __device__ __forceinline__ void gemm_phase(PG8_LAS unsigned char* lds, const Gemm g, const Sched& S, const Epi& E) {
;     ...
;             PG8_LDB(B0, 0, 0); PG8_LDB(B1, 0, 1); PG8_SCHED; PG8_LDA(At, 0, 0); PG8_LDX(0); PG8_STAGE(PG8_SA(1, 1), a1 + hstepA, voffA);
;             PG8_WAIT_LOOP(); PG8_WAIT_L(0); PG8_BAR; PG8_MMA(0, 0, At, B0); PG8_MMA(0, 1, At, B1); PG8_MMAX(); PG8_BAR; PG8_SCHED;
;             PG8_LDA(At, 0, 1); PG8_STAGE(PG8_SB(0, 0), b2, voffB); PG8_STAGE(PG8_SB(0, 1), b2 + hstep, voffB); PG8_STAGE(PG8_SA(0, 0), a2, voffA); PG8_STAGEX(0, x2);
;             PG8_WAIT_LOOP(); PG8_WAIT_L(0); PG8_BAR; PG8_MMA(1, 0, At, B0); PG8_MMA(1, 1, At, B1); PG8_BAR; PG8_SCHED;
;             PG8_LDB(B0, 1, 0); PG8_LDB(B1, 1, 1); PG8_SCHED; PG8_LDA(At, 1, 0); PG8_LDX(1); PG8_STAGE(PG8_SA(0, 1), a2 + hstepA, voffA);
;             PG8_WAIT_LOOP(); PG8_WAIT_L(0); PG8_BAR; PG8_MMA(0, 0, At, B0); PG8_MMA(0, 1, At, B1); PG8_MMAX(); PG8_BAR; PG8_SCHED;
;             PG8_LDA(At, 1, 1); PG8_STAGE(PG8_SB(1, 0), b3, voffB); PG8_STAGE(PG8_SB(1, 1), b3 + hstep, voffB); PG8_STAGE(PG8_SA(1, 0), a3, voffA); PG8_STAGEX(1, x3);
;             PG8_WAIT_LOOP(); PG8_WAIT_L(0); PG8_BAR; PG8_MMA(1, 0, At, B0); PG8_MMA(1, 1, At, B1); PG8_BAR; PG8_SCHED;
.LBB0_1509:
	s_or_b64 exec, exec, s[64:65]
	s_waitcnt vmcnt(9)
	s_waitcnt lgkmcnt(0)
	s_barrier
	v_mfma_f32_16x16x32_bf16 v[72:75], v[156:159], v[196:199], v[72:75]
	v_mfma_f32_16x16x32_bf16 v[68:71], v[164:167], v[196:199], v[68:71]
	v_mfma_f32_16x16x32_bf16 v[64:67], v[156:159], v[188:191], v[64:67]
	v_mfma_f32_16x16x32_bf16 v[60:63], v[164:167], v[188:191], v[60:63]
	v_mfma_f32_16x16x32_bf16 v[56:59], v[156:159], v[180:183], v[56:59]
	v_mfma_f32_16x16x32_bf16 v[52:55], v[164:167], v[180:183], v[52:55]
	v_mfma_f32_16x16x32_bf16 v[48:51], v[156:159], v[172:175], v[48:51]
	v_mfma_f32_16x16x32_bf16 v[44:47], v[164:167], v[172:175], v[44:47]
	v_mfma_f32_16x16x32_bf16 v[72:75], v[160:163], v[200:203], v[72:75]
	v_mfma_f32_16x16x32_bf16 v[68:71], v[168:171], v[200:203], v[68:71]
	v_mfma_f32_16x16x32_bf16 v[64:67], v[160:163], v[192:195], v[64:67]
	v_mfma_f32_16x16x32_bf16 v[60:63], v[168:171], v[192:195], v[60:63]
	v_mfma_f32_16x16x32_bf16 v[56:59], v[160:163], v[184:187], v[56:59]
	v_mfma_f32_16x16x32_bf16 v[52:55], v[168:171], v[184:187], v[52:55]
	v_mfma_f32_16x16x32_bf16 v[48:51], v[160:163], v[176:179], v[48:51]
	v_mfma_f32_16x16x32_bf16 v[44:47], v[168:171], v[176:179], v[44:47]
	v_mfma_f32_16x16x32_bf16 v[40:43], v[140:143], v[196:199], v[40:43]
	v_mfma_f32_16x16x32_bf16 v[36:39], v[148:151], v[196:199], v[36:39]
	v_mfma_f32_16x16x32_bf16 v[32:35], v[140:143], v[188:191], v[32:35]
	v_mfma_f32_16x16x32_bf16 v[28:31], v[148:151], v[188:191], v[28:31]
	v_mfma_f32_16x16x32_bf16 v[24:27], v[140:143], v[180:183], v[24:27]
	v_mfma_f32_16x16x32_bf16 v[20:23], v[148:151], v[180:183], v[20:23]
	v_mfma_f32_16x16x32_bf16 v[16:19], v[140:143], v[172:175], v[16:19]
	v_mfma_f32_16x16x32_bf16 v[12:15], v[148:151], v[172:175], v[12:15]
	v_mfma_f32_16x16x32_bf16 v[40:43], v[144:147], v[200:203], v[40:43]
	v_mfma_f32_16x16x32_bf16 v[36:39], v[152:155], v[200:203], v[36:39]
	v_mfma_f32_16x16x32_bf16 v[32:35], v[144:147], v[192:195], v[32:35]
	v_mfma_f32_16x16x32_bf16 v[28:31], v[152:155], v[192:195], v[28:31]
	v_mfma_f32_16x16x32_bf16 v[24:27], v[144:147], v[184:187], v[24:27]
	v_mfma_f32_16x16x32_bf16 v[20:23], v[152:155], v[184:187], v[20:23]
	v_mfma_f32_16x16x32_bf16 v[16:19], v[144:147], v[176:179], v[16:19]
	v_mfma_f32_16x16x32_bf16 v[12:15], v[152:155], v[176:179], v[12:15]
	s_barrier
	v_add_u32_e32 v140, 0x18000, v248
	v_add_u32_e32 v152, 0x1c000, v248
	ds_read_b128 v[156:159], v140
	ds_read_b128 v[160:163], v140 offset:1024
	ds_read_b128 v[164:167], v140 offset:2048
	ds_read_b128 v[168:171], v140 offset:3072
	ds_read_b128 v[140:143], v152
	ds_read_b128 v[144:147], v152 offset:1024
	ds_read_b128 v[148:151], v152 offset:2048
	ds_read_b128 v[152:155], v152 offset:3072
	s_add_u32 s62, s62, s28
	s_addc_u32 s63, s63, s29
	s_mov_b32 m0, s12
	v_add_u32_e32 v176, 0x22c00, v250
	ds_read_b128 v[180:183], v249 offset:32768
	ds_read_b128 v[184:187], v249 offset:33792
	ds_read_b128 v[188:191], v249 offset:34816
	ds_read_b128 v[192:195], v249 offset:35840
	ds_read_b128 v[196:199], v249 offset:36864
	ds_read_b128 v[200:203], v249 offset:37888
	ds_read_b128 v[206:209], v249 offset:38912
	ds_read_b128 v[242:245], v249 offset:39936
	ds_read_b128 v[172:175], v176
	ds_read_b128 v[176:179], v176 offset:1024
	global_load_lds_dwordx4 v204, s[62:63]
	s_mov_b32 m0, s13
	s_nop 0
	global_load_lds_dwordx4 v216, s[62:63]
	s_waitcnt vmcnt(9)
	s_waitcnt lgkmcnt(0)
	s_barrier
	v_mfma_f32_16x16x32_bf16 v[136:139], v[156:159], v[180:183], v[136:139]
	v_mfma_f32_16x16x32_bf16 v[132:135], v[164:167], v[180:183], v[132:135]
	v_mfma_f32_16x16x32_bf16 v[128:131], v[156:159], v[188:191], v[128:131]
	v_mfma_f32_16x16x32_bf16 v[124:127], v[164:167], v[188:191], v[124:127]
	v_mfma_f32_16x16x32_bf16 v[120:123], v[156:159], v[196:199], v[120:123]
	v_mfma_f32_16x16x32_bf16 v[116:119], v[164:167], v[196:199], v[116:119]
	v_mfma_f32_16x16x32_bf16 v[112:115], v[156:159], v[206:209], v[112:115]
	v_mfma_f32_16x16x32_bf16 v[108:111], v[164:167], v[206:209], v[108:111]
	v_mfma_f32_16x16x32_bf16 v[136:139], v[160:163], v[184:187], v[136:139]
	v_mfma_f32_16x16x32_bf16 v[132:135], v[168:171], v[184:187], v[132:135]
	v_mfma_f32_16x16x32_bf16 v[128:131], v[160:163], v[192:195], v[128:131]
	v_mfma_f32_16x16x32_bf16 v[124:127], v[168:171], v[192:195], v[124:127]
	v_mfma_f32_16x16x32_bf16 v[120:123], v[160:163], v[200:203], v[120:123]
	v_mfma_f32_16x16x32_bf16 v[116:119], v[168:171], v[200:203], v[116:119]
	v_mfma_f32_16x16x32_bf16 v[112:115], v[160:163], v[242:245], v[112:115]
	v_mfma_f32_16x16x32_bf16 v[108:111], v[168:171], v[242:245], v[108:111]
	v_mfma_f32_16x16x32_bf16 v[104:107], v[140:143], v[180:183], v[104:107]
	v_mfma_f32_16x16x32_bf16 v[100:103], v[148:151], v[180:183], v[100:103]
	v_mfma_f32_16x16x32_bf16 v[96:99], v[140:143], v[188:191], v[96:99]
	v_mfma_f32_16x16x32_bf16 v[92:95], v[148:151], v[188:191], v[92:95]
	v_mfma_f32_16x16x32_bf16 v[88:91], v[140:143], v[196:199], v[88:91]
	v_mfma_f32_16x16x32_bf16 v[84:87], v[148:151], v[196:199], v[84:87]
	v_mfma_f32_16x16x32_bf16 v[80:83], v[140:143], v[206:209], v[80:83]
	v_mfma_f32_16x16x32_bf16 v[76:79], v[148:151], v[206:209], v[76:79]
	v_mfma_f32_16x16x32_bf16 v[104:107], v[144:147], v[184:187], v[104:107]
	v_mfma_f32_16x16x32_bf16 v[100:103], v[152:155], v[184:187], v[100:103]
	v_mfma_f32_16x16x32_bf16 v[96:99], v[144:147], v[192:195], v[96:99]
	v_mfma_f32_16x16x32_bf16 v[92:95], v[152:155], v[192:195], v[92:95]
	v_mfma_f32_16x16x32_bf16 v[88:91], v[144:147], v[200:203], v[88:91]
	v_mfma_f32_16x16x32_bf16 v[84:87], v[152:155], v[200:203], v[84:87]
	v_mfma_f32_16x16x32_bf16 v[80:83], v[144:147], v[242:245], v[80:83]
	v_mfma_f32_16x16x32_bf16 v[76:79], v[152:155], v[242:245], v[76:79]
	s_and_b64 vcc, exec, s[6:7]
	s_cbranch_vccnz .LBB0_1515
	s_setprio 1
	s_and_b64 vcc, exec, s[4:5]
	s_mov_b64 s[4:5], -1
	s_cbranch_vccnz .LBB0_1512
	v_mfma_f32_16x16x32_bf16 v[8:11], v[140:143], v[172:175], v[8:11]
	s_mov_b64 s[4:5], 0
	v_mfma_f32_16x16x32_bf16 v[4:7], v[148:151], v[172:175], v[4:7]
	v_mfma_f32_16x16x32_bf16 v[8:11], v[144:147], v[176:179], v[8:11]
	v_mfma_f32_16x16x32_bf16 v[4:7], v[152:155], v[176:179], v[4:7]

; #define PG8_STAGEX(b, gbase) do { if constexpr (XR) { if (lane < 16) __builtin_amdgcn_global_load_lds((const unsigned*)((const char*)(gbase) + voffX), (PG8_LAS unsigned*)(lds + XR_OFF + (b) * 2048 + wid * 256), 16, 0, 0); } } while (0)
; #define PG8_LDX(b) do { if constexpr (XR) { _Pragma("unroll") for (int k = 0; k < 2; ++k) Ax_[k] = *(const PG8_LAS bf16x8*)(lds + XR_OFF + (b) * 2048 + aoffx + k * 1024); } } while (0)
; #define PG8_MMAX() do { if constexpr (XR) { if (hasx) { __builtin_amdgcn_s_setprio(1); if (wr == 0) PG8_MMAX_(B0); else PG8_MMAX_(B1); __builtin_amdgcn_s_setprio(0); } } } while (0)
; #define PG8_WAIT_LOOP() do { if constexpr (XR) PG8_WAIT_V(9); else PG8_WAIT_V(8); } while (0)
; #define PG8_STAGE(bufoff, gbase, voff) do { _Pragma("unroll") for (int _i = 0; _i < 2; ++_i) \
;         __builtin_amdgcn_global_load_lds((const unsigned*)((const char*)(gbase) + (voff)[_i]), (PG8_LAS unsigned*)(lds + (bufoff) + ldsw + _i * 8192), 16, 0, 0); } while (0)
; #define PG8_BAR __builtin_amdgcn_s_barrier()
; template <class Epi, class Sched, bool ALIGN_EPI = false, bool SP2 = false, bool DRAIN = true, bool XR = false>
; __device__ __forceinline__ void gemm_phase(PG8_LAS unsigned char* lds, const Gemm g, const Sched& S, const Epi& E) {
;     ...
;             PG8_LDB(B0, 0, 0); PG8_LDB(B1, 0, 1); PG8_SCHED; PG8_LDA(At, 0, 0); PG8_LDX(0); PG8_STAGE(PG8_SA(1, 1), a1 + hstepA, voffA);
;             PG8_WAIT_LOOP(); PG8_WAIT_L(0); PG8_BAR; PG8_MMA(0, 0, At, B0); PG8_MMA(0, 1, At, B1); PG8_MMAX(); PG8_BAR; PG8_SCHED;
;             PG8_LDA(At, 0, 1); PG8_STAGE(PG8_SB(0, 0), b2, voffB); PG8_STAGE(PG8_SB(0, 1), b2 + hstep, voffB); PG8_STAGE(PG8_SA(0, 0), a2, voffA); PG8_STAGEX(0, x2);
;             PG8_WAIT_LOOP(); PG8_WAIT_L(0); PG8_BAR; PG8_MMA(1, 0, At, B0); PG8_MMA(1, 1, At, B1); PG8_BAR; PG8_SCHED;
;             PG8_LDB(B0, 1, 0); PG8_LDB(B1, 1, 1); PG8_SCHED; PG8_LDA(At, 1, 0); PG8_LDX(1); PG8_STAGE(PG8_SA(0, 1), a2 + hstepA, voffA);
;             PG8_WAIT_LOOP(); PG8_WAIT_L(0); PG8_BAR; PG8_MMA(0, 0, At, B0); PG8_MMA(0, 1, At, B1); PG8_MMAX(); PG8_BAR; PG8_SCHED;
;             PG8_LDA(At, 1, 1); PG8_STAGE(PG8_SB(1, 0), b3, voffB); PG8_STAGE(PG8_SB(1, 1), b3 + hstep, voffB); PG8_STAGE(PG8_SA(1, 0), a3, voffA); PG8_STAGEX(1, x3);
;             PG8_WAIT_LOOP(); PG8_WAIT_L(0); PG8_BAR; PG8_MMA(1, 0, At, B0); PG8_MMA(1, 1, At, B1); PG8_BAR; PG8_SCHED;
.LBB0_1651:
	s_or_b64 exec, exec, s[0:1]
	s_waitcnt vmcnt(9)
	s_waitcnt lgkmcnt(0)
	s_barrier
	v_mfma_f32_16x16x32_bf16 v[74:77], v[158:161], v[198:201], v[74:77]
	v_mfma_f32_16x16x32_bf16 v[70:73], v[166:169], v[198:201], v[70:73]
	v_mfma_f32_16x16x32_bf16 v[58:61], v[158:161], v[190:193], v[58:61]
	v_mfma_f32_16x16x32_bf16 v[54:57], v[166:169], v[190:193], v[54:57]
	v_mfma_f32_16x16x32_bf16 v[42:45], v[158:161], v[182:185], v[42:45]
	v_mfma_f32_16x16x32_bf16 v[38:41], v[166:169], v[182:185], v[38:41]
	v_mfma_f32_16x16x32_bf16 v[26:29], v[158:161], v[174:177], v[26:29]
	v_mfma_f32_16x16x32_bf16 v[22:25], v[166:169], v[174:177], v[22:25]
	v_mfma_f32_16x16x32_bf16 v[74:77], v[162:165], v[202:205], v[74:77]
	v_mfma_f32_16x16x32_bf16 v[70:73], v[170:173], v[202:205], v[70:73]
	v_mfma_f32_16x16x32_bf16 v[58:61], v[162:165], v[194:197], v[58:61]
	v_mfma_f32_16x16x32_bf16 v[54:57], v[170:173], v[194:197], v[54:57]
	v_mfma_f32_16x16x32_bf16 v[42:45], v[162:165], v[186:189], v[42:45]
	v_mfma_f32_16x16x32_bf16 v[38:41], v[170:173], v[186:189], v[38:41]
	v_mfma_f32_16x16x32_bf16 v[26:29], v[162:165], v[178:181], v[26:29]
	v_mfma_f32_16x16x32_bf16 v[22:25], v[170:173], v[178:181], v[22:25]
	v_mfma_f32_16x16x32_bf16 v[66:69], v[142:145], v[198:201], v[66:69]
	v_mfma_f32_16x16x32_bf16 v[62:65], v[150:153], v[198:201], v[62:65]
	v_mfma_f32_16x16x32_bf16 v[50:53], v[142:145], v[190:193], v[50:53]
	v_mfma_f32_16x16x32_bf16 v[46:49], v[150:153], v[190:193], v[46:49]
	v_mfma_f32_16x16x32_bf16 v[34:37], v[142:145], v[182:185], v[34:37]
	v_mfma_f32_16x16x32_bf16 v[30:33], v[150:153], v[182:185], v[30:33]
	v_mfma_f32_16x16x32_bf16 v[18:21], v[142:145], v[174:177], v[18:21]
	v_mfma_f32_16x16x32_bf16 v[14:17], v[150:153], v[174:177], v[14:17]
	v_mfma_f32_16x16x32_bf16 v[66:69], v[146:149], v[202:205], v[66:69]
	v_mfma_f32_16x16x32_bf16 v[62:65], v[154:157], v[202:205], v[62:65]
	v_mfma_f32_16x16x32_bf16 v[50:53], v[146:149], v[194:197], v[50:53]
	v_mfma_f32_16x16x32_bf16 v[46:49], v[154:157], v[194:197], v[46:49]
	v_mfma_f32_16x16x32_bf16 v[34:37], v[146:149], v[186:189], v[34:37]
	v_mfma_f32_16x16x32_bf16 v[30:33], v[154:157], v[186:189], v[30:33]
	v_mfma_f32_16x16x32_bf16 v[18:21], v[146:149], v[178:181], v[18:21]
	v_mfma_f32_16x16x32_bf16 v[14:17], v[154:157], v[178:181], v[14:17]
	s_barrier
	s_add_i32 s89, s89, 2
	s_cmp_ge_i32 s89, s58
	s_cbranch_scc1 .LBB0_1669
.LBB0_1652:
	v_add_u32_e32 v2, 0x10000, v248
	s_add_i32 s46, s54, s89
	ds_read_b128 v[158:161], v2
	ds_read_b128 v[162:165], v2 offset:1024
	ds_read_b128 v[166:169], v2 offset:2048
	ds_read_b128 v[170:173], v2 offset:3072
	v_add_u32_e32 v2, 0x14000, v248
	s_and_b32 s6, s46, s59
	ds_read_b128 v[142:145], v2
	ds_read_b128 v[146:149], v2 offset:1024
	ds_read_b128 v[150:153], v2 offset:2048
	ds_read_b128 v[154:157], v2 offset:3072
	s_lshr_b32 s84, s6, 2
	s_lshl_b32 s6, s6, 7
	s_lshl_b64 s[0:1], s[84:85], 17
	s_and_b32 s6, s6, 0x100
	s_add_u32 s0, s40, s0
	s_addc_u32 s1, s41, s1
	s_add_u32 s0, s0, s6
	s_addc_u32 s1, s1, 0
	s_add_u32 s0, s0, 0x10080
	s_addc_u32 s1, s1, 0
	v_add_u32_e32 v2, 0x22400, v250
	s_add_i32 m0, s63, 0xc000
	ds_read_b128 v[182:185], v249
	ds_read_b128 v[186:189], v249 offset:1024
	ds_read_b128 v[190:193], v249 offset:2048
	ds_read_b128 v[194:197], v249 offset:3072
	ds_read_b128 v[198:201], v249 offset:4096
	ds_read_b128 v[202:205], v249 offset:5120
	ds_read_b128 v[206:209], v249 offset:6144
	ds_read_b128 v[224:227], v249 offset:7168
	ds_read_b128 v[174:177], v2
	ds_read_b128 v[178:181], v2 offset:1024
	global_load_lds_dwordx4 v214, s[0:1]
	s_add_i32 m0, s63, 0xe000
	s_nop 0
	global_load_lds_dwordx4 v218, s[0:1]
	s_waitcnt vmcnt(9)
	s_waitcnt lgkmcnt(0)
	s_barrier
	v_mfma_f32_16x16x32_bf16 v[138:141], v[158:161], v[182:185], v[138:141]
	v_mfma_f32_16x16x32_bf16 v[134:137], v[166:169], v[182:185], v[134:137]
	v_mfma_f32_16x16x32_bf16 v[122:125], v[158:161], v[190:193], v[122:125]
	v_mfma_f32_16x16x32_bf16 v[118:121], v[166:169], v[190:193], v[118:121]
	v_mfma_f32_16x16x32_bf16 v[106:109], v[158:161], v[198:201], v[106:109]
	v_mfma_f32_16x16x32_bf16 v[102:105], v[166:169], v[198:201], v[102:105]
	v_mfma_f32_16x16x32_bf16 v[90:93], v[158:161], v[206:209], v[90:93]
	v_mfma_f32_16x16x32_bf16 v[86:89], v[166:169], v[206:209], v[86:89]
	v_mfma_f32_16x16x32_bf16 v[138:141], v[162:165], v[186:189], v[138:141]
	v_mfma_f32_16x16x32_bf16 v[134:137], v[170:173], v[186:189], v[134:137]
	v_mfma_f32_16x16x32_bf16 v[122:125], v[162:165], v[194:197], v[122:125]
	v_mfma_f32_16x16x32_bf16 v[118:121], v[170:173], v[194:197], v[118:121]
	v_mfma_f32_16x16x32_bf16 v[106:109], v[162:165], v[202:205], v[106:109]
	v_mfma_f32_16x16x32_bf16 v[102:105], v[170:173], v[202:205], v[102:105]
	v_mfma_f32_16x16x32_bf16 v[90:93], v[162:165], v[224:227], v[90:93]
	v_mfma_f32_16x16x32_bf16 v[86:89], v[170:173], v[224:227], v[86:89]
	v_mfma_f32_16x16x32_bf16 v[130:133], v[142:145], v[182:185], v[130:133]
	v_mfma_f32_16x16x32_bf16 v[126:129], v[150:153], v[182:185], v[126:129]
	v_mfma_f32_16x16x32_bf16 v[114:117], v[142:145], v[190:193], v[114:117]
	v_mfma_f32_16x16x32_bf16 v[110:113], v[150:153], v[190:193], v[110:113]
	v_mfma_f32_16x16x32_bf16 v[98:101], v[142:145], v[198:201], v[98:101]
	v_mfma_f32_16x16x32_bf16 v[94:97], v[150:153], v[198:201], v[94:97]
	v_mfma_f32_16x16x32_bf16 v[82:85], v[142:145], v[206:209], v[82:85]
	v_mfma_f32_16x16x32_bf16 v[78:81], v[150:153], v[206:209], v[78:81]
	v_mfma_f32_16x16x32_bf16 v[130:133], v[146:149], v[186:189], v[130:133]
	v_mfma_f32_16x16x32_bf16 v[126:129], v[154:157], v[186:189], v[126:129]
	v_mfma_f32_16x16x32_bf16 v[114:117], v[146:149], v[194:197], v[114:117]
	v_mfma_f32_16x16x32_bf16 v[110:113], v[154:157], v[194:197], v[110:113]
	v_mfma_f32_16x16x32_bf16 v[98:101], v[146:149], v[202:205], v[98:101]
	v_mfma_f32_16x16x32_bf16 v[94:97], v[154:157], v[202:205], v[94:97]
	v_mfma_f32_16x16x32_bf16 v[82:85], v[146:149], v[224:227], v[82:85]
	v_mfma_f32_16x16x32_bf16 v[78:81], v[154:157], v[224:227], v[78:81]
	v_cndmask_b32_e64 v2, 0, 1, s[30:31]
	v_cmp_ne_u32_e64 s[6:7], 1, v2
	v_cndmask_b32_e64 v2, 0, 1, s[22:23]
	s_andn2_b64 vcc, exec, s[30:31]
	v_cmp_ne_u32_e64 s[0:1], 1, v2
	s_cbranch_vccnz .LBB0_1658
	s_setprio 1
	s_and_b64 vcc, exec, s[0:1]
	s_mov_b64 s[44:45], -1
	s_cbranch_vccnz .LBB0_1655
	v_mfma_f32_16x16x32_bf16 v[10:13], v[142:145], v[174:177], v[10:13]
	s_mov_b64 s[44:45], 0
	v_mfma_f32_16x16x32_bf16 v[6:9], v[150:153], v[174:177], v[6:9]
	v_mfma_f32_16x16x32_bf16 v[10:13], v[146:149], v[178:181], v[10:13]
	v_mfma_f32_16x16x32_bf16 v[6:9], v[154:157], v[178:181], v[6:9]

; #define PG8_STAGEX(b, gbase) do { if constexpr (XR) { if (lane < 16) __builtin_amdgcn_global_load_lds((const unsigned*)((const char*)(gbase) + voffX), (PG8_LAS unsigned*)(lds + XR_OFF + (b) * 2048 + wid * 256), 16, 0, 0); } } while (0)
; #define PG8_LDX(b) do { if constexpr (XR) { _Pragma("unroll") for (int k = 0; k < 2; ++k) Ax_[k] = *(const PG8_LAS bf16x8*)(lds + XR_OFF + (b) * 2048 + aoffx + k * 1024); } } while (0)
; #define PG8_MMAX() do { if constexpr (XR) { if (hasx) { __builtin_amdgcn_s_setprio(1); if (wr == 0) PG8_MMAX_(B0); else PG8_MMAX_(B1); __builtin_amdgcn_s_setprio(0); } } } while (0)
; #define PG8_WAIT_LOOP() do { if constexpr (XR) PG8_WAIT_V(9); else PG8_WAIT_V(8); } while (0)
; #define PG8_STAGE(bufoff, gbase, voff) do { _Pragma("unroll") for (int _i = 0; _i < 2; ++_i) \
;         __builtin_amdgcn_global_load_lds((const unsigned*)((const char*)(gbase) + (voff)[_i]), (PG8_LAS unsigned*)(lds + (bufoff) + ldsw + _i * 8192), 16, 0, 0); } while (0)
; #define PG8_BAR __builtin_amdgcn_s_barrier()
; template <class Epi, class Sched, bool ALIGN_EPI = false, bool SP2 = false, bool DRAIN = true, bool XR = false>
; __device__ __forceinline__ void gemm_phase(PG8_LAS unsigned char* lds, const Gemm g, const Sched& S, const Epi& E) {
;     ...
;             PG8_LDB(B0, 0, 0); PG8_LDB(B1, 0, 1); PG8_SCHED; PG8_LDA(At, 0, 0); PG8_LDX(0); PG8_STAGE(PG8_SA(1, 1), a1 + hstepA, voffA);
;             PG8_WAIT_LOOP(); PG8_WAIT_L(0); PG8_BAR; PG8_MMA(0, 0, At, B0); PG8_MMA(0, 1, At, B1); PG8_MMAX(); PG8_BAR; PG8_SCHED;
;             PG8_LDA(At, 0, 1); PG8_STAGE(PG8_SB(0, 0), b2, voffB); PG8_STAGE(PG8_SB(0, 1), b2 + hstep, voffB); PG8_STAGE(PG8_SA(0, 0), a2, voffA); PG8_STAGEX(0, x2);
;             PG8_WAIT_LOOP(); PG8_WAIT_L(0); PG8_BAR; PG8_MMA(1, 0, At, B0); PG8_MMA(1, 1, At, B1); PG8_BAR; PG8_SCHED;
;             PG8_LDB(B0, 1, 0); PG8_LDB(B1, 1, 1); PG8_SCHED; PG8_LDA(At, 1, 0); PG8_LDX(1); PG8_STAGE(PG8_SA(0, 1), a2 + hstepA, voffA);
;             PG8_WAIT_LOOP(); PG8_WAIT_L(0); PG8_BAR; PG8_MMA(0, 0, At, B0); PG8_MMA(0, 1, At, B1); PG8_MMAX(); PG8_BAR; PG8_SCHED;
;             PG8_LDA(At, 1, 1); PG8_STAGE(PG8_SB(1, 0), b3, voffB); PG8_STAGE(PG8_SB(1, 1), b3 + hstep, voffB); PG8_STAGE(PG8_SA(1, 0), a3, voffA); PG8_STAGEX(1, x3);
;             PG8_WAIT_LOOP(); PG8_WAIT_L(0); PG8_BAR; PG8_MMA(1, 0, At, B0); PG8_MMA(1, 1, At, B1); PG8_BAR; PG8_SCHED;
.LBB0_1660:
	s_or_b64 exec, exec, s[46:47]
	s_waitcnt vmcnt(9)
	s_waitcnt lgkmcnt(0)
	s_barrier
	v_mfma_f32_16x16x32_bf16 v[74:77], v[158:161], v[198:201], v[74:77]
	v_mfma_f32_16x16x32_bf16 v[70:73], v[166:169], v[198:201], v[70:73]
	v_mfma_f32_16x16x32_bf16 v[58:61], v[158:161], v[190:193], v[58:61]
	v_mfma_f32_16x16x32_bf16 v[54:57], v[166:169], v[190:193], v[54:57]
	v_mfma_f32_16x16x32_bf16 v[42:45], v[158:161], v[182:185], v[42:45]
	v_mfma_f32_16x16x32_bf16 v[38:41], v[166:169], v[182:185], v[38:41]
	v_mfma_f32_16x16x32_bf16 v[26:29], v[158:161], v[174:177], v[26:29]
	v_mfma_f32_16x16x32_bf16 v[22:25], v[166:169], v[174:177], v[22:25]
	v_mfma_f32_16x16x32_bf16 v[74:77], v[162:165], v[202:205], v[74:77]
	v_mfma_f32_16x16x32_bf16 v[70:73], v[170:173], v[202:205], v[70:73]
	v_mfma_f32_16x16x32_bf16 v[58:61], v[162:165], v[194:197], v[58:61]
	v_mfma_f32_16x16x32_bf16 v[54:57], v[170:173], v[194:197], v[54:57]
	v_mfma_f32_16x16x32_bf16 v[42:45], v[162:165], v[186:189], v[42:45]
	v_mfma_f32_16x16x32_bf16 v[38:41], v[170:173], v[186:189], v[38:41]
	v_mfma_f32_16x16x32_bf16 v[26:29], v[162:165], v[178:181], v[26:29]
	v_mfma_f32_16x16x32_bf16 v[22:25], v[170:173], v[178:181], v[22:25]
	v_mfma_f32_16x16x32_bf16 v[66:69], v[142:145], v[198:201], v[66:69]
	v_mfma_f32_16x16x32_bf16 v[62:65], v[150:153], v[198:201], v[62:65]
	v_mfma_f32_16x16x32_bf16 v[50:53], v[142:145], v[190:193], v[50:53]
	v_mfma_f32_16x16x32_bf16 v[46:49], v[150:153], v[190:193], v[46:49]
	v_mfma_f32_16x16x32_bf16 v[34:37], v[142:145], v[182:185], v[34:37]
	v_mfma_f32_16x16x32_bf16 v[30:33], v[150:153], v[182:185], v[30:33]
	v_mfma_f32_16x16x32_bf16 v[18:21], v[142:145], v[174:177], v[18:21]
	v_mfma_f32_16x16x32_bf16 v[14:17], v[150:153], v[174:177], v[14:17]
	v_mfma_f32_16x16x32_bf16 v[66:69], v[146:149], v[202:205], v[66:69]
	v_mfma_f32_16x16x32_bf16 v[62:65], v[154:157], v[202:205], v[62:65]
	v_mfma_f32_16x16x32_bf16 v[50:53], v[146:149], v[194:197], v[50:53]
	v_mfma_f32_16x16x32_bf16 v[46:49], v[154:157], v[194:197], v[46:49]
	v_mfma_f32_16x16x32_bf16 v[34:37], v[146:149], v[186:189], v[34:37]
	v_mfma_f32_16x16x32_bf16 v[30:33], v[154:157], v[186:189], v[30:33]
	v_mfma_f32_16x16x32_bf16 v[18:21], v[146:149], v[178:181], v[18:21]
	v_mfma_f32_16x16x32_bf16 v[14:17], v[154:157], v[178:181], v[14:17]
	s_barrier
	v_add_u32_e32 v2, 0x18000, v248
	ds_read_b128 v[158:161], v2
	ds_read_b128 v[162:165], v2 offset:1024
	ds_read_b128 v[166:169], v2 offset:2048
	ds_read_b128 v[170:173], v2 offset:3072
	v_add_u32_e32 v2, 0x1c000, v248
	ds_read_b128 v[142:145], v2
	ds_read_b128 v[146:149], v2 offset:1024
	ds_read_b128 v[150:153], v2 offset:2048
	ds_read_b128 v[154:157], v2 offset:3072
	s_add_u32 s44, s44, 0x10000
	s_addc_u32 s45, s45, 0
	s_mov_b32 m0, s72
	v_add_u32_e32 v2, 0x22c00, v250
	ds_read_b128 v[182:185], v249 offset:32768
	ds_read_b128 v[186:189], v249 offset:33792
	ds_read_b128 v[190:193], v249 offset:34816
	ds_read_b128 v[194:197], v249 offset:35840
	ds_read_b128 v[198:201], v249 offset:36864
	ds_read_b128 v[202:205], v249 offset:37888
	ds_read_b128 v[206:209], v249 offset:38912
	ds_read_b128 v[240:243], v249 offset:39936
	ds_read_b128 v[174:177], v2
	ds_read_b128 v[178:181], v2 offset:1024
	global_load_lds_dwordx4 v214, s[44:45]
	s_mov_b32 m0, s73
	s_nop 0
	global_load_lds_dwordx4 v218, s[44:45]
	s_waitcnt vmcnt(9)
	s_waitcnt lgkmcnt(0)
	s_barrier
	v_mfma_f32_16x16x32_bf16 v[138:141], v[158:161], v[182:185], v[138:141]
	v_mfma_f32_16x16x32_bf16 v[134:137], v[166:169], v[182:185], v[134:137]
	v_mfma_f32_16x16x32_bf16 v[122:125], v[158:161], v[190:193], v[122:125]
	v_mfma_f32_16x16x32_bf16 v[118:121], v[166:169], v[190:193], v[118:121]
	v_mfma_f32_16x16x32_bf16 v[106:109], v[158:161], v[198:201], v[106:109]
	v_mfma_f32_16x16x32_bf16 v[102:105], v[166:169], v[198:201], v[102:105]
	v_mfma_f32_16x16x32_bf16 v[90:93], v[158:161], v[206:209], v[90:93]
	v_mfma_f32_16x16x32_bf16 v[86:89], v[166:169], v[206:209], v[86:89]
	v_mfma_f32_16x16x32_bf16 v[138:141], v[162:165], v[186:189], v[138:141]
	v_mfma_f32_16x16x32_bf16 v[134:137], v[170:173], v[186:189], v[134:137]
	v_mfma_f32_16x16x32_bf16 v[122:125], v[162:165], v[194:197], v[122:125]
	v_mfma_f32_16x16x32_bf16 v[118:121], v[170:173], v[194:197], v[118:121]
	v_mfma_f32_16x16x32_bf16 v[106:109], v[162:165], v[202:205], v[106:109]
	v_mfma_f32_16x16x32_bf16 v[102:105], v[170:173], v[202:205], v[102:105]
	v_mfma_f32_16x16x32_bf16 v[90:93], v[162:165], v[240:243], v[90:93]
	v_mfma_f32_16x16x32_bf16 v[86:89], v[170:173], v[240:243], v[86:89]
	v_mfma_f32_16x16x32_bf16 v[130:133], v[142:145], v[182:185], v[130:133]
	v_mfma_f32_16x16x32_bf16 v[126:129], v[150:153], v[182:185], v[126:129]
	v_mfma_f32_16x16x32_bf16 v[114:117], v[142:145], v[190:193], v[114:117]
	v_mfma_f32_16x16x32_bf16 v[110:113], v[150:153], v[190:193], v[110:113]
	v_mfma_f32_16x16x32_bf16 v[98:101], v[142:145], v[198:201], v[98:101]
	v_mfma_f32_16x16x32_bf16 v[94:97], v[150:153], v[198:201], v[94:97]
	v_mfma_f32_16x16x32_bf16 v[82:85], v[142:145], v[206:209], v[82:85]
	v_mfma_f32_16x16x32_bf16 v[78:81], v[150:153], v[206:209], v[78:81]
	v_mfma_f32_16x16x32_bf16 v[130:133], v[146:149], v[186:189], v[130:133]
	v_mfma_f32_16x16x32_bf16 v[126:129], v[154:157], v[186:189], v[126:129]
	v_mfma_f32_16x16x32_bf16 v[114:117], v[146:149], v[194:197], v[114:117]
	v_mfma_f32_16x16x32_bf16 v[110:113], v[154:157], v[194:197], v[110:113]
	v_mfma_f32_16x16x32_bf16 v[98:101], v[146:149], v[202:205], v[98:101]
	v_mfma_f32_16x16x32_bf16 v[94:97], v[154:157], v[202:205], v[94:97]
	v_mfma_f32_16x16x32_bf16 v[82:85], v[146:149], v[240:243], v[82:85]
	v_mfma_f32_16x16x32_bf16 v[78:81], v[154:157], v[240:243], v[78:81]
	s_and_b64 vcc, exec, s[6:7]
	s_cbranch_vccnz .LBB0_1666
	s_setprio 1
	s_and_b64 vcc, exec, s[0:1]
	s_mov_b64 s[0:1], -1
	s_cbranch_vccnz .LBB0_1663
	v_mfma_f32_16x16x32_bf16 v[10:13], v[142:145], v[174:177], v[10:13]
	s_mov_b64 s[0:1], 0
	v_mfma_f32_16x16x32_bf16 v[6:9], v[150:153], v[174:177], v[6:9]
	v_mfma_f32_16x16x32_bf16 v[10:13], v[146:149], v[178:181], v[10:13]
	v_mfma_f32_16x16x32_bf16 v[6:9], v[154:157], v[178:181], v[6:9]

; #define PG8_STAGEX(b, gbase) do { if constexpr (XR) { if (lane < 16) __builtin_amdgcn_global_load_lds((const unsigned*)((const char*)(gbase) + voffX), (PG8_LAS unsigned*)(lds + XR_OFF + (b) * 2048 + wid * 256), 16, 0, 0); } } while (0)
; #define PG8_LDX(b) do { if constexpr (XR) { _Pragma("unroll") for (int k = 0; k < 2; ++k) Ax_[k] = *(const PG8_LAS bf16x8*)(lds + XR_OFF + (b) * 2048 + aoffx + k * 1024); } } while (0)
; #define PG8_MMAX() do { if constexpr (XR) { if (hasx) { __builtin_amdgcn_s_setprio(1); if (wr == 0) PG8_MMAX_(B0); else PG8_MMAX_(B1); __builtin_amdgcn_s_setprio(0); } } } while (0)
; #define PG8_WAIT_LOOP() do { if constexpr (XR) PG8_WAIT_V(9); else PG8_WAIT_V(8); } while (0)
; #define PG8_STAGE(bufoff, gbase, voff) do { _Pragma("unroll") for (int _i = 0; _i < 2; ++_i) \
;         __builtin_amdgcn_global_load_lds((const unsigned*)((const char*)(gbase) + (voff)[_i]), (PG8_LAS unsigned*)(lds + (bufoff) + ldsw + _i * 8192), 16, 0, 0); } while (0)
; #define PG8_BAR __builtin_amdgcn_s_barrier()
; template <class Epi, class Sched, bool ALIGN_EPI = false, bool SP2 = false, bool DRAIN = true, bool XR = false>
; __device__ __forceinline__ void gemm_phase(PG8_LAS unsigned char* lds, const Gemm g, const Sched& S, const Epi& E) {
;     ...
;             PG8_LDB(B0, 0, 0); PG8_LDB(B1, 0, 1); PG8_SCHED; PG8_LDA(At, 0, 0); PG8_LDX(0); PG8_STAGE(PG8_SA(1, 1), a1 + hstepA, voffA);
;             PG8_WAIT_LOOP(); PG8_WAIT_L(0); PG8_BAR; PG8_MMA(0, 0, At, B0); PG8_MMA(0, 1, At, B1); PG8_MMAX(); PG8_BAR; PG8_SCHED;
;             PG8_LDA(At, 0, 1); PG8_STAGE(PG8_SB(0, 0), b2, voffB); PG8_STAGE(PG8_SB(0, 1), b2 + hstep, voffB); PG8_STAGE(PG8_SA(0, 0), a2, voffA); PG8_STAGEX(0, x2);
;             PG8_WAIT_LOOP(); PG8_WAIT_L(0); PG8_BAR; PG8_MMA(1, 0, At, B0); PG8_MMA(1, 1, At, B1); PG8_BAR; PG8_SCHED;
;             PG8_LDB(B0, 1, 0); PG8_LDB(B1, 1, 1); PG8_SCHED; PG8_LDA(At, 1, 0); PG8_LDX(1); PG8_STAGE(PG8_SA(0, 1), a2 + hstepA, voffA);
;             PG8_WAIT_LOOP(); PG8_WAIT_L(0); PG8_BAR; PG8_MMA(0, 0, At, B0); PG8_MMA(0, 1, At, B1); PG8_MMAX(); PG8_BAR; PG8_SCHED;
;             PG8_LDA(At, 1, 1); PG8_STAGE(PG8_SB(1, 0), b3, voffB); PG8_STAGE(PG8_SB(1, 1), b3 + hstep, voffB); PG8_STAGE(PG8_SA(1, 0), a3, voffA); PG8_STAGEX(1, x3);
;             PG8_WAIT_LOOP(); PG8_WAIT_L(0); PG8_BAR; PG8_MMA(1, 0, At, B0); PG8_MMA(1, 1, At, B1); PG8_BAR; PG8_SCHED;
.LBB0_1855:
	s_or_b64 exec, exec, s[0:1]
	s_waitcnt vmcnt(9)
	s_waitcnt lgkmcnt(0)
	s_barrier
	v_mfma_f32_16x16x32_bf16 v[74:77], v[158:161], v[198:201], v[74:77]
	v_mfma_f32_16x16x32_bf16 v[70:73], v[166:169], v[198:201], v[70:73]
	v_mfma_f32_16x16x32_bf16 v[66:69], v[158:161], v[190:193], v[66:69]
	v_mfma_f32_16x16x32_bf16 v[62:65], v[166:169], v[190:193], v[62:65]
	v_mfma_f32_16x16x32_bf16 v[58:61], v[158:161], v[182:185], v[58:61]
	v_mfma_f32_16x16x32_bf16 v[54:57], v[166:169], v[182:185], v[54:57]
	v_mfma_f32_16x16x32_bf16 v[50:53], v[158:161], v[174:177], v[50:53]
	v_mfma_f32_16x16x32_bf16 v[46:49], v[166:169], v[174:177], v[46:49]
	v_mfma_f32_16x16x32_bf16 v[74:77], v[162:165], v[202:205], v[74:77]
	v_mfma_f32_16x16x32_bf16 v[70:73], v[170:173], v[202:205], v[70:73]
	v_mfma_f32_16x16x32_bf16 v[66:69], v[162:165], v[194:197], v[66:69]
	v_mfma_f32_16x16x32_bf16 v[62:65], v[170:173], v[194:197], v[62:65]
	v_mfma_f32_16x16x32_bf16 v[58:61], v[162:165], v[186:189], v[58:61]
	v_mfma_f32_16x16x32_bf16 v[54:57], v[170:173], v[186:189], v[54:57]
	v_mfma_f32_16x16x32_bf16 v[50:53], v[162:165], v[178:181], v[50:53]
	v_mfma_f32_16x16x32_bf16 v[46:49], v[170:173], v[178:181], v[46:49]
	v_mfma_f32_16x16x32_bf16 v[42:45], v[142:145], v[198:201], v[42:45]
	v_mfma_f32_16x16x32_bf16 v[38:41], v[150:153], v[198:201], v[38:41]
	v_mfma_f32_16x16x32_bf16 v[34:37], v[142:145], v[190:193], v[34:37]
	v_mfma_f32_16x16x32_bf16 v[30:33], v[150:153], v[190:193], v[30:33]
	v_mfma_f32_16x16x32_bf16 v[26:29], v[142:145], v[182:185], v[26:29]
	v_mfma_f32_16x16x32_bf16 v[22:25], v[150:153], v[182:185], v[22:25]
	v_mfma_f32_16x16x32_bf16 v[18:21], v[142:145], v[174:177], v[18:21]
	v_mfma_f32_16x16x32_bf16 v[14:17], v[150:153], v[174:177], v[14:17]
	v_mfma_f32_16x16x32_bf16 v[42:45], v[146:149], v[202:205], v[42:45]
	v_mfma_f32_16x16x32_bf16 v[38:41], v[154:157], v[202:205], v[38:41]
	v_mfma_f32_16x16x32_bf16 v[34:37], v[146:149], v[194:197], v[34:37]
	v_mfma_f32_16x16x32_bf16 v[30:33], v[154:157], v[194:197], v[30:33]
	v_mfma_f32_16x16x32_bf16 v[26:29], v[146:149], v[186:189], v[26:29]
	v_mfma_f32_16x16x32_bf16 v[22:25], v[154:157], v[186:189], v[22:25]
	v_mfma_f32_16x16x32_bf16 v[18:21], v[146:149], v[178:181], v[18:21]
	v_mfma_f32_16x16x32_bf16 v[14:17], v[154:157], v[178:181], v[14:17]
	s_barrier
	s_add_i32 s45, s45, 2
	s_cmp_ge_i32 s45, s71
	s_cbranch_scc1 .LBB0_1872
.LBB0_1856:
	v_add_u32_e32 v2, 0x10000, v237
	s_add_i32 s56, s88, s45
	ds_read_b128 v[158:161], v2
	ds_read_b128 v[162:165], v2 offset:1024
	ds_read_b128 v[166:169], v2 offset:2048
	ds_read_b128 v[170:173], v2 offset:3072
	v_add_u32_e32 v2, 0x14000, v237
	s_and_b32 s8, s56, s67
	ds_read_b128 v[142:145], v2
	ds_read_b128 v[146:149], v2 offset:1024
	ds_read_b128 v[150:153], v2 offset:2048
	ds_read_b128 v[154:157], v2 offset:3072
	s_lshr_b32 s84, s8, 2
	s_lshl_b32 s8, s8, 7
	s_lshl_b64 s[0:1], s[84:85], 9
	s_and_b32 s8, s8, 0x100
	s_add_u32 s0, s24, s0
	s_addc_u32 s1, s25, s1
	s_add_u32 s0, s0, s8
	s_addc_u32 s1, s1, 0
	s_add_u32 s0, s0, s18
	s_addc_u32 s1, s1, s19
	v_lshl_add_u64 v[4:5], s[0:1], 0, v[214:215]
	v_add_u32_e32 v2, 0x22400, v239
	v_lshl_add_u64 v[4:5], v[4:5], 0, s[86:87]
	s_add_i32 m0, s72, 0xc000
	ds_read_b128 v[182:185], v238
	ds_read_b128 v[186:189], v238 offset:1024
	ds_read_b128 v[190:193], v238 offset:2048
	ds_read_b128 v[194:197], v238 offset:3072
	ds_read_b128 v[198:201], v238 offset:4096
	ds_read_b128 v[202:205], v238 offset:5120
	ds_read_b128 v[206:209], v238 offset:6144
	ds_read_b128 v[224:227], v238 offset:7168
	ds_read_b128 v[174:177], v2
	ds_read_b128 v[178:181], v2 offset:1024
	global_load_lds_dwordx4 v[4:5], off
	v_lshl_add_u64 v[4:5], s[0:1], 0, v[218:219]
	v_lshl_add_u64 v[4:5], v[4:5], 0, s[86:87]
	s_add_i32 m0, s72, 0xe000
	s_nop 0
	global_load_lds_dwordx4 v[4:5], off
	s_waitcnt vmcnt(9)
	s_waitcnt lgkmcnt(0)
	s_barrier
	v_mfma_f32_16x16x32_bf16 v[138:141], v[158:161], v[182:185], v[138:141]
	v_mfma_f32_16x16x32_bf16 v[134:137], v[166:169], v[182:185], v[134:137]
	v_mfma_f32_16x16x32_bf16 v[130:133], v[158:161], v[190:193], v[130:133]
	v_mfma_f32_16x16x32_bf16 v[126:129], v[166:169], v[190:193], v[126:129]
	v_mfma_f32_16x16x32_bf16 v[122:125], v[158:161], v[198:201], v[122:125]
	v_mfma_f32_16x16x32_bf16 v[118:121], v[166:169], v[198:201], v[118:121]
	v_mfma_f32_16x16x32_bf16 v[114:117], v[158:161], v[206:209], v[114:117]
	v_mfma_f32_16x16x32_bf16 v[110:113], v[166:169], v[206:209], v[110:113]
	v_mfma_f32_16x16x32_bf16 v[138:141], v[162:165], v[186:189], v[138:141]
	v_mfma_f32_16x16x32_bf16 v[134:137], v[170:173], v[186:189], v[134:137]
	v_mfma_f32_16x16x32_bf16 v[130:133], v[162:165], v[194:197], v[130:133]
	v_mfma_f32_16x16x32_bf16 v[126:129], v[170:173], v[194:197], v[126:129]
	v_mfma_f32_16x16x32_bf16 v[122:125], v[162:165], v[202:205], v[122:125]
	v_mfma_f32_16x16x32_bf16 v[118:121], v[170:173], v[202:205], v[118:121]
	v_mfma_f32_16x16x32_bf16 v[114:117], v[162:165], v[224:227], v[114:117]
	v_mfma_f32_16x16x32_bf16 v[110:113], v[170:173], v[224:227], v[110:113]
	v_mfma_f32_16x16x32_bf16 v[106:109], v[142:145], v[182:185], v[106:109]
	v_mfma_f32_16x16x32_bf16 v[102:105], v[150:153], v[182:185], v[102:105]
	v_mfma_f32_16x16x32_bf16 v[98:101], v[142:145], v[190:193], v[98:101]
	v_mfma_f32_16x16x32_bf16 v[94:97], v[150:153], v[190:193], v[94:97]
	v_mfma_f32_16x16x32_bf16 v[90:93], v[142:145], v[198:201], v[90:93]
	v_mfma_f32_16x16x32_bf16 v[86:89], v[150:153], v[198:201], v[86:89]
	v_mfma_f32_16x16x32_bf16 v[82:85], v[142:145], v[206:209], v[82:85]
	v_mfma_f32_16x16x32_bf16 v[78:81], v[150:153], v[206:209], v[78:81]
	v_mfma_f32_16x16x32_bf16 v[106:109], v[146:149], v[186:189], v[106:109]
	v_mfma_f32_16x16x32_bf16 v[102:105], v[154:157], v[186:189], v[102:105]
	v_mfma_f32_16x16x32_bf16 v[98:101], v[146:149], v[194:197], v[98:101]
	v_mfma_f32_16x16x32_bf16 v[94:97], v[154:157], v[194:197], v[94:97]
	v_mfma_f32_16x16x32_bf16 v[90:93], v[146:149], v[202:205], v[90:93]
	v_mfma_f32_16x16x32_bf16 v[86:89], v[154:157], v[202:205], v[86:89]
	v_mfma_f32_16x16x32_bf16 v[82:85], v[146:149], v[224:227], v[82:85]
	v_mfma_f32_16x16x32_bf16 v[78:81], v[154:157], v[224:227], v[78:81]
	v_cndmask_b32_e64 v2, 0, 1, s[40:41]
	v_cmp_ne_u32_e64 s[8:9], 1, v2
	v_cndmask_b32_e64 v2, 0, 1, s[46:47]
	s_andn2_b64 vcc, exec, s[40:41]
	v_cmp_ne_u32_e64 s[0:1], 1, v2
	s_cbranch_vccnz .LBB0_1862
	s_setprio 1
	s_and_b64 vcc, exec, s[0:1]
	s_mov_b64 s[54:55], -1
	s_cbranch_vccnz .LBB0_1859
	v_mfma_f32_16x16x32_bf16 v[10:13], v[142:145], v[174:177], v[10:13]
	s_mov_b64 s[54:55], 0
	v_mfma_f32_16x16x32_bf16 v[6:9], v[150:153], v[174:177], v[6:9]
	v_mfma_f32_16x16x32_bf16 v[10:13], v[146:149], v[178:181], v[10:13]
	v_mfma_f32_16x16x32_bf16 v[6:9], v[154:157], v[178:181], v[6:9]

; #define PG8_STAGEX(b, gbase) do { if constexpr (XR) { if (lane < 16) __builtin_amdgcn_global_load_lds((const unsigned*)((const char*)(gbase) + voffX), (PG8_LAS unsigned*)(lds + XR_OFF + (b) * 2048 + wid * 256), 16, 0, 0); } } while (0)
; #define PG8_LDX(b) do { if constexpr (XR) { _Pragma("unroll") for (int k = 0; k < 2; ++k) Ax_[k] = *(const PG8_LAS bf16x8*)(lds + XR_OFF + (b) * 2048 + aoffx + k * 1024); } } while (0)
; #define PG8_MMAX() do { if constexpr (XR) { if (hasx) { __builtin_amdgcn_s_setprio(1); if (wr == 0) PG8_MMAX_(B0); else PG8_MMAX_(B1); __builtin_amdgcn_s_setprio(0); } } } while (0)
; #define PG8_WAIT_LOOP() do { if constexpr (XR) PG8_WAIT_V(9); else PG8_WAIT_V(8); } while (0)
; #define PG8_STAGE(bufoff, gbase, voff) do { _Pragma("unroll") for (int _i = 0; _i < 2; ++_i) \
;         __builtin_amdgcn_global_load_lds((const unsigned*)((const char*)(gbase) + (voff)[_i]), (PG8_LAS unsigned*)(lds + (bufoff) + ldsw + _i * 8192), 16, 0, 0); } while (0)
; #define PG8_BAR __builtin_amdgcn_s_barrier()
; template <class Epi, class Sched, bool ALIGN_EPI = false, bool SP2 = false, bool DRAIN = true, bool XR = false>
; __device__ __forceinline__ void gemm_phase(PG8_LAS unsigned char* lds, const Gemm g, const Sched& S, const Epi& E) {
;     ...
;             PG8_LDB(B0, 0, 0); PG8_LDB(B1, 0, 1); PG8_SCHED; PG8_LDA(At, 0, 0); PG8_LDX(0); PG8_STAGE(PG8_SA(1, 1), a1 + hstepA, voffA);
;             PG8_WAIT_LOOP(); PG8_WAIT_L(0); PG8_BAR; PG8_MMA(0, 0, At, B0); PG8_MMA(0, 1, At, B1); PG8_MMAX(); PG8_BAR; PG8_SCHED;
;             PG8_LDA(At, 0, 1); PG8_STAGE(PG8_SB(0, 0), b2, voffB); PG8_STAGE(PG8_SB(0, 1), b2 + hstep, voffB); PG8_STAGE(PG8_SA(0, 0), a2, voffA); PG8_STAGEX(0, x2);
;             PG8_WAIT_LOOP(); PG8_WAIT_L(0); PG8_BAR; PG8_MMA(1, 0, At, B0); PG8_MMA(1, 1, At, B1); PG8_BAR; PG8_SCHED;
;             PG8_LDB(B0, 1, 0); PG8_LDB(B1, 1, 1); PG8_SCHED; PG8_LDA(At, 1, 0); PG8_LDX(1); PG8_STAGE(PG8_SA(0, 1), a2 + hstepA, voffA);
;             PG8_WAIT_LOOP(); PG8_WAIT_L(0); PG8_BAR; PG8_MMA(0, 0, At, B0); PG8_MMA(0, 1, At, B1); PG8_MMAX(); PG8_BAR; PG8_SCHED;
;             PG8_LDA(At, 1, 1); PG8_STAGE(PG8_SB(1, 0), b3, voffB); PG8_STAGE(PG8_SB(1, 1), b3 + hstep, voffB); PG8_STAGE(PG8_SA(1, 0), a3, voffA); PG8_STAGEX(1, x3);
;             PG8_WAIT_LOOP(); PG8_WAIT_L(0); PG8_BAR; PG8_MMA(1, 0, At, B0); PG8_MMA(1, 1, At, B1); PG8_BAR; PG8_SCHED;
.LBB0_1864:
	s_or_b64 exec, exec, s[56:57]
	s_waitcnt vmcnt(9)
	s_waitcnt lgkmcnt(0)
	s_barrier
	v_mfma_f32_16x16x32_bf16 v[74:77], v[158:161], v[198:201], v[74:77]
	v_mfma_f32_16x16x32_bf16 v[70:73], v[166:169], v[198:201], v[70:73]
	v_mfma_f32_16x16x32_bf16 v[66:69], v[158:161], v[190:193], v[66:69]
	v_mfma_f32_16x16x32_bf16 v[62:65], v[166:169], v[190:193], v[62:65]
	v_mfma_f32_16x16x32_bf16 v[58:61], v[158:161], v[182:185], v[58:61]
	v_mfma_f32_16x16x32_bf16 v[54:57], v[166:169], v[182:185], v[54:57]
	v_mfma_f32_16x16x32_bf16 v[50:53], v[158:161], v[174:177], v[50:53]
	v_mfma_f32_16x16x32_bf16 v[46:49], v[166:169], v[174:177], v[46:49]
	v_mfma_f32_16x16x32_bf16 v[74:77], v[162:165], v[202:205], v[74:77]
	v_mfma_f32_16x16x32_bf16 v[70:73], v[170:173], v[202:205], v[70:73]
	v_mfma_f32_16x16x32_bf16 v[66:69], v[162:165], v[194:197], v[66:69]
	v_mfma_f32_16x16x32_bf16 v[62:65], v[170:173], v[194:197], v[62:65]
	v_mfma_f32_16x16x32_bf16 v[58:61], v[162:165], v[186:189], v[58:61]
	v_mfma_f32_16x16x32_bf16 v[54:57], v[170:173], v[186:189], v[54:57]
	v_mfma_f32_16x16x32_bf16 v[50:53], v[162:165], v[178:181], v[50:53]
	v_mfma_f32_16x16x32_bf16 v[46:49], v[170:173], v[178:181], v[46:49]
	v_mfma_f32_16x16x32_bf16 v[42:45], v[142:145], v[198:201], v[42:45]
	v_mfma_f32_16x16x32_bf16 v[38:41], v[150:153], v[198:201], v[38:41]
	v_mfma_f32_16x16x32_bf16 v[34:37], v[142:145], v[190:193], v[34:37]
	v_mfma_f32_16x16x32_bf16 v[30:33], v[150:153], v[190:193], v[30:33]
	v_mfma_f32_16x16x32_bf16 v[26:29], v[142:145], v[182:185], v[26:29]
	v_mfma_f32_16x16x32_bf16 v[22:25], v[150:153], v[182:185], v[22:25]
	v_mfma_f32_16x16x32_bf16 v[18:21], v[142:145], v[174:177], v[18:21]
	v_mfma_f32_16x16x32_bf16 v[14:17], v[150:153], v[174:177], v[14:17]
	v_mfma_f32_16x16x32_bf16 v[42:45], v[146:149], v[202:205], v[42:45]
	v_mfma_f32_16x16x32_bf16 v[38:41], v[154:157], v[202:205], v[38:41]
	v_mfma_f32_16x16x32_bf16 v[34:37], v[146:149], v[194:197], v[34:37]
	v_mfma_f32_16x16x32_bf16 v[30:33], v[154:157], v[194:197], v[30:33]
	v_mfma_f32_16x16x32_bf16 v[26:29], v[146:149], v[186:189], v[26:29]
	v_mfma_f32_16x16x32_bf16 v[22:25], v[154:157], v[186:189], v[22:25]
	v_mfma_f32_16x16x32_bf16 v[18:21], v[146:149], v[178:181], v[18:21]
	v_mfma_f32_16x16x32_bf16 v[14:17], v[154:157], v[178:181], v[14:17]
	s_barrier
	v_add_u32_e32 v2, 0x18000, v237
	ds_read_b128 v[158:161], v2
	ds_read_b128 v[162:165], v2 offset:1024
	ds_read_b128 v[166:169], v2 offset:2048
	ds_read_b128 v[170:173], v2 offset:3072
	v_add_u32_e32 v2, 0x1c000, v237
	ds_read_b128 v[142:145], v2
	ds_read_b128 v[146:149], v2 offset:1024
	ds_read_b128 v[150:153], v2 offset:2048
	ds_read_b128 v[154:157], v2 offset:3072
	s_add_u32 s54, s54, s18
	s_addc_u32 s55, s55, s19
	s_mov_b32 m0, s79
	v_add_u32_e32 v2, 0x22c00, v239
	ds_read_b128 v[182:185], v238 offset:32768
	ds_read_b128 v[186:189], v238 offset:33792
	ds_read_b128 v[190:193], v238 offset:34816
	ds_read_b128 v[194:197], v238 offset:35840
	ds_read_b128 v[198:201], v238 offset:36864
	ds_read_b128 v[202:205], v238 offset:37888
	ds_read_b128 v[206:209], v238 offset:38912
	ds_read_b128 v[240:243], v238 offset:39936
	ds_read_b128 v[174:177], v2
	ds_read_b128 v[178:181], v2 offset:1024
	global_load_lds_dwordx4 v214, s[54:55]
	s_mov_b32 m0, s80
	s_nop 0
	global_load_lds_dwordx4 v218, s[54:55]
	s_waitcnt vmcnt(9)
	s_waitcnt lgkmcnt(0)
	s_barrier
	v_mfma_f32_16x16x32_bf16 v[138:141], v[158:161], v[182:185], v[138:141]
	v_mfma_f32_16x16x32_bf16 v[134:137], v[166:169], v[182:185], v[134:137]
	v_mfma_f32_16x16x32_bf16 v[130:133], v[158:161], v[190:193], v[130:133]
	v_mfma_f32_16x16x32_bf16 v[126:129], v[166:169], v[190:193], v[126:129]
	v_mfma_f32_16x16x32_bf16 v[122:125], v[158:161], v[198:201], v[122:125]
	v_mfma_f32_16x16x32_bf16 v[118:121], v[166:169], v[198:201], v[118:121]
	v_mfma_f32_16x16x32_bf16 v[114:117], v[158:161], v[206:209], v[114:117]
	v_mfma_f32_16x16x32_bf16 v[110:113], v[166:169], v[206:209], v[110:113]
	v_mfma_f32_16x16x32_bf16 v[138:141], v[162:165], v[186:189], v[138:141]
	v_mfma_f32_16x16x32_bf16 v[134:137], v[170:173], v[186:189], v[134:137]
	v_mfma_f32_16x16x32_bf16 v[130:133], v[162:165], v[194:197], v[130:133]
	v_mfma_f32_16x16x32_bf16 v[126:129], v[170:173], v[194:197], v[126:129]
	v_mfma_f32_16x16x32_bf16 v[122:125], v[162:165], v[202:205], v[122:125]
	v_mfma_f32_16x16x32_bf16 v[118:121], v[170:173], v[202:205], v[118:121]
	v_mfma_f32_16x16x32_bf16 v[114:117], v[162:165], v[240:243], v[114:117]
	v_mfma_f32_16x16x32_bf16 v[110:113], v[170:173], v[240:243], v[110:113]
	v_mfma_f32_16x16x32_bf16 v[106:109], v[142:145], v[182:185], v[106:109]
	v_mfma_f32_16x16x32_bf16 v[102:105], v[150:153], v[182:185], v[102:105]
	v_mfma_f32_16x16x32_bf16 v[98:101], v[142:145], v[190:193], v[98:101]
	v_mfma_f32_16x16x32_bf16 v[94:97], v[150:153], v[190:193], v[94:97]
	v_mfma_f32_16x16x32_bf16 v[90:93], v[142:145], v[198:201], v[90:93]
	v_mfma_f32_16x16x32_bf16 v[86:89], v[150:153], v[198:201], v[86:89]
	v_mfma_f32_16x16x32_bf16 v[82:85], v[142:145], v[206:209], v[82:85]
	v_mfma_f32_16x16x32_bf16 v[78:81], v[150:153], v[206:209], v[78:81]
	v_mfma_f32_16x16x32_bf16 v[106:109], v[146:149], v[186:189], v[106:109]
	v_mfma_f32_16x16x32_bf16 v[102:105], v[154:157], v[186:189], v[102:105]
	v_mfma_f32_16x16x32_bf16 v[98:101], v[146:149], v[194:197], v[98:101]
	v_mfma_f32_16x16x32_bf16 v[94:97], v[154:157], v[194:197], v[94:97]
	v_mfma_f32_16x16x32_bf16 v[90:93], v[146:149], v[202:205], v[90:93]
	v_mfma_f32_16x16x32_bf16 v[86:89], v[154:157], v[202:205], v[86:89]
	v_mfma_f32_16x16x32_bf16 v[82:85], v[146:149], v[240:243], v[82:85]
	v_mfma_f32_16x16x32_bf16 v[78:81], v[154:157], v[240:243], v[78:81]
	s_and_b64 vcc, exec, s[8:9]
	s_cbranch_vccnz .LBB0_1870
	s_setprio 1
	s_and_b64 vcc, exec, s[0:1]
	s_mov_b64 s[0:1], -1
	s_cbranch_vccnz .LBB0_1867
	v_mfma_f32_16x16x32_bf16 v[10:13], v[142:145], v[174:177], v[10:13]
	s_mov_b64 s[0:1], 0
	v_mfma_f32_16x16x32_bf16 v[6:9], v[150:153], v[174:177], v[6:9]
	v_mfma_f32_16x16x32_bf16 v[10:13], v[146:149], v[178:181], v[10:13]
	v_mfma_f32_16x16x32_bf16 v[6:9], v[154:157], v[178:181], v[6:9]

; #define PG8_STAGEX(b, gbase) do { if constexpr (XR) { if (lane < 16) __builtin_amdgcn_global_load_lds((const unsigned*)((const char*)(gbase) + voffX), (PG8_LAS unsigned*)(lds + XR_OFF + (b) * 2048 + wid * 256), 16, 0, 0); } } while (0)
; #define PG8_LDX(b) do { if constexpr (XR) { _Pragma("unroll") for (int k = 0; k < 2; ++k) Ax_[k] = *(const PG8_LAS bf16x8*)(lds + XR_OFF + (b) * 2048 + aoffx + k * 1024); } } while (0)
; #define PG8_MMAX() do { if constexpr (XR) { if (hasx) { __builtin_amdgcn_s_setprio(1); if (wr == 0) PG8_MMAX_(B0); else PG8_MMAX_(B1); __builtin_amdgcn_s_setprio(0); } } } while (0)
; #define PG8_WAIT_LOOP() do { if constexpr (XR) PG8_WAIT_V(9); else PG8_WAIT_V(8); } while (0)
; #define PG8_LDA(dst, b, h) do { _Pragma("unroll") for (int m = 0; m < 4; ++m) _Pragma("unroll") for (int k = 0; k < 2; ++k) dst[m][k] = *(const PG8_LAS bf16x8*)(lds + PG8_SA(b, h) + aoff + m * 2048 + k * 1024); } while (0)
; template <class Epi, class Sched, bool ALIGN_EPI = false, bool SP2 = false, bool DRAIN = true, bool XR = false>
; __device__ __forceinline__ void gemm_phase(PG8_LAS unsigned char* lds, const Gemm g, const Sched& S, const Epi& E) {
;     ...
;         for (int t = 0; t < nt; t += 2) {
;             if constexpr (Epi::MIDSCALE) { if (t == (nt >> 1)) E.midscale(acc, cur, wr, fr); }
;             const bool last = (t == nt - 2);
;             const char* a1 = cA + PG8_KOA(t) + kstep;
;             const char* a2 = last ? nA + ka0 : cA + PG8_KOA(t + 2); const char* b2 = last ? nB + kb0 : cB + PG8_KOB(t + 2);
;             const char* x2 = XR ? (last ? nX + kx0 : cX + PG8_KOX(t + 2)) : nullptr; const char* x3 = XR ? x2 + kstep : nullptr;
;             const char* a3 = a2 + kstep; const char* b3 = b2 + kstep;
;             if (last && has_next) S.a_ready(nxt);
;             if constexpr (SP2) {
;             PG8_LDB(B0, 0, 0); PG8_LDB(B1, 0, 1); PG8_SCHED; PG8_LDA(At, 0, 0); PG8_LDX(0); PG8_STAGE(PG8_SA(1, 1), a1 + hstepA, voffA);
;             PG8_WAIT_LOOP(); PG8_WAIT_L(0); PG8_BAR; PG8_MMA(0, 0, At, B0); PG8_MMA(0, 1, At, B1); PG8_MMAX(); PG8_BAR; PG8_SCHED;
;             PG8_LDA(At, 0, 1); PG8_STAGE(PG8_SB(0, 0), b2, voffB); PG8_STAGE(PG8_SB(0, 1), b2 + hstep, voffB); PG8_STAGE(PG8_SA(0, 0), a2, voffA); PG8_STAGEX(0, x2);
;             PG8_WAIT_LOOP(); PG8_WAIT_L(0); PG8_BAR; PG8_MMA(1, 0, At, B0); PG8_MMA(1, 1, At, B1); PG8_BAR; PG8_SCHED;
.LBB0_2023:
	s_add_i32 s40, s88, s25
	s_and_b32 s41, s40, s93
	s_lshr_b32 s84, s41, 2
	s_lshl_b32 s36, s41, 7
	s_lshl_b64 s[0:1], s[84:85], 9
	s_and_b32 s36, s36, 0x100
	s_add_u32 s0, s58, s0
	s_addc_u32 s1, s59, s1
	s_add_u32 s42, s0, s36
	s_addc_u32 s43, s1, 0
	s_add_i32 s40, s40, 2
	s_and_b32 s0, s40, s93
	s_lshr_b32 s84, s0, 2
	s_lshl_b32 s1, s0, 7
	s_lshl_b64 s[40:41], s[84:85], 9
	s_and_b32 s1, s1, 0x100
	s_add_u32 s36, s58, s40
	s_addc_u32 s40, s59, s41
	s_add_u32 s36, s36, s1
	s_mov_b32 s1, s85
	s_addc_u32 s40, s40, 0
	s_lshl_b64 s[0:1], s[0:1], 7
	s_add_u32 s44, s56, s0
	s_addc_u32 s41, s57, s1
	s_add_i32 s45, 0, 0x10000
	s_cmp_eq_u32 s92, s25
	s_cselect_b32 s1, s22, s40
	s_cselect_b32 s0, s9, s36
	v_add_u32_e32 v2, s45, v182
	s_cselect_b32 s41, s24, s41
	s_cselect_b32 s40, s23, s44
	s_add_i32 s36, 0, 0x14000
	ds_read_b128 v[134:137], v2
	ds_read_b128 v[138:141], v2 offset:1024
	ds_read_b128 v[142:145], v2 offset:2048
	ds_read_b128 v[146:149], v2 offset:3072
	v_add_u32_e32 v2, s36, v182
	ds_read_b128 v[150:153], v2
	ds_read_b128 v[154:157], v2 offset:1024
	ds_read_b128 v[158:161], v2 offset:2048
	ds_read_b128 v[162:165], v2 offset:3072
	s_add_u32 s42, s42, s68
	s_addc_u32 s43, s43, s69
	v_lshl_add_u64 v[4:5], s[42:43], 0, v[172:173]
	v_lshl_add_u64 v[4:5], v[4:5], 0, s[86:87]
	s_add_i32 m0, s49, 0xc000
	ds_read_b128 v[174:177], v199
	ds_read_b128 v[200:203], v199 offset:1024
	ds_read_b128 v[204:207], v199 offset:2048
	ds_read_b128 v[214:217], v199 offset:3072
	ds_read_b128 v[218:221], v199 offset:4096
	ds_read_b128 v[222:225], v199 offset:5120
	ds_read_b128 v[226:229], v199 offset:6144
	ds_read_b128 v[230:233], v199 offset:7168
	global_load_lds_dwordx4 v[4:5], off
	v_lshl_add_u64 v[4:5], s[42:43], 0, v[168:169]
	v_lshl_add_u64 v[4:5], v[4:5], 0, s[86:87]
	s_add_i32 m0, s49, 0xe000
	s_nop 0
	global_load_lds_dwordx4 v[4:5], off
	s_waitcnt vmcnt(8)
	s_waitcnt lgkmcnt(0)
	s_barrier
	v_mfma_f32_16x16x32_bf16 v[130:133], v[134:137], v[174:177], v[130:133]
	v_mfma_f32_16x16x32_bf16 v[98:101], v[142:145], v[174:177], v[98:101]
	v_mfma_f32_16x16x32_bf16 v[126:129], v[134:137], v[204:207], v[126:129]
	v_mfma_f32_16x16x32_bf16 v[90:93], v[142:145], v[204:207], v[90:93]
	v_mfma_f32_16x16x32_bf16 v[122:125], v[134:137], v[218:221], v[122:125]
	v_mfma_f32_16x16x32_bf16 v[82:85], v[142:145], v[218:221], v[82:85]
	v_mfma_f32_16x16x32_bf16 v[118:121], v[134:137], v[226:229], v[118:121]
	v_mfma_f32_16x16x32_bf16 v[74:77], v[142:145], v[226:229], v[74:77]
	v_mfma_f32_16x16x32_bf16 v[130:133], v[138:141], v[200:203], v[130:133]
	v_mfma_f32_16x16x32_bf16 v[98:101], v[146:149], v[200:203], v[98:101]
	v_mfma_f32_16x16x32_bf16 v[126:129], v[138:141], v[214:217], v[126:129]
	v_mfma_f32_16x16x32_bf16 v[90:93], v[146:149], v[214:217], v[90:93]
	v_mfma_f32_16x16x32_bf16 v[122:125], v[138:141], v[222:225], v[122:125]
	v_mfma_f32_16x16x32_bf16 v[82:85], v[146:149], v[222:225], v[82:85]
	v_mfma_f32_16x16x32_bf16 v[118:121], v[138:141], v[230:233], v[118:121]
	v_mfma_f32_16x16x32_bf16 v[74:77], v[146:149], v[230:233], v[74:77]
	v_mfma_f32_16x16x32_bf16 v[114:117], v[150:153], v[174:177], v[114:117]
	v_mfma_f32_16x16x32_bf16 v[66:69], v[158:161], v[174:177], v[66:69]
	v_mfma_f32_16x16x32_bf16 v[110:113], v[150:153], v[204:207], v[110:113]
	v_mfma_f32_16x16x32_bf16 v[58:61], v[158:161], v[204:207], v[58:61]
	v_mfma_f32_16x16x32_bf16 v[106:109], v[150:153], v[218:221], v[106:109]
	v_mfma_f32_16x16x32_bf16 v[50:53], v[158:161], v[218:221], v[50:53]
	v_mfma_f32_16x16x32_bf16 v[102:105], v[150:153], v[226:229], v[102:105]
	v_mfma_f32_16x16x32_bf16 v[42:45], v[158:161], v[226:229], v[42:45]
	v_mfma_f32_16x16x32_bf16 v[114:117], v[154:157], v[200:203], v[114:117]
	v_mfma_f32_16x16x32_bf16 v[66:69], v[162:165], v[200:203], v[66:69]
	v_mfma_f32_16x16x32_bf16 v[110:113], v[154:157], v[214:217], v[110:113]
	v_mfma_f32_16x16x32_bf16 v[58:61], v[162:165], v[214:217], v[58:61]
	v_mfma_f32_16x16x32_bf16 v[106:109], v[154:157], v[222:225], v[106:109]
	v_mfma_f32_16x16x32_bf16 v[50:53], v[162:165], v[222:225], v[50:53]
	v_mfma_f32_16x16x32_bf16 v[102:105], v[154:157], v[230:233], v[102:105]
	v_mfma_f32_16x16x32_bf16 v[42:45], v[162:165], v[230:233], v[42:45]
	s_barrier
	s_add_i32 s42, s45, s48
	v_lshl_add_u64 v[178:179], s[40:41], 0, v[170:171]
	s_mov_b32 m0, s42
	ds_read_b128 v[174:177], v199 offset:16384
	ds_read_b128 v[200:203], v199 offset:17408
	ds_read_b128 v[204:207], v199 offset:18432
	ds_read_b128 v[214:217], v199 offset:19456
	ds_read_b128 v[218:221], v199 offset:20480
	ds_read_b128 v[222:225], v199 offset:21504
	ds_read_b128 v[226:229], v199 offset:22528
	ds_read_b128 v[230:233], v199 offset:23552
	global_load_lds_dwordx4 v170, s[40:41]
	s_add_i32 m0, s42, 0x2000
	v_lshl_add_u64 v[208:209], s[40:41], 0, v[166:167]
	s_add_u32 s40, s40, s68
	s_addc_u32 s41, s41, s69
	s_add_i32 s36, s36, s48
	global_load_lds_dwordx4 v[208:209], off
	v_lshl_add_u64 v[212:213], s[40:41], 0, v[170:171]
	s_mov_b32 m0, s36
	v_lshl_add_u64 v[234:235], s[40:41], 0, v[166:167]
	global_load_lds_dwordx4 v170, s[40:41]
	s_add_i32 m0, s36, 0x2000
	v_lshl_add_u64 v[236:237], s[0:1], 0, v[172:173]
	global_load_lds_dwordx4 v166, s[40:41]
	s_mov_b32 m0, s49
	v_lshl_add_u64 v[238:239], s[0:1], 0, v[168:169]
	global_load_lds_dwordx4 v172, s[0:1]
	s_mov_b32 m0, s83
	s_nop 0
	global_load_lds_dwordx4 v168, s[0:1]
	s_waitcnt vmcnt(8)
	s_waitcnt lgkmcnt(0)
	s_barrier
; #define PG8_LDX(b) do { if constexpr (XR) { _Pragma("unroll") for (int k = 0; k < 2; ++k) Ax_[k] = *(const PG8_LAS bf16x8*)(lds + XR_OFF + (b) * 2048 + aoffx + k * 1024); } } while (0)
; #define PG8_MMAX() do { if constexpr (XR) { if (hasx) { __builtin_amdgcn_s_setprio(1); if (wr == 0) PG8_MMAX_(B0); else PG8_MMAX_(B1); __builtin_amdgcn_s_setprio(0); } } } while (0)
; #define PG8_WAIT_LOOP() do { if constexpr (XR) PG8_WAIT_V(9); else PG8_WAIT_V(8); } while (0)
; #define PG8_STAGE(bufoff, gbase, voff) do { _Pragma("unroll") for (int _i = 0; _i < 2; ++_i) \
;         __builtin_amdgcn_global_load_lds((const unsigned*)((const char*)(gbase) + (voff)[_i]), (PG8_LAS unsigned*)(lds + (bufoff) + ldsw + _i * 8192), 16, 0, 0); } while (0)
; #define PG8_LDA(dst, b, h) do { _Pragma("unroll") for (int m = 0; m < 4; ++m) _Pragma("unroll") for (int k = 0; k < 2; ++k) dst[m][k] = *(const PG8_LAS bf16x8*)(lds + PG8_SA(b, h) + aoff + m * 2048 + k * 1024); } while (0)
; #define PG8_LDB(dst, b, h) do { _Pragma("unroll") for (int n = 0; n < 2; ++n) _Pragma("unroll") for (int k = 0; k < 2; ++k) dst[n][k] = *(const PG8_LAS bf16x8*)(lds + PG8_SB(b, h) + boff + n * 2048 + k * 1024); } while (0)
; #define PG8_MMA(ai, bj, At, Bt) do { __builtin_amdgcn_s_setprio(1); _Pragma("unroll") for (int m = 0; m < 4; ++m) _Pragma("unroll") for (int n = 0; n < 2; ++n) _Pragma("unroll") for (int k = 0; k < 2; ++k) \
;         acc[ai][bj][m][n] = __builtin_amdgcn_mfma_f32_16x16x32_bf16(Bt[n][k], At[m][k], acc[ai][bj][m][n], 0, 0, 0); __builtin_amdgcn_s_setprio(0); } while (0)
; #define PG8_WAIT_L(n) asm volatile("s_waitcnt lgkmcnt(" #n ")" ::: "memory")
; #define PG8_BAR __builtin_amdgcn_s_barrier()
; #define PG8_SCHED __builtin_amdgcn_sched_barrier(0)
; template <class Epi, class Sched, bool ALIGN_EPI = false, bool SP2 = false, bool DRAIN = true, bool XR = false>
; __device__ __forceinline__ void gemm_phase(PG8_LAS unsigned char* lds, const Gemm g, const Sched& S, const Epi& E) {
;     ...
;             PG8_WAIT_LOOP(); PG8_WAIT_L(0); PG8_BAR; PG8_MMA(1, 0, At, B0); PG8_MMA(1, 1, At, B1); PG8_BAR; PG8_SCHED;
;             PG8_LDB(B0, 1, 0); PG8_LDB(B1, 1, 1); PG8_SCHED; PG8_LDA(At, 1, 0); PG8_LDX(1); PG8_STAGE(PG8_SA(0, 1), a2 + hstepA, voffA);
;             PG8_WAIT_LOOP(); PG8_WAIT_L(0); PG8_BAR; PG8_MMA(0, 0, At, B0); PG8_MMA(0, 1, At, B1); PG8_MMAX(); PG8_BAR; PG8_SCHED;
	v_mfma_f32_16x16x32_bf16 v[94:97], v[134:137], v[174:177], v[94:97]
	v_mfma_f32_16x16x32_bf16 v[34:37], v[142:145], v[174:177], v[34:37]
	v_mfma_f32_16x16x32_bf16 v[86:89], v[134:137], v[204:207], v[86:89]
	v_mfma_f32_16x16x32_bf16 v[30:33], v[142:145], v[204:207], v[30:33]
	v_mfma_f32_16x16x32_bf16 v[78:81], v[134:137], v[218:221], v[78:81]
	v_mfma_f32_16x16x32_bf16 v[26:29], v[142:145], v[218:221], v[26:29]
	v_mfma_f32_16x16x32_bf16 v[70:73], v[134:137], v[226:229], v[70:73]
	v_mfma_f32_16x16x32_bf16 v[22:25], v[142:145], v[226:229], v[22:25]
	v_mfma_f32_16x16x32_bf16 v[94:97], v[138:141], v[200:203], v[94:97]
	v_mfma_f32_16x16x32_bf16 v[34:37], v[146:149], v[200:203], v[34:37]
	v_mfma_f32_16x16x32_bf16 v[86:89], v[138:141], v[214:217], v[86:89]
	v_mfma_f32_16x16x32_bf16 v[30:33], v[146:149], v[214:217], v[30:33]
	v_mfma_f32_16x16x32_bf16 v[78:81], v[138:141], v[222:225], v[78:81]
	v_mfma_f32_16x16x32_bf16 v[26:29], v[146:149], v[222:225], v[26:29]
	v_mfma_f32_16x16x32_bf16 v[70:73], v[138:141], v[230:233], v[70:73]
	v_mfma_f32_16x16x32_bf16 v[22:25], v[146:149], v[230:233], v[22:25]
	v_mfma_f32_16x16x32_bf16 v[62:65], v[150:153], v[174:177], v[62:65]
	v_mfma_f32_16x16x32_bf16 v[18:21], v[158:161], v[174:177], v[18:21]
	v_mfma_f32_16x16x32_bf16 v[54:57], v[150:153], v[204:207], v[54:57]
	v_mfma_f32_16x16x32_bf16 v[14:17], v[158:161], v[204:207], v[14:17]
	v_mfma_f32_16x16x32_bf16 v[46:49], v[150:153], v[218:221], v[46:49]
	v_mfma_f32_16x16x32_bf16 v[10:13], v[158:161], v[218:221], v[10:13]
	v_mfma_f32_16x16x32_bf16 v[38:41], v[150:153], v[226:229], v[38:41]
	v_mfma_f32_16x16x32_bf16 v[4:7], v[158:161], v[226:229], v[6:9]
	v_mfma_f32_16x16x32_bf16 v[62:65], v[154:157], v[200:203], v[62:65]
	v_mfma_f32_16x16x32_bf16 v[18:21], v[162:165], v[200:203], v[18:21]
	v_mfma_f32_16x16x32_bf16 v[54:57], v[154:157], v[214:217], v[54:57]
	v_mfma_f32_16x16x32_bf16 v[14:17], v[162:165], v[214:217], v[14:17]
	v_mfma_f32_16x16x32_bf16 v[46:49], v[154:157], v[222:225], v[46:49]
	v_mfma_f32_16x16x32_bf16 v[10:13], v[162:165], v[222:225], v[10:13]
	v_mfma_f32_16x16x32_bf16 v[38:41], v[154:157], v[230:233], v[38:41]
	v_mfma_f32_16x16x32_bf16 v[4:7], v[162:165], v[230:233], v[4:7]
	s_barrier
	s_add_i32 s36, 0, 0x18000
	v_add_u32_e32 v2, s36, v182
	s_add_i32 s40, 0, 0x1c000
	ds_read_b128 v[134:137], v2
	ds_read_b128 v[138:141], v2 offset:1024
	ds_read_b128 v[142:145], v2 offset:2048
	ds_read_b128 v[146:149], v2 offset:3072
	v_add_u32_e32 v2, s40, v182
	ds_read_b128 v[150:153], v2
	ds_read_b128 v[154:157], v2 offset:1024
	ds_read_b128 v[158:161], v2 offset:2048
	ds_read_b128 v[162:165], v2 offset:3072
	s_add_u32 s0, s0, s68
	s_addc_u32 s1, s1, s69
	s_mov_b32 m0, s4
	ds_read_b128 v[174:177], v199 offset:32768
	ds_read_b128 v[200:203], v199 offset:33792
	ds_read_b128 v[204:207], v199 offset:34816
	ds_read_b128 v[214:217], v199 offset:35840
	ds_read_b128 v[218:221], v199 offset:36864
	ds_read_b128 v[222:225], v199 offset:37888
	ds_read_b128 v[226:229], v199 offset:38912
	ds_read_b128 v[230:233], v199 offset:39936
	global_load_lds_dwordx4 v172, s[0:1]
	s_mov_b32 m0, s5
	s_nop 0
	global_load_lds_dwordx4 v168, s[0:1]
	s_waitcnt vmcnt(8)
	s_waitcnt lgkmcnt(0)
	s_barrier
	v_mfma_f32_16x16x32_bf16 v[130:133], v[134:137], v[174:177], v[130:133]
	v_mfma_f32_16x16x32_bf16 v[98:101], v[142:145], v[174:177], v[98:101]
	v_mfma_f32_16x16x32_bf16 v[126:129], v[134:137], v[204:207], v[126:129]
	v_mfma_f32_16x16x32_bf16 v[90:93], v[142:145], v[204:207], v[90:93]
	v_mfma_f32_16x16x32_bf16 v[122:125], v[134:137], v[218:221], v[122:125]
	v_mfma_f32_16x16x32_bf16 v[82:85], v[142:145], v[218:221], v[82:85]
	v_mfma_f32_16x16x32_bf16 v[118:121], v[134:137], v[226:229], v[118:121]
	v_mfma_f32_16x16x32_bf16 v[74:77], v[142:145], v[226:229], v[74:77]
	v_mfma_f32_16x16x32_bf16 v[130:133], v[138:141], v[200:203], v[130:133]
	v_mfma_f32_16x16x32_bf16 v[98:101], v[146:149], v[200:203], v[98:101]
	v_mfma_f32_16x16x32_bf16 v[126:129], v[138:141], v[214:217], v[126:129]
	v_mfma_f32_16x16x32_bf16 v[90:93], v[146:149], v[214:217], v[90:93]
	v_mfma_f32_16x16x32_bf16 v[122:125], v[138:141], v[222:225], v[122:125]
	v_mfma_f32_16x16x32_bf16 v[82:85], v[146:149], v[222:225], v[82:85]
	v_mfma_f32_16x16x32_bf16 v[118:121], v[138:141], v[230:233], v[118:121]
	v_mfma_f32_16x16x32_bf16 v[74:77], v[146:149], v[230:233], v[74:77]
	v_mfma_f32_16x16x32_bf16 v[114:117], v[150:153], v[174:177], v[114:117]
	v_mfma_f32_16x16x32_bf16 v[66:69], v[158:161], v[174:177], v[66:69]
	v_mfma_f32_16x16x32_bf16 v[110:113], v[150:153], v[204:207], v[110:113]
	v_mfma_f32_16x16x32_bf16 v[58:61], v[158:161], v[204:207], v[58:61]
	v_mfma_f32_16x16x32_bf16 v[106:109], v[150:153], v[218:221], v[106:109]
	v_mfma_f32_16x16x32_bf16 v[50:53], v[158:161], v[218:221], v[50:53]
	v_mfma_f32_16x16x32_bf16 v[102:105], v[150:153], v[226:229], v[102:105]
	v_mfma_f32_16x16x32_bf16 v[42:45], v[158:161], v[226:229], v[42:45]
	v_mfma_f32_16x16x32_bf16 v[114:117], v[154:157], v[200:203], v[114:117]
	v_mfma_f32_16x16x32_bf16 v[66:69], v[162:165], v[200:203], v[66:69]
	v_mfma_f32_16x16x32_bf16 v[110:113], v[154:157], v[214:217], v[110:113]
	v_mfma_f32_16x16x32_bf16 v[58:61], v[162:165], v[214:217], v[58:61]
	v_mfma_f32_16x16x32_bf16 v[106:109], v[154:157], v[222:225], v[106:109]
	v_mfma_f32_16x16x32_bf16 v[50:53], v[162:165], v[222:225], v[50:53]
	v_mfma_f32_16x16x32_bf16 v[102:105], v[154:157], v[230:233], v[102:105]
	v_mfma_f32_16x16x32_bf16 v[42:45], v[162:165], v[230:233], v[42:45]
	s_barrier
; #define PG8_STAGEX(b, gbase) do { if constexpr (XR) { if (lane < 16) __builtin_amdgcn_global_load_lds((const unsigned*)((const char*)(gbase) + voffX), (PG8_LAS unsigned*)(lds + XR_OFF + (b) * 2048 + wid * 256), 16, 0, 0); } } while (0)
; #define PG8_WAIT_LOOP() do { if constexpr (XR) PG8_WAIT_V(9); else PG8_WAIT_V(8); } while (0)
; #define PG8_STAGE(bufoff, gbase, voff) do { _Pragma("unroll") for (int _i = 0; _i < 2; ++_i) \
;         __builtin_amdgcn_global_load_lds((const unsigned*)((const char*)(gbase) + (voff)[_i]), (PG8_LAS unsigned*)(lds + (bufoff) + ldsw + _i * 8192), 16, 0, 0); } while (0)
; #define PG8_LDA(dst, b, h) do { _Pragma("unroll") for (int m = 0; m < 4; ++m) _Pragma("unroll") for (int k = 0; k < 2; ++k) dst[m][k] = *(const PG8_LAS bf16x8*)(lds + PG8_SA(b, h) + aoff + m * 2048 + k * 1024); } while (0)
; #define PG8_MMA(ai, bj, At, Bt) do { __builtin_amdgcn_s_setprio(1); _Pragma("unroll") for (int m = 0; m < 4; ++m) _Pragma("unroll") for (int n = 0; n < 2; ++n) _Pragma("unroll") for (int k = 0; k < 2; ++k) \
;         acc[ai][bj][m][n] = __builtin_amdgcn_mfma_f32_16x16x32_bf16(Bt[n][k], At[m][k], acc[ai][bj][m][n], 0, 0, 0); __builtin_amdgcn_s_setprio(0); } while (0)
; #define PG8_WAIT_L(n) asm volatile("s_waitcnt lgkmcnt(" #n ")" ::: "memory")
; #define PG8_BAR __builtin_amdgcn_s_barrier()
; #define PG8_SCHED __builtin_amdgcn_sched_barrier(0)
; template <class Epi, class Sched, bool ALIGN_EPI = false, bool SP2 = false, bool DRAIN = true, bool XR = false>
; __device__ __forceinline__ void gemm_phase(PG8_LAS unsigned char* lds, const Gemm g, const Sched& S, const Epi& E) {
;     ...
;         for (int t = 0; t < nt; t += 2) {
;     ...
;             PG8_LDA(At, 1, 1); PG8_STAGE(PG8_SB(1, 0), b3, voffB); PG8_STAGE(PG8_SB(1, 1), b3 + hstep, voffB); PG8_STAGE(PG8_SA(1, 0), a3, voffA); PG8_STAGEX(1, x3);
;             PG8_WAIT_LOOP(); PG8_WAIT_L(0); PG8_BAR; PG8_MMA(1, 0, At, B0); PG8_MMA(1, 1, At, B1); PG8_BAR; PG8_SCHED;
	s_add_i32 s0, s36, s48
	v_lshl_add_u64 v[8:9], v[178:179], 0, s[86:87]
	s_mov_b32 m0, s0
	ds_read_b128 v[174:177], v199 offset:49152
	ds_read_b128 v[200:203], v199 offset:50176
	ds_read_b128 v[204:207], v199 offset:51200
	ds_read_b128 v[214:217], v199 offset:52224
	ds_read_b128 v[218:221], v199 offset:53248
	ds_read_b128 v[222:225], v199 offset:54272
	ds_read_b128 v[226:229], v199 offset:55296
	ds_read_b128 v[230:233], v199 offset:56320
	global_load_lds_dwordx4 v[8:9], off
	v_lshl_add_u64 v[8:9], v[208:209], 0, s[86:87]
	s_add_i32 m0, s0, 0x2000
	s_add_i32 s0, s40, s48
	global_load_lds_dwordx4 v[8:9], off
	v_lshl_add_u64 v[8:9], v[212:213], 0, s[86:87]
	s_mov_b32 m0, s0
	s_nop 0
	global_load_lds_dwordx4 v[8:9], off
	v_lshl_add_u64 v[8:9], v[234:235], 0, s[86:87]
	s_add_i32 m0, s0, 0x2000
	s_nop 0
	global_load_lds_dwordx4 v[8:9], off
	v_lshl_add_u64 v[8:9], v[236:237], 0, s[86:87]
	s_mov_b32 m0, s77
	s_nop 0
	global_load_lds_dwordx4 v[8:9], off
	v_lshl_add_u64 v[8:9], v[238:239], 0, s[86:87]
	s_mov_b32 m0, s6
	s_nop 0
	global_load_lds_dwordx4 v[8:9], off
	s_waitcnt vmcnt(8)
	s_waitcnt lgkmcnt(0)
	s_barrier
	v_mfma_f32_16x16x32_bf16 v[94:97], v[134:137], v[174:177], v[94:97]
	v_mfma_f32_16x16x32_bf16 v[34:37], v[142:145], v[174:177], v[34:37]
	v_mfma_f32_16x16x32_bf16 v[86:89], v[134:137], v[204:207], v[86:89]
	v_mfma_f32_16x16x32_bf16 v[30:33], v[142:145], v[204:207], v[30:33]
	v_mfma_f32_16x16x32_bf16 v[78:81], v[134:137], v[218:221], v[78:81]
	v_mfma_f32_16x16x32_bf16 v[26:29], v[142:145], v[218:221], v[26:29]
	v_mfma_f32_16x16x32_bf16 v[70:73], v[134:137], v[226:229], v[70:73]
	v_mfma_f32_16x16x32_bf16 v[22:25], v[142:145], v[226:229], v[22:25]
	v_mfma_f32_16x16x32_bf16 v[94:97], v[138:141], v[200:203], v[94:97]
	v_mfma_f32_16x16x32_bf16 v[34:37], v[146:149], v[200:203], v[34:37]
	v_mfma_f32_16x16x32_bf16 v[86:89], v[138:141], v[214:217], v[86:89]
	v_mfma_f32_16x16x32_bf16 v[30:33], v[146:149], v[214:217], v[30:33]
	v_mfma_f32_16x16x32_bf16 v[78:81], v[138:141], v[222:225], v[78:81]
	v_mfma_f32_16x16x32_bf16 v[26:29], v[146:149], v[222:225], v[26:29]
	v_mfma_f32_16x16x32_bf16 v[70:73], v[138:141], v[230:233], v[70:73]
	v_mfma_f32_16x16x32_bf16 v[22:25], v[146:149], v[230:233], v[22:25]
	v_mfma_f32_16x16x32_bf16 v[62:65], v[150:153], v[174:177], v[62:65]
	v_mfma_f32_16x16x32_bf16 v[18:21], v[158:161], v[174:177], v[18:21]
	v_mfma_f32_16x16x32_bf16 v[54:57], v[150:153], v[204:207], v[54:57]
	v_mfma_f32_16x16x32_bf16 v[14:17], v[158:161], v[204:207], v[14:17]
	v_mfma_f32_16x16x32_bf16 v[46:49], v[150:153], v[218:221], v[46:49]
	v_mfma_f32_16x16x32_bf16 v[8:11], v[158:161], v[218:221], v[10:13]
	v_mfma_f32_16x16x32_bf16 v[38:41], v[150:153], v[226:229], v[38:41]
	v_mfma_f32_16x16x32_bf16 v[4:7], v[158:161], v[226:229], v[4:7]
	v_mfma_f32_16x16x32_bf16 v[62:65], v[154:157], v[200:203], v[62:65]
	v_mfma_f32_16x16x32_bf16 v[18:21], v[162:165], v[200:203], v[18:21]
	v_mfma_f32_16x16x32_bf16 v[54:57], v[154:157], v[214:217], v[54:57]
	v_mfma_f32_16x16x32_bf16 v[14:17], v[162:165], v[214:217], v[14:17]
	v_mfma_f32_16x16x32_bf16 v[46:49], v[154:157], v[222:225], v[46:49]
	v_mfma_f32_16x16x32_bf16 v[10:13], v[162:165], v[222:225], v[8:11]
	v_mfma_f32_16x16x32_bf16 v[38:41], v[154:157], v[230:233], v[38:41]
	v_mfma_f32_16x16x32_bf16 v[6:9], v[162:165], v[230:233], v[4:7]
	s_barrier
	s_add_i32 s25, s25, 2
	s_cmp_ge_i32 s25, s78
	s_cbranch_scc0 .LBB0_2023
